# zero-fill register pairs with v_mov_b64 (150 pairs, mostly FFN1 halo defaults)
# baseline (speedup 1.0000x reference)
;     __device__ __forceinline__ void operator()(AccRef acc, const Unit& u, int wr, int wc, int fr, int fq) const {
;     ...
;         float* rawu = raw + (size_t)(u.pm * 22 + u.pn) * 1024;
;         if (wr == 0 && fr == 0) {
; #pragma unroll
;             for (int bj = 0; bj < 2; ++bj)
; #pragma unroll
;                 for (int n = 0; n < 2; ++n) { *(f32x4*)(rawu + 0 * 256 + bj * 128 + clb + 4 * n) = acc[0][bj][0][n]; *(f32x4*)(rawu + 1 * 256 + bj * 128 + clb + 4 * n) = acc[0][bj][1][n]; }
;         }
;         if (wr == 1 && fr == 15) {
; #pragma unroll
;             for (int bj = 0; bj < 2; ++bj)
; #pragma unroll
;                 for (int n = 0; n < 2; ++n) { *(f32x4*)(rawu + 2 * 256 + bj * 128 + clb + 4 * n) = acc[1][bj][2][n]; *(f32x4*)(rawu + 3 * 256 + bj * 128 + clb + 4 * n) = acc[1][bj][3][n]; }
;         }
;         asm volatile("s_waitcnt lgkmcnt(0)" ::: "memory"); __builtin_amdgcn_s_barrier(); __builtin_amdgcn_s_barrier(); asm volatile("" ::: "memory");
;         const int hc0 = 128 * u.pn + clb, row0 = u.pm * 256 + wr * 64 + 4 * fr;
; #pragma unroll
;         for (int n = 0; n < 2; ++n) {
;             const f32x4 w0v = cwv[n][0], w1v = cwv[n][1], w2v = cwv[n][2], bvv = cwv[n][3], w0g = cwv[n][4], w1g = cwv[n][5], w2g = cwv[n][6], bvg = cwv[n][7];
; #pragma unroll
;             for (int ai = 0; ai < 2; ++ai) {
;                 if (n == 0 && ai == 0) {
;                     asm volatile("" ::: "memory");
;                     const float* cv = cw + hc0 + 4; const float* cg = cv + FH; const float* bp = cb + hc0 + 4;
;                     cwv[1][0] = *(const f32x4*)(cv); cwv[1][1] = *(const f32x4*)(cv + F2); cwv[1][2] = *(const f32x4*)(cv + 2 * F2); cwv[1][3] = *(const f32x4*)(bp);
;                     cwv[1][4] = *(const f32x4*)(cg); cwv[1][5] = *(const f32x4*)(cg + F2); cwv[1][6] = *(const f32x4*)(cg + 2 * F2); cwv[1][7] = *(const f32x4*)(bp + FH);
;                     asm volatile("" ::: "memory"); }
;                 f32x4 h2v = (f32x4){0.f, 0.f, 0.f, 0.f}, h3v = h2v, h2g = h2v, h3g = h2v;
;                 const int pb = ai * 2 + wr - 1;
;                 if (pb >= 0 && fr == 0) { const LAS float* xp = xch + (pb * 2) * 256 + clb + 4 * n;
;                     h2v = *(const LAS f32x4*)(xp); h3v = *(const LAS f32x4*)(xp + 256); h2g = *(const LAS f32x4*)(xp + 128); h3g = *(const LAS f32x4*)(xp + 256 + 128); }
.LBB0_312:
	s_or_b64 exec, exec, s[38:39]
	s_mul_i32 s25, s34, 22
	s_add_i32 s38, s25, s35
	s_ashr_i32 s39, s38, 31
	s_lshl_b64 s[38:39], s[38:39], 12
	s_add_u32 s38, s64, s38
	s_addc_u32 s39, s65, s39
	v_lshlrev_b32_e32 v96, 2, v218
	v_or_b32_e32 v232, s36, v218
	v_ashrrev_i32_e32 v233, 31, v232
	v_lshlrev_b64 v[96:97], 2, v[232:233]
	v_lshl_add_u64 v[120:121], s[56:57], 0, v[96:97]
	v_add_co_u32_e32 v100, vcc, 0x5000, v120
	s_waitcnt lgkmcnt(0)
	s_barrier
	s_nop 0
	v_addc_co_u32_e32 v101, vcc, 0, v121, vcc
	v_add_co_u32_e32 v104, vcc, 0xb000, v120
	s_barrier
	s_nop 0
	v_addc_co_u32_e32 v105, vcc, 0, v121, vcc
	v_add_co_u32_e32 v112, vcc, s49, v120
	v_lshl_add_u64 v[124:125], s[58:59], 0, v[96:97]
	s_nop 0
	v_addc_co_u32_e32 v113, vcc, 0, v121, vcc
	v_add_co_u32_e32 v116, vcc, 0x8000, v120
	s_nop 0
	s_nop 0
	v_addc_co_u32_e32 v117, vcc, 0, v121, vcc
	v_add_co_u32_e32 v120, vcc, 0xd000, v120
	s_nop 0
	s_nop 0
	v_addc_co_u32_e32 v121, vcc, 0, v121, vcc
	v_add_co_u32_e32 v124, vcc, 0x2000, v124
	s_nop 0
	s_nop 0
	v_addc_co_u32_e32 v125, vcc, 0, v125, vcc
	v_mov_b32_e32 v192, 0
	v_mov_b64_e32 v[198:199], 0
	v_mov_b64_e32 v[200:201], 0
	v_mov_b64_e32 v[206:207], 0
	v_mov_b64_e32 v[208:209], 0
	v_mov_b64_e32 v[194:195], 0
	v_mov_b64_e32 v[196:197], 0
	v_mov_b64_e32 v[202:203], 0
	v_mov_b64_e32 v[204:205], 0
	s_and_saveexec_b64 s[36:37], s[18:19]
	s_cbranch_execz .LBB0_318
	ds_read_b128 v[202:205], v238
	ds_read_b128 v[206:209], v238 offset:512
	ds_read_b128 v[194:197], v238 offset:1024
	ds_read_b128 v[198:201], v238 offset:1536

; #define LAS __attribute__((address_space(3)))
; __device__ __forceinline__ float sigmoidf_(float x) { return __builtin_amdgcn_rcpf(1.0f + __expf(-x)); }
;     __device__ __forceinline__ void operator()(AccRef acc, const Unit& u, int wr, int wc, int fr, int fq) const {
;     ...
;                 f32x4 h2v = (f32x4){0.f, 0.f, 0.f, 0.f}, h3v = h2v, h2g = h2v, h3g = h2v;
;                 const int pb = ai * 2 + wr - 1;
;                 if (pb >= 0 && fr == 0) { const LAS float* xp = xch + (pb * 2) * 256 + clb + 4 * n;
;                     h2v = *(const LAS f32x4*)(xp); h3v = *(const LAS f32x4*)(xp + 256); h2g = *(const LAS f32x4*)(xp + 128); h3g = *(const LAS f32x4*)(xp + 256 + 128); }
;                 float o[4][4];
; #pragma unroll
;                 for (int j = 0; j < 4; ++j) {
;                     const float v0 = acc[ai][0][0][n][j], v1 = acc[ai][0][1][n][j], v2 = acc[ai][0][2][n][j], v3 = acc[ai][0][3][n][j];
;                     const float g0 = acc[ai][1][0][n][j], g1 = acc[ai][1][1][n][j], g2 = acc[ai][1][2][n][j], g3 = acc[ai][1][3][n][j];
;                     const float pv3 = dpp_upd<0x111>(h3v[j], v3), pv2 = dpp_upd<0x111>(h2v[j], v2), pg3 = dpp_upd<0x111>(h3g[j], g3), pg2 = dpp_upd<0x111>(h2g[j], g2);
;                     const float hv0 = bvv[j] + w2v[j] * v0 + w1v[j] * pv3 + w0v[j] * pv2, hv1 = bvv[j] + w2v[j] * v1 + w1v[j] * v0 + w0v[j] * pv3;
;                     const float hv2 = bvv[j] + w2v[j] * v2 + w1v[j] * v1 + w0v[j] * v0, hv3 = bvv[j] + w2v[j] * v3 + w1v[j] * v2 + w0v[j] * v1;
;                     const float hg0 = bvg[j] + w2g[j] * g0 + w1g[j] * pg3 + w0g[j] * pg2, hg1 = bvg[j] + w2g[j] * g1 + w1g[j] * g0 + w0g[j] * pg3;
;                     const float hg2 = bvg[j] + w2g[j] * g2 + w1g[j] * g1 + w0g[j] * g0, hg3 = bvg[j] + w2g[j] * g3 + w1g[j] * g2 + w0g[j] * g1;
;                     o[0][j] = hg0 * sigmoidf_(hg0) * hv0; o[1][j] = hg1 * sigmoidf_(hg1) * hv1; o[2][j] = hg2 * sigmoidf_(hg2) * hv2; o[3][j] = hg3 * sigmoidf_(hg3) * hv3; }
; #pragma unroll
;                 for (int m = 0; m < 4; ++m) { u32x2 w; w.x = cvt_pk_bf16(o[m][0], o[m][1]); w.y = cvt_pk_bf16(o[m][2], o[m][3]);
;                     *(u32x2*)(Aout + (size_t)(row0 + ai * 128 + m) * FH + hc0 + 4 * n) = w; } } }
.LBB0_316:
	s_or_b64 exec, exec, s[40:41]
	v_pk_fma_f32 v[248:249], v[152:153], v[184:185], v[188:189]
	v_mov_b32_dpp v206, v128 row_shr:1 row_mask:0xf bank_mask:0xf
	v_mov_b32_dpp v207, v129 row_shr:1 row_mask:0xf bank_mask:0xf
	v_pk_fma_f32 v[248:249], v[180:181], v[198:199], v[248:249]
	v_mov_b32_dpp v194, v148 row_shr:1 row_mask:0xf bank_mask:0xf
	v_pk_fma_f32 v[206:207], v[176:177], v[206:207], v[248:249]
	v_mov_b32_dpp v195, v149 row_shr:1 row_mask:0xf bank_mask:0xf
	v_exp_f32_e32 v248, v206
	v_exp_f32_e32 v249, v207
	v_pk_fma_f32 v[250:251], v[156:157], v[168:169], v[172:173]
	v_pk_add_f32 v[248:249], v[248:249], 1.0 op_sel_hi:[1,0]
	v_rcp_f32_e32 v248, v248
	v_rcp_f32_e32 v249, v249
	v_mov_b32_dpp v202, v136 row_shr:1 row_mask:0xf bank_mask:0xf
	v_mov_b32_dpp v203, v137 row_shr:1 row_mask:0xf bank_mask:0xf
	v_pk_fma_f32 v[250:251], v[164:165], v[194:195], v[250:251]
	v_pk_mul_f32 v[206:207], v[206:207], v[248:249]
	v_pk_fma_f32 v[202:203], v[160:161], v[202:203], v[250:251]
	v_mov_b32_dpp v200, v142 row_shr:1 row_mask:0xf bank_mask:0xf
	v_mov_b32_dpp v201, v143 row_shr:1 row_mask:0xf bank_mask:0xf
	v_pk_mul_f32 v[202:203], v[202:203], v[206:207]
	v_pk_fma_f32 v[206:207], v[154:155], v[186:187], v[190:191]
	v_mov_b32_dpp v208, v130 row_shr:1 row_mask:0xf bank_mask:0xf
	v_mov_b32_dpp v209, v131 row_shr:1 row_mask:0xf bank_mask:0xf
	v_pk_fma_f32 v[206:207], v[182:183], v[200:201], v[206:207]
	v_mov_b32_dpp v196, v150 row_shr:1 row_mask:0xf bank_mask:0xf
	v_pk_fma_f32 v[206:207], v[178:179], v[208:209], v[206:207]
	v_mov_b32_dpp v197, v151 row_shr:1 row_mask:0xf bank_mask:0xf
	v_exp_f32_e32 v193, v206
	v_exp_f32_e32 v209, v207
	v_cvt_pk_bf16_f32 v208, v202, v203
	v_add_f32_e32 v193, 1.0, v193
	v_rcp_f32_e32 v202, v193
	v_add_f32_e32 v193, 1.0, v209
	v_rcp_f32_e32 v203, v193
	v_pk_fma_f32 v[248:249], v[158:159], v[170:171], v[174:175]
	v_mov_b32_dpp v204, v138 row_shr:1 row_mask:0xf bank_mask:0xf
	v_mov_b32_dpp v205, v139 row_shr:1 row_mask:0xf bank_mask:0xf
	v_pk_fma_f32 v[248:249], v[166:167], v[196:197], v[248:249]
	v_pk_mul_f32 v[202:203], v[206:207], v[202:203]
	v_pk_fma_f32 v[204:205], v[162:163], v[204:205], v[248:249]
	v_lshl_add_u32 v246, s34, 8, v236
	v_pk_mul_f32 v[202:203], v[204:205], v[202:203]
	v_lshlrev_b64 v[204:205], 1, v[232:233]
	v_pk_fma_f32 v[232:233], v[132:133], v[184:185], v[188:189]
	v_mov_b64_e32 v[206:207], s[60:61]
	v_pk_fma_f32 v[232:233], v[152:153], v[180:181], v[232:233]
	v_cvt_pk_bf16_f32 v209, v202, v203
	v_pk_fma_f32 v[198:199], v[176:177], v[198:199], v[232:233]
	v_mad_i64_i32 v[202:203], s[34:35], v246, s74, v[206:207]
	v_exp_f32_e32 v193, v198
	v_exp_f32_e32 v232, v199
	v_lshl_add_u64 v[202:203], v[202:203], 0, v[204:205]
	v_add_f32_e32 v193, 1.0, v193
	v_mov_b32_e32 v247, v208
	v_mov_b32_e32 v248, v209
	v_rcp_f32_e32 v208, v193
	v_add_f32_e32 v193, 1.0, v232
	v_rcp_f32_e32 v209, v193
	v_pk_fma_f32 v[232:233], v[144:145], v[168:169], v[172:173]
	v_pk_fma_f32 v[140:141], v[140:141], v[184:185], v[188:189]
	v_pk_fma_f32 v[232:233], v[156:157], v[164:165], v[232:233]
	v_pk_mul_f32 v[198:199], v[198:199], v[208:209]
	v_pk_fma_f32 v[194:195], v[160:161], v[194:195], v[232:233]
	v_pk_fma_f32 v[208:209], v[146:147], v[170:171], v[174:175]
	v_pk_mul_f32 v[194:195], v[194:195], v[198:199]
	v_pk_fma_f32 v[198:199], v[134:135], v[186:187], v[190:191]
	v_pk_fma_f32 v[208:209], v[158:159], v[166:167], v[208:209]
	v_pk_fma_f32 v[198:199], v[154:155], v[182:183], v[198:199]
	v_pk_fma_f32 v[196:197], v[162:163], v[196:197], v[208:209]
	v_pk_fma_f32 v[198:199], v[178:179], v[200:201], v[198:199]
	v_cvt_pk_bf16_f32 v194, v194, v195
	v_exp_f32_e32 v200, v198
	v_exp_f32_e32 v201, v199
	v_pk_fma_f32 v[148:149], v[148:149], v[168:169], v[172:173]
	v_pk_add_f32 v[200:201], v[200:201], 1.0 op_sel_hi:[1,0]
	v_rcp_f32_e32 v200, v200
	v_rcp_f32_e32 v201, v201
	v_or_b32_e32 v193, 1, v246
	v_pk_mul_f32 v[198:199], v[198:199], v[200:201]
	s_nop 0
	v_pk_mul_f32 v[196:197], v[196:197], v[198:199]
	v_pk_fma_f32 v[198:199], v[128:129], v[184:185], v[188:189]
	v_cvt_pk_bf16_f32 v195, v196, v197
	v_pk_fma_f32 v[198:199], v[132:133], v[180:181], v[198:199]
	v_mad_i64_i32 v[196:197], s[34:35], v193, s74, v[206:207]
	v_pk_fma_f32 v[152:153], v[152:153], v[176:177], v[198:199]
	v_lshl_add_u64 v[196:197], v[196:197], 0, v[204:205]
	v_exp_f32_e32 v193, v152
	v_exp_f32_e32 v198, v153
	v_mov_b32_e32 v249, v194
	v_mov_b32_e32 v250, v195
	v_add_f32_e32 v193, 1.0, v193
	v_rcp_f32_e32 v194, v193
	v_add_f32_e32 v193, 1.0, v198
	v_rcp_f32_e32 v195, v193
	v_pk_fma_f32 v[198:199], v[136:137], v[168:169], v[172:173]
	v_pk_fma_f32 v[128:129], v[128:129], v[180:181], v[140:141]
	v_pk_fma_f32 v[198:199], v[144:145], v[164:165], v[198:199]
	v_pk_fma_f32 v[128:129], v[132:133], v[176:177], v[128:129]
	v_pk_fma_f32 v[156:157], v[156:157], v[160:161], v[198:199]
	v_pk_mul_f32 v[152:153], v[152:153], v[194:195]
	v_pk_mul_f32 v[152:153], v[156:157], v[152:153]
	v_pk_fma_f32 v[156:157], v[130:131], v[186:187], v[190:191]
	v_exp_f32_e32 v140, v128
	v_pk_fma_f32 v[132:133], v[142:143], v[186:187], v[190:191]
	v_pk_fma_f32 v[156:157], v[134:135], v[182:183], v[156:157]
	v_pk_fma_f32 v[130:131], v[130:131], v[182:183], v[132:133]
	v_pk_fma_f32 v[154:155], v[154:155], v[178:179], v[156:157]
	v_pk_fma_f32 v[130:131], v[134:135], v[178:179], v[130:131]
	v_exp_f32_e32 v157, v154
	v_exp_f32_e32 v141, v129
	v_exp_f32_e32 v132, v130
	v_exp_f32_e32 v133, v131
	v_exp_f32_e32 v193, v155
	v_pk_add_f32 v[140:141], v[140:141], 1.0 op_sel_hi:[1,0]
	v_pk_add_f32 v[132:133], v[132:133], 1.0 op_sel_hi:[1,0]
	v_cvt_pk_bf16_f32 v156, v152, v153
	v_add_f32_e32 v152, 1.0, v157
; #define LAS __attribute__((address_space(3)))
; __device__ __forceinline__ float sigmoidf_(float x) { return __builtin_amdgcn_rcpf(1.0f + __expf(-x)); }
;     __device__ __forceinline__ void operator()(AccRef acc, const Unit& u, int wr, int wc, int fr, int fq) const {
;     ...
;                 f32x4 h2v = (f32x4){0.f, 0.f, 0.f, 0.f}, h3v = h2v, h2g = h2v, h3g = h2v;
;                 const int pb = ai * 2 + wr - 1;
;                 if (pb >= 0 && fr == 0) { const LAS float* xp = xch + (pb * 2) * 256 + clb + 4 * n;
;                     h2v = *(const LAS f32x4*)(xp); h3v = *(const LAS f32x4*)(xp + 256); h2g = *(const LAS f32x4*)(xp + 128); h3g = *(const LAS f32x4*)(xp + 256 + 128); }
;                 float o[4][4];
; #pragma unroll
;                 for (int j = 0; j < 4; ++j) {
;                     const float v0 = acc[ai][0][0][n][j], v1 = acc[ai][0][1][n][j], v2 = acc[ai][0][2][n][j], v3 = acc[ai][0][3][n][j];
;                     const float g0 = acc[ai][1][0][n][j], g1 = acc[ai][1][1][n][j], g2 = acc[ai][1][2][n][j], g3 = acc[ai][1][3][n][j];
;                     const float pv3 = dpp_upd<0x111>(h3v[j], v3), pv2 = dpp_upd<0x111>(h2v[j], v2), pg3 = dpp_upd<0x111>(h3g[j], g3), pg2 = dpp_upd<0x111>(h2g[j], g2);
;                     const float hv0 = bvv[j] + w2v[j] * v0 + w1v[j] * pv3 + w0v[j] * pv2, hv1 = bvv[j] + w2v[j] * v1 + w1v[j] * v0 + w0v[j] * pv3;
;                     const float hv2 = bvv[j] + w2v[j] * v2 + w1v[j] * v1 + w0v[j] * v0, hv3 = bvv[j] + w2v[j] * v3 + w1v[j] * v2 + w0v[j] * v1;
;                     const float hg0 = bvg[j] + w2g[j] * g0 + w1g[j] * pg3 + w0g[j] * pg2, hg1 = bvg[j] + w2g[j] * g1 + w1g[j] * g0 + w0g[j] * pg3;
;                     const float hg2 = bvg[j] + w2g[j] * g2 + w1g[j] * g1 + w0g[j] * g0, hg3 = bvg[j] + w2g[j] * g3 + w1g[j] * g2 + w0g[j] * g1;
;                     o[0][j] = hg0 * sigmoidf_(hg0) * hv0; o[1][j] = hg1 * sigmoidf_(hg1) * hv1; o[2][j] = hg2 * sigmoidf_(hg2) * hv2; o[3][j] = hg3 * sigmoidf_(hg3) * hv3; }
; #pragma unroll
;                 for (int m = 0; m < 4; ++m) { u32x2 w; w.x = cvt_pk_bf16(o[m][0], o[m][1]); w.y = cvt_pk_bf16(o[m][2], o[m][3]);
;                     *(u32x2*)(Aout + (size_t)(row0 + ai * 128 + m) * FH + hc0 + 4 * n) = w; } } }
	v_add_f32_e32 v153, 1.0, v193
	v_rcp_f32_e32 v140, v140
	v_rcp_f32_e32 v141, v141
	v_rcp_f32_e32 v132, v132
	v_rcp_f32_e32 v133, v133
	v_rcp_f32_e32 v152, v152
	v_rcp_f32_e32 v153, v153
	v_pk_fma_f32 v[142:143], v[150:151], v[170:171], v[174:175]
	v_pk_fma_f32 v[194:195], v[138:139], v[170:171], v[174:175]
	v_pk_fma_f32 v[136:137], v[136:137], v[164:165], v[148:149]
	v_pk_fma_f32 v[134:135], v[138:139], v[166:167], v[142:143]
	v_pk_fma_f32 v[194:195], v[146:147], v[166:167], v[194:195]
	v_pk_fma_f32 v[136:137], v[144:145], v[160:161], v[136:137]
	v_pk_mul_f32 v[128:129], v[128:129], v[140:141]
	v_pk_fma_f32 v[134:135], v[146:147], v[162:163], v[134:135]
	v_pk_mul_f32 v[130:131], v[130:131], v[132:133]
	v_pk_fma_f32 v[158:159], v[158:159], v[162:163], v[194:195]
	v_pk_mul_f32 v[152:153], v[154:155], v[152:153]
	v_pk_mul_f32 v[128:129], v[136:137], v[128:129]
	v_pk_mul_f32 v[130:131], v[134:135], v[130:131]
	v_pk_mul_f32 v[152:153], v[158:159], v[152:153]
	v_cvt_pk_bf16_f32 v128, v128, v129
	v_cvt_pk_bf16_f32 v129, v130, v131
	v_or_b32_e32 v130, 3, v246
	v_cvt_pk_bf16_f32 v157, v152, v153
	v_or_b32_e32 v152, 2, v246
	v_mad_i64_i32 v[130:131], s[34:35], v130, s74, v[206:207]
	v_mad_i64_i32 v[152:153], s[34:35], v152, s74, v[206:207]
	v_lshl_add_u64 v[140:141], v[130:131], 0, v[204:205]
	v_lshl_add_u64 v[152:153], v[152:153], 0, v[204:205]
	v_mov_b32_e32 v251, v128
	v_mov_b32_e32 v253, v129
	v_mov_b32_e32 v193, 0
	v_mov_b64_e32 v[194:195], 0
	v_mov_b64_e32 v[136:137], 0
	v_mov_b64_e32 v[138:139], 0
	v_mov_b64_e32 v[128:129], 0
	v_mov_b64_e32 v[130:131], 0
	v_mov_b64_e32 v[132:133], 0
	v_mov_b64_e32 v[134:135], 0
	v_mov_b32_e32 v254, v156
	v_mov_b32_e32 v255, v157
	s_and_saveexec_b64 s[34:35], s[22:23]
	s_cbranch_execz .LBB0_320
	ds_read_b128 v[132:135], v237 offset:2048
	ds_read_b128 v[136:139], v237 offset:2560
	ds_read_b128 v[128:131], v237 offset:3072
	ds_read_b128 v[192:195], v237 offset:3584
.LBB0_320:
	s_or_b64 exec, exec, s[34:35]
	s_waitcnt lgkmcnt(0)
	v_mov_b32_dpp v192, v72 row_shr:1 row_mask:0xf bank_mask:0xf
	v_mov_b32_dpp v193, v73 row_shr:1 row_mask:0xf bank_mask:0xf
	v_pk_fma_f32 v[142:143], v[88:89], v[184:185], v[188:189]
	v_mov_b32_dpp v136, v64 row_shr:1 row_mask:0xf bank_mask:0xf
	v_mov_b32_dpp v137, v65 row_shr:1 row_mask:0xf bank_mask:0xf
	v_pk_fma_f32 v[142:143], v[180:181], v[192:193], v[142:143]
	v_mov_b32_dpp v128, v84 row_shr:1 row_mask:0xf bank_mask:0xf
	v_pk_fma_f32 v[136:137], v[176:177], v[136:137], v[142:143]
	v_mov_b32_dpp v129, v85 row_shr:1 row_mask:0xf bank_mask:0xf
	v_exp_f32_e32 v142, v136
	v_exp_f32_e32 v143, v137
	v_pk_fma_f32 v[144:145], v[92:93], v[168:169], v[172:173]
	v_mov_b32_dpp v132, v76 row_shr:1 row_mask:0xf bank_mask:0xf
	v_pk_add_f32 v[142:143], v[142:143], 1.0 op_sel_hi:[1,0]
	v_rcp_f32_e32 v142, v142
	v_rcp_f32_e32 v143, v143
	v_mov_b32_dpp v133, v77 row_shr:1 row_mask:0xf bank_mask:0xf
	v_pk_fma_f32 v[144:145], v[164:165], v[128:129], v[144:145]
	v_mov_b32_dpp v194, v74 row_shr:1 row_mask:0xf bank_mask:0xf
	v_pk_fma_f32 v[132:133], v[160:161], v[132:133], v[144:145]
	v_pk_mul_f32 v[136:137], v[136:137], v[142:143]
	v_mov_b32_dpp v195, v75 row_shr:1 row_mask:0xf bank_mask:0xf
	v_pk_mul_f32 v[132:133], v[132:133], v[136:137]
	v_pk_fma_f32 v[136:137], v[90:91], v[186:187], v[190:191]
	v_mov_b32_dpp v138, v66 row_shr:1 row_mask:0xf bank_mask:0xf
	v_mov_b32_dpp v139, v67 row_shr:1 row_mask:0xf bank_mask:0xf
	v_pk_fma_f32 v[136:137], v[182:183], v[194:195], v[136:137]
	v_mov_b32_dpp v130, v86 row_shr:1 row_mask:0xf bank_mask:0xf
	v_pk_fma_f32 v[136:137], v[178:179], v[138:139], v[136:137]
	v_mov_b32_dpp v131, v87 row_shr:1 row_mask:0xf bank_mask:0xf
	v_exp_f32_e32 v139, v136
	v_exp_f32_e32 v142, v137
	v_cvt_pk_bf16_f32 v138, v132, v133
	v_add_f32_e32 v132, 1.0, v139
	v_rcp_f32_e32 v132, v132
	v_add_f32_e32 v133, 1.0, v142
	v_rcp_f32_e32 v133, v133
	v_pk_fma_f32 v[142:143], v[94:95], v[170:171], v[174:175]
	v_mov_b32_dpp v134, v78 row_shr:1 row_mask:0xf bank_mask:0xf
	v_mov_b32_dpp v135, v79 row_shr:1 row_mask:0xf bank_mask:0xf
	v_pk_mul_f32 v[132:133], v[136:137], v[132:133]
	v_pk_fma_f32 v[136:137], v[68:69], v[184:185], v[188:189]
	v_pk_fma_f32 v[142:143], v[166:167], v[130:131], v[142:143]
	v_pk_fma_f32 v[136:137], v[88:89], v[180:181], v[136:137]
	v_pk_fma_f32 v[134:135], v[162:163], v[134:135], v[142:143]
	v_pk_fma_f32 v[136:137], v[176:177], v[192:193], v[136:137]
	v_add_u32_e32 v146, 0x80, v246
	v_exp_f32_e32 v142, v136
	v_exp_f32_e32 v143, v137
	v_pk_mul_f32 v[132:133], v[134:135], v[132:133]
	v_mov_b64_e32 v[134:135], s[60:61]
	v_cvt_pk_bf16_f32 v139, v132, v133
	v_mad_i64_i32 v[132:133], s[34:35], v146, s74, v[134:135]
	v_lshl_add_u64 v[132:133], v[132:133], 0, v[204:205]
	v_mov_b32_e32 v144, v138
	v_mov_b32_e32 v145, v139
	v_add_f32_e32 v138, 1.0, v142
	v_add_f32_e32 v139, 1.0, v143
	v_rcp_f32_e32 v138, v138
	v_rcp_f32_e32 v139, v139
	v_pk_fma_f32 v[142:143], v[80:81], v[168:169], v[172:173]
	v_pk_fma_f32 v[72:73], v[72:73], v[184:185], v[188:189]
	v_pk_fma_f32 v[142:143], v[92:93], v[164:165], v[142:143]
	v_pk_mul_f32 v[136:137], v[136:137], v[138:139]
	v_pk_fma_f32 v[128:129], v[160:161], v[128:129], v[142:143]
	v_pk_fma_f32 v[84:85], v[84:85], v[168:169], v[172:173]
	v_pk_mul_f32 v[128:129], v[128:129], v[136:137]
	v_pk_fma_f32 v[136:137], v[70:71], v[186:187], v[190:191]
	s_nop 0
	v_pk_fma_f32 v[136:137], v[90:91], v[182:183], v[136:137]
	s_nop 0
	v_pk_fma_f32 v[136:137], v[178:179], v[194:195], v[136:137]
	s_nop 0
	v_exp_f32_e32 v139, v136
	v_exp_f32_e32 v142, v137
	v_cvt_pk_bf16_f32 v138, v128, v129
	v_add_f32_e32 v128, 1.0, v139
	v_rcp_f32_e32 v128, v128
	v_add_f32_e32 v129, 1.0, v142
; #define LAS __attribute__((address_space(3)))
; __device__ __forceinline__ float sigmoidf_(float x) { return __builtin_amdgcn_rcpf(1.0f + __expf(-x)); }
;     __device__ __forceinline__ void operator()(AccRef acc, const Unit& u, int wr, int wc, int fr, int fq) const {
;     ...
;                 f32x4 h2v = (f32x4){0.f, 0.f, 0.f, 0.f}, h3v = h2v, h2g = h2v, h3g = h2v;
;                 const int pb = ai * 2 + wr - 1;
;                 if (pb >= 0 && fr == 0) { const LAS float* xp = xch + (pb * 2) * 256 + clb + 4 * n;
;                     h2v = *(const LAS f32x4*)(xp); h3v = *(const LAS f32x4*)(xp + 256); h2g = *(const LAS f32x4*)(xp + 128); h3g = *(const LAS f32x4*)(xp + 256 + 128); }
;                 float o[4][4];
; #pragma unroll
;                 for (int j = 0; j < 4; ++j) {
;                     const float v0 = acc[ai][0][0][n][j], v1 = acc[ai][0][1][n][j], v2 = acc[ai][0][2][n][j], v3 = acc[ai][0][3][n][j];
;                     const float g0 = acc[ai][1][0][n][j], g1 = acc[ai][1][1][n][j], g2 = acc[ai][1][2][n][j], g3 = acc[ai][1][3][n][j];
;                     const float pv3 = dpp_upd<0x111>(h3v[j], v3), pv2 = dpp_upd<0x111>(h2v[j], v2), pg3 = dpp_upd<0x111>(h3g[j], g3), pg2 = dpp_upd<0x111>(h2g[j], g2);
;                     const float hv0 = bvv[j] + w2v[j] * v0 + w1v[j] * pv3 + w0v[j] * pv2, hv1 = bvv[j] + w2v[j] * v1 + w1v[j] * v0 + w0v[j] * pv3;
;                     const float hv2 = bvv[j] + w2v[j] * v2 + w1v[j] * v1 + w0v[j] * v0, hv3 = bvv[j] + w2v[j] * v3 + w1v[j] * v2 + w0v[j] * v1;
;                     const float hg0 = bvg[j] + w2g[j] * g0 + w1g[j] * pg3 + w0g[j] * pg2, hg1 = bvg[j] + w2g[j] * g1 + w1g[j] * g0 + w0g[j] * pg3;
;                     const float hg2 = bvg[j] + w2g[j] * g2 + w1g[j] * g1 + w0g[j] * g0, hg3 = bvg[j] + w2g[j] * g3 + w1g[j] * g2 + w0g[j] * g1;
;                     o[0][j] = hg0 * sigmoidf_(hg0) * hv0; o[1][j] = hg1 * sigmoidf_(hg1) * hv1; o[2][j] = hg2 * sigmoidf_(hg2) * hv2; o[3][j] = hg3 * sigmoidf_(hg3) * hv3; }
; #pragma unroll
;                 for (int m = 0; m < 4; ++m) { u32x2 w; w.x = cvt_pk_bf16(o[m][0], o[m][1]); w.y = cvt_pk_bf16(o[m][2], o[m][3]);
;                     *(u32x2*)(Aout + (size_t)(row0 + ai * 128 + m) * FH + hc0 + 4 * n) = w; } } }
	v_rcp_f32_e32 v129, v129
	v_pk_fma_f32 v[142:143], v[82:83], v[170:171], v[174:175]
	v_pk_mul_f32 v[128:129], v[136:137], v[128:129]
	v_pk_fma_f32 v[142:143], v[94:95], v[166:167], v[142:143]
	v_pk_fma_f32 v[136:137], v[76:77], v[168:169], v[172:173]
	v_pk_fma_f32 v[130:131], v[162:163], v[130:131], v[142:143]
	v_pk_fma_f32 v[136:137], v[80:81], v[164:165], v[136:137]
	v_pk_mul_f32 v[128:129], v[130:131], v[128:129]
	v_pk_fma_f32 v[130:131], v[64:65], v[184:185], v[188:189]
	v_pk_fma_f32 v[64:65], v[64:65], v[180:181], v[72:73]
	v_pk_fma_f32 v[130:131], v[68:69], v[180:181], v[130:131]
	v_pk_fma_f32 v[64:65], v[68:69], v[176:177], v[64:65]
	v_pk_fma_f32 v[88:89], v[88:89], v[176:177], v[130:131]
	v_pk_fma_f32 v[92:93], v[92:93], v[160:161], v[136:137]
	v_exp_f32_e32 v130, v88
	v_exp_f32_e32 v131, v89
	v_exp_f32_e32 v72, v64
	v_pk_add_f32 v[130:131], v[130:131], 1.0 op_sel_hi:[1,0]
	v_rcp_f32_e32 v130, v130
	v_rcp_f32_e32 v131, v131
	v_pk_fma_f32 v[68:69], v[74:75], v[186:187], v[190:191]
	v_exp_f32_e32 v73, v65
	v_pk_mul_f32 v[88:89], v[88:89], v[130:131]
	v_pk_mul_f32 v[88:89], v[92:93], v[88:89]
	v_pk_fma_f32 v[92:93], v[66:67], v[186:187], v[190:191]
	v_pk_fma_f32 v[66:67], v[66:67], v[182:183], v[68:69]
	v_pk_fma_f32 v[92:93], v[70:71], v[182:183], v[92:93]
	v_pk_fma_f32 v[66:67], v[70:71], v[178:179], v[66:67]
	v_pk_fma_f32 v[90:91], v[90:91], v[178:179], v[92:93]
	v_exp_f32_e32 v93, v90
	v_exp_f32_e32 v68, v66
	v_exp_f32_e32 v69, v67
	v_exp_f32_e32 v130, v91
	v_pk_add_f32 v[72:73], v[72:73], 1.0 op_sel_hi:[1,0]
	v_pk_add_f32 v[68:69], v[68:69], 1.0 op_sel_hi:[1,0]
	v_cvt_pk_bf16_f32 v92, v88, v89
	v_add_f32_e32 v88, 1.0, v93
	v_add_f32_e32 v89, 1.0, v130
	v_rcp_f32_e32 v72, v72
	v_rcp_f32_e32 v73, v73
	v_rcp_f32_e32 v68, v68
	v_rcp_f32_e32 v69, v69
	v_rcp_f32_e32 v88, v88
	v_rcp_f32_e32 v89, v89
	v_pk_fma_f32 v[74:75], v[86:87], v[170:171], v[174:175]
	v_pk_fma_f32 v[130:131], v[78:79], v[170:171], v[174:175]
	v_pk_fma_f32 v[76:77], v[76:77], v[164:165], v[84:85]
	v_pk_fma_f32 v[70:71], v[78:79], v[166:167], v[74:75]
	v_pk_fma_f32 v[130:131], v[82:83], v[166:167], v[130:131]
	v_pk_fma_f32 v[76:77], v[80:81], v[160:161], v[76:77]
	v_pk_mul_f32 v[64:65], v[64:65], v[72:73]
	v_pk_fma_f32 v[70:71], v[82:83], v[162:163], v[70:71]
	v_pk_mul_f32 v[66:67], v[66:67], v[68:69]
	v_pk_fma_f32 v[94:95], v[94:95], v[162:163], v[130:131]
	v_pk_mul_f32 v[88:89], v[90:91], v[88:89]
	v_pk_mul_f32 v[64:65], v[76:77], v[64:65]
	v_pk_mul_f32 v[66:67], v[70:71], v[66:67]
	v_pk_mul_f32 v[88:89], v[94:95], v[88:89]
	v_cvt_pk_bf16_f32 v64, v64, v65
	v_cvt_pk_bf16_f32 v65, v66, v67
	v_add_u32_e32 v66, 0x83, v246
	v_cvt_pk_bf16_f32 v139, v128, v129
	v_add_u32_e32 v128, 0x81, v246
	v_cvt_pk_bf16_f32 v93, v88, v89
	v_add_u32_e32 v88, 0x82, v246
	v_mad_i64_i32 v[66:67], s[34:35], v66, s74, v[134:135]
	v_mad_i64_i32 v[128:129], s[34:35], v128, s74, v[134:135]
	v_mad_i64_i32 v[88:89], s[34:35], v88, s74, v[134:135]
	v_lshl_add_u64 v[82:83], v[66:67], 0, v[204:205]
	v_lshl_add_u64 v[128:129], v[128:129], 0, v[204:205]
	v_lshl_add_u64 v[88:89], v[88:89], 0, v[204:205]
	v_mov_b32_e32 v148, v64
	v_mov_b32_e32 v149, v65
	v_mov_b32_e32 v64, 0
	v_mov_b64_e32 v[70:71], 0
	v_mov_b64_e32 v[72:73], 0
	v_mov_b64_e32 v[78:79], 0
	v_mov_b64_e32 v[80:81], 0
	v_mov_b64_e32 v[66:67], 0
	v_mov_b64_e32 v[68:69], 0
	v_mov_b64_e32 v[74:75], 0
	v_mov_b64_e32 v[76:77], 0
	v_mov_b32_e32 v154, v138
	v_mov_b32_e32 v155, v139
	v_mov_b32_e32 v198, v92
	v_mov_b32_e32 v199, v93
	s_and_saveexec_b64 s[34:35], s[18:19]
	s_cbranch_execz .LBB0_322
	ds_read_b128 v[74:77], v242
	ds_read_b128 v[66:69], v241
	ds_read_b128 v[78:81], v240
	ds_read_b128 v[70:73], v239
; __device__ __forceinline__ float sigmoidf_(float x) { return __builtin_amdgcn_rcpf(1.0f + __expf(-x)); }
;     __device__ __forceinline__ void operator()(AccRef acc, const Unit& u, int wr, int wc, int fr, int fq) const {
;     ...
;                 float o[4][4];
; #pragma unroll
;                 for (int j = 0; j < 4; ++j) {
;                     const float v0 = acc[ai][0][0][n][j], v1 = acc[ai][0][1][n][j], v2 = acc[ai][0][2][n][j], v3 = acc[ai][0][3][n][j];
;                     const float g0 = acc[ai][1][0][n][j], g1 = acc[ai][1][1][n][j], g2 = acc[ai][1][2][n][j], g3 = acc[ai][1][3][n][j];
;                     const float pv3 = dpp_upd<0x111>(h3v[j], v3), pv2 = dpp_upd<0x111>(h2v[j], v2), pg3 = dpp_upd<0x111>(h3g[j], g3), pg2 = dpp_upd<0x111>(h2g[j], g2);
;                     const float hv0 = bvv[j] + w2v[j] * v0 + w1v[j] * pv3 + w0v[j] * pv2, hv1 = bvv[j] + w2v[j] * v1 + w1v[j] * v0 + w0v[j] * pv3;
;                     const float hv2 = bvv[j] + w2v[j] * v2 + w1v[j] * v1 + w0v[j] * v0, hv3 = bvv[j] + w2v[j] * v3 + w1v[j] * v2 + w0v[j] * v1;
;                     const float hg0 = bvg[j] + w2g[j] * g0 + w1g[j] * pg3 + w0g[j] * pg2, hg1 = bvg[j] + w2g[j] * g1 + w1g[j] * g0 + w0g[j] * pg3;
;                     const float hg2 = bvg[j] + w2g[j] * g2 + w1g[j] * g1 + w0g[j] * g0, hg3 = bvg[j] + w2g[j] * g3 + w1g[j] * g2 + w0g[j] * g1;
;                     o[0][j] = hg0 * sigmoidf_(hg0) * hv0; o[1][j] = hg1 * sigmoidf_(hg1) * hv1; o[2][j] = hg2 * sigmoidf_(hg2) * hv2; o[3][j] = hg3 * sigmoidf_(hg3) * hv3; }
; #pragma unroll
;                 for (int m = 0; m < 4; ++m) { u32x2 w; w.x = cvt_pk_bf16(o[m][0], o[m][1]); w.y = cvt_pk_bf16(o[m][2], o[m][3]);
;                     *(u32x2*)(Aout + (size_t)(row0 + ai * 128 + m) * FH + hc0 + 4 * n) = w; } } }
.LBB0_322:
	s_or_b64 exec, exec, s[34:35]
	s_waitcnt lgkmcnt(0)
	v_mov_b32_dpp v70, v44 row_shr:1 row_mask:0xf bank_mask:0xf
	v_mov_b32_dpp v71, v45 row_shr:1 row_mask:0xf bank_mask:0xf
	s_waitcnt vmcnt(0)
	v_pk_fma_f32 v[84:85], v[56:57], v[120:121], v[124:125]
	v_mov_b32_dpp v78, v32 row_shr:1 row_mask:0xf bank_mask:0xf
	v_mov_b32_dpp v79, v33 row_shr:1 row_mask:0xf bank_mask:0xf
	v_pk_fma_f32 v[84:85], v[116:117], v[70:71], v[84:85]
	v_mov_b32_dpp v66, v52 row_shr:1 row_mask:0xf bank_mask:0xf
	v_pk_fma_f32 v[78:79], v[112:113], v[78:79], v[84:85]
	v_mov_b32_dpp v67, v53 row_shr:1 row_mask:0xf bank_mask:0xf
	v_exp_f32_e32 v84, v78
	v_exp_f32_e32 v85, v79
	v_pk_fma_f32 v[86:87], v[60:61], v[104:105], v[108:109]
	v_pk_add_f32 v[84:85], v[84:85], 1.0 op_sel_hi:[1,0]
	v_rcp_f32_e32 v84, v84
	v_rcp_f32_e32 v85, v85
	v_mov_b32_dpp v74, v40 row_shr:1 row_mask:0xf bank_mask:0xf
	v_mov_b32_dpp v75, v41 row_shr:1 row_mask:0xf bank_mask:0xf
	v_pk_fma_f32 v[86:87], v[100:101], v[66:67], v[86:87]
	v_pk_mul_f32 v[78:79], v[78:79], v[84:85]
	v_pk_fma_f32 v[74:75], v[96:97], v[74:75], v[86:87]
	v_mov_b32_dpp v72, v46 row_shr:1 row_mask:0xf bank_mask:0xf
	v_mov_b32_dpp v73, v47 row_shr:1 row_mask:0xf bank_mask:0xf
	v_pk_mul_f32 v[74:75], v[74:75], v[78:79]
	v_pk_fma_f32 v[78:79], v[58:59], v[122:123], v[126:127]
	v_mov_b32_dpp v80, v34 row_shr:1 row_mask:0xf bank_mask:0xf
	v_mov_b32_dpp v81, v35 row_shr:1 row_mask:0xf bank_mask:0xf
	v_pk_fma_f32 v[78:79], v[118:119], v[72:73], v[78:79]
	v_mov_b32_dpp v68, v54 row_shr:1 row_mask:0xf bank_mask:0xf
	v_pk_fma_f32 v[78:79], v[114:115], v[80:81], v[78:79]
	v_mov_b32_dpp v69, v55 row_shr:1 row_mask:0xf bank_mask:0xf
	v_exp_f32_e32 v80, v78
	v_exp_f32_e32 v81, v79
	v_pk_fma_f32 v[84:85], v[62:63], v[106:107], v[110:111]
	v_pk_add_f32 v[80:81], v[80:81], 1.0 op_sel_hi:[1,0]
	v_rcp_f32_e32 v80, v80
	v_rcp_f32_e32 v81, v81
	v_mov_b32_dpp v76, v42 row_shr:1 row_mask:0xf bank_mask:0xf
	v_mov_b32_dpp v77, v43 row_shr:1 row_mask:0xf bank_mask:0xf
	v_pk_fma_f32 v[84:85], v[102:103], v[68:69], v[84:85]
	v_pk_mul_f32 v[78:79], v[78:79], v[80:81]
	v_pk_fma_f32 v[76:77], v[98:99], v[76:77], v[84:85]
	v_cvt_pk_bf16_f32 v74, v74, v75
	v_pk_mul_f32 v[76:77], v[76:77], v[78:79]
	v_pk_fma_f32 v[44:45], v[44:45], v[120:121], v[124:125]
	v_cvt_pk_bf16_f32 v75, v76, v77
	v_pk_fma_f32 v[76:77], v[36:37], v[120:121], v[124:125]
	v_mov_b32_e32 v90, v247
	v_mov_b32_e32 v91, v248
	v_mov_b32_e32 v92, v74
	v_mov_b32_e32 v93, v75
	global_store_dwordx4 v[202:203], v[90:93], off
	v_pk_fma_f32 v[76:77], v[56:57], v[116:117], v[76:77]
	v_pk_fma_f32 v[52:53], v[52:53], v[104:105], v[108:109]
	v_pk_fma_f32 v[70:71], v[112:113], v[70:71], v[76:77]
	s_nop 0
	v_exp_f32_e32 v74, v70
	v_exp_f32_e32 v75, v71
	s_nop 0
	v_pk_add_f32 v[74:75], v[74:75], 1.0 op_sel_hi:[1,0]
	v_rcp_f32_e32 v74, v74
	v_rcp_f32_e32 v75, v75
	v_pk_fma_f32 v[76:77], v[48:49], v[104:105], v[108:109]
	v_pk_mul_f32 v[70:71], v[70:71], v[74:75]
	v_pk_fma_f32 v[76:77], v[60:61], v[100:101], v[76:77]
	v_pk_fma_f32 v[74:75], v[50:51], v[106:107], v[110:111]
	v_pk_fma_f32 v[66:67], v[96:97], v[66:67], v[76:77]
	v_pk_fma_f32 v[74:75], v[62:63], v[102:103], v[74:75]
	v_pk_mul_f32 v[66:67], v[66:67], v[70:71]
	v_pk_fma_f32 v[70:71], v[38:39], v[122:123], v[126:127]
	v_pk_fma_f32 v[68:69], v[98:99], v[68:69], v[74:75]
	v_pk_fma_f32 v[70:71], v[58:59], v[118:119], v[70:71]
	v_cvt_pk_bf16_f32 v66, v66, v67
	v_pk_fma_f32 v[70:71], v[114:115], v[72:73], v[70:71]
	s_nop 0
	v_exp_f32_e32 v72, v70
	v_exp_f32_e32 v73, v71
	s_nop 0
	v_pk_add_f32 v[72:73], v[72:73], 1.0 op_sel_hi:[1,0]
	v_rcp_f32_e32 v72, v72
	v_rcp_f32_e32 v73, v73
	s_nop 0
	v_pk_mul_f32 v[70:71], v[70:71], v[72:73]
	s_nop 0
	v_pk_mul_f32 v[68:69], v[68:69], v[70:71]
	s_nop 0
	v_cvt_pk_bf16_f32 v67, v68, v69
	v_pk_fma_f32 v[68:69], v[32:33], v[120:121], v[124:125]
	v_mov_b32_e32 v134, v249
	v_mov_b32_e32 v135, v250
	v_mov_b32_e32 v136, v66
	v_mov_b32_e32 v137, v67
	global_store_dwordx4 v[196:197], v[134:137], off
	v_pk_fma_f32 v[68:69], v[36:37], v[116:117], v[68:69]
	v_pk_fma_f32 v[32:33], v[32:33], v[116:117], v[44:45]
	v_pk_fma_f32 v[56:57], v[56:57], v[112:113], v[68:69]
	v_pk_fma_f32 v[32:33], v[36:37], v[112:113], v[32:33]
	v_exp_f32_e32 v66, v56
	v_exp_f32_e32 v67, v57
	s_nop 0
	v_pk_add_f32 v[66:67], v[66:67], 1.0 op_sel_hi:[1,0]
	v_rcp_f32_e32 v66, v66
	v_rcp_f32_e32 v67, v67
	v_pk_fma_f32 v[68:69], v[40:41], v[104:105], v[108:109]
	v_exp_f32_e32 v44, v32
	v_pk_fma_f32 v[68:69], v[48:49], v[100:101], v[68:69]
	v_pk_mul_f32 v[56:57], v[56:57], v[66:67]
	v_pk_fma_f32 v[60:61], v[60:61], v[96:97], v[68:69]
	v_pk_fma_f32 v[36:37], v[46:47], v[122:123], v[126:127]
	v_pk_mul_f32 v[56:57], v[60:61], v[56:57]
	v_pk_fma_f32 v[60:61], v[34:35], v[122:123], v[126:127]
	v_pk_fma_f32 v[34:35], v[34:35], v[118:119], v[36:37]
	v_pk_fma_f32 v[60:61], v[38:39], v[118:119], v[60:61]
	v_pk_fma_f32 v[34:35], v[38:39], v[114:115], v[34:35]
	v_pk_fma_f32 v[58:59], v[58:59], v[114:115], v[60:61]
	v_exp_f32_e32 v60, v58
	v_exp_f32_e32 v45, v33
	v_exp_f32_e32 v36, v34
	v_exp_f32_e32 v37, v35
	v_exp_f32_e32 v61, v59
	v_cvt_pk_bf16_f32 v56, v56, v57
	v_pk_add_f32 v[44:45], v[44:45], 1.0 op_sel_hi:[1,0]
	v_pk_add_f32 v[36:37], v[36:37], 1.0 op_sel_hi:[1,0]
	v_pk_add_f32 v[60:61], v[60:61], 1.0 op_sel_hi:[1,0]
	v_rcp_f32_e32 v44, v44
	v_rcp_f32_e32 v45, v45
	v_rcp_f32_e32 v36, v36
	v_rcp_f32_e32 v37, v37
	v_rcp_f32_e32 v60, v60
	v_rcp_f32_e32 v61, v61
	v_pk_fma_f32 v[46:47], v[54:55], v[106:107], v[110:111]
	v_pk_fma_f32 v[66:67], v[42:43], v[106:107], v[110:111]
	v_pk_fma_f32 v[40:41], v[40:41], v[100:101], v[52:53]
	v_pk_fma_f32 v[38:39], v[42:43], v[102:103], v[46:47]
	v_pk_fma_f32 v[66:67], v[50:51], v[102:103], v[66:67]
	v_pk_fma_f32 v[40:41], v[48:49], v[96:97], v[40:41]
	v_pk_mul_f32 v[32:33], v[32:33], v[44:45]
	v_pk_fma_f32 v[38:39], v[50:51], v[98:99], v[38:39]
	v_pk_mul_f32 v[34:35], v[34:35], v[36:37]
	v_pk_fma_f32 v[62:63], v[62:63], v[98:99], v[66:67]
	v_pk_mul_f32 v[58:59], v[58:59], v[60:61]
	v_pk_mul_f32 v[32:33], v[40:41], v[32:33]
	v_pk_mul_f32 v[34:35], v[38:39], v[34:35]
	v_pk_mul_f32 v[58:59], v[62:63], v[58:59]
	v_cvt_pk_bf16_f32 v32, v32, v33
	v_cvt_pk_bf16_f32 v33, v34, v35
	v_cvt_pk_bf16_f32 v57, v58, v59
	v_mov_b32_e32 v158, v251
	v_mov_b32_e32 v159, v253
	v_mov_b32_e32 v160, v32
	v_mov_b32_e32 v161, v33
	global_store_dwordx4 v[140:141], v[158:161], off
	v_mov_b32_e32 v65, 0
	v_mov_b64_e32 v[66:67], 0
	v_mov_b64_e32 v[40:41], 0
	v_mov_b64_e32 v[42:43], 0
	v_mov_b64_e32 v[32:33], 0
	v_mov_b64_e32 v[34:35], 0
	v_mov_b64_e32 v[36:37], 0
	v_mov_b64_e32 v[38:39], 0
	v_mov_b32_e32 v162, v254
	v_mov_b32_e32 v163, v255
	v_mov_b32_e32 v164, v56
	v_mov_b32_e32 v165, v57
	global_store_dwordx4 v[152:153], v[162:165], off
	s_and_saveexec_b64 s[34:35], s[22:23]
	s_cbranch_execz .LBB0_305
	ds_read_b128 v[36:39], v237 offset:2064
	ds_read_b128 v[40:43], v237 offset:2576
	ds_read_b128 v[32:35], v237 offset:3088
	ds_read_b128 v[64:67], v237 offset:3600
	s_branch .LBB0_305

;     __device__ __forceinline__ void operator()(AccRef acc, const Unit& u, int wr, int wc, int fr, int fq) const {
;     ...
;         float* rawu = raw + (size_t)(u.pm * 22 + u.pn) * 1024;
;         if (wr == 0 && fr == 0) {
; #pragma unroll
;             for (int bj = 0; bj < 2; ++bj)
; #pragma unroll
;                 for (int n = 0; n < 2; ++n) { *(f32x4*)(rawu + 0 * 256 + bj * 128 + clb + 4 * n) = acc[0][bj][0][n]; *(f32x4*)(rawu + 1 * 256 + bj * 128 + clb + 4 * n) = acc[0][bj][1][n]; }
;         }
;         if (wr == 1 && fr == 15) {
; #pragma unroll
;             for (int bj = 0; bj < 2; ++bj)
; #pragma unroll
;                 for (int n = 0; n < 2; ++n) { *(f32x4*)(rawu + 2 * 256 + bj * 128 + clb + 4 * n) = acc[1][bj][2][n]; *(f32x4*)(rawu + 3 * 256 + bj * 128 + clb + 4 * n) = acc[1][bj][3][n]; }
;         }
;         asm volatile("s_waitcnt lgkmcnt(0)" ::: "memory"); __builtin_amdgcn_s_barrier(); __builtin_amdgcn_s_barrier(); asm volatile("" ::: "memory");
;         const int hc0 = 128 * u.pn + clb, row0 = u.pm * 256 + wr * 64 + 4 * fr;
; #pragma unroll
;         for (int n = 0; n < 2; ++n) {
;             const f32x4 w0v = cwv[n][0], w1v = cwv[n][1], w2v = cwv[n][2], bvv = cwv[n][3], w0g = cwv[n][4], w1g = cwv[n][5], w2g = cwv[n][6], bvg = cwv[n][7];
; #pragma unroll
;             for (int ai = 0; ai < 2; ++ai) {
;                 if (n == 0 && ai == 0) {
;                     asm volatile("" ::: "memory");
;                     const float* cv = cw + hc0 + 4; const float* cg = cv + FH; const float* bp = cb + hc0 + 4;
;                     cwv[1][0] = *(const f32x4*)(cv); cwv[1][1] = *(const f32x4*)(cv + F2); cwv[1][2] = *(const f32x4*)(cv + 2 * F2); cwv[1][3] = *(const f32x4*)(bp);
;                     cwv[1][4] = *(const f32x4*)(cg); cwv[1][5] = *(const f32x4*)(cg + F2); cwv[1][6] = *(const f32x4*)(cg + 2 * F2); cwv[1][7] = *(const f32x4*)(bp + FH);
;                     asm volatile("" ::: "memory"); }
;                 f32x4 h2v = (f32x4){0.f, 0.f, 0.f, 0.f}, h3v = h2v, h2g = h2v, h3g = h2v;
;                 const int pb = ai * 2 + wr - 1;
;                 if (pb >= 0 && fr == 0) { const LAS float* xp = xch + (pb * 2) * 256 + clb + 4 * n;
;                     h2v = *(const LAS f32x4*)(xp); h3v = *(const LAS f32x4*)(xp + 256); h2g = *(const LAS f32x4*)(xp + 128); h3g = *(const LAS f32x4*)(xp + 256 + 128); }
.LBB0_761:
	s_or_b64 exec, exec, s[44:45]
	s_mul_i32 s31, s40, 22
	s_add_i32 s44, s31, s41
	s_ashr_i32 s45, s44, 31
	s_lshl_b64 s[44:45], s[44:45], 12
	s_add_u32 s44, s64, s44
	s_addc_u32 s45, s65, s45
	v_lshlrev_b32_e32 v96, 2, v218
	v_or_b32_e32 v232, s42, v218
	v_ashrrev_i32_e32 v233, 31, v232
	v_lshlrev_b64 v[96:97], 2, v[232:233]
	v_lshl_add_u64 v[120:121], s[18:19], 0, v[96:97]
	v_add_co_u32_e32 v100, vcc, 0x5000, v120
	s_waitcnt lgkmcnt(0)
	s_barrier
	s_nop 0
	v_addc_co_u32_e32 v101, vcc, 0, v121, vcc
	v_add_co_u32_e32 v104, vcc, 0xb000, v120
	s_barrier
	s_nop 0
	v_addc_co_u32_e32 v105, vcc, 0, v121, vcc
	v_add_co_u32_e32 v112, vcc, s70, v120
	v_lshl_add_u64 v[124:125], s[22:23], 0, v[96:97]
	s_nop 0
	v_addc_co_u32_e32 v113, vcc, 0, v121, vcc
	v_add_co_u32_e32 v116, vcc, 0x8000, v120
	s_nop 0
	s_nop 0
	v_addc_co_u32_e32 v117, vcc, 0, v121, vcc
	v_add_co_u32_e32 v120, vcc, 0xd000, v120
	s_nop 0
	s_nop 0
	v_addc_co_u32_e32 v121, vcc, 0, v121, vcc
	v_add_co_u32_e32 v124, vcc, 0x2000, v124
	s_nop 0
	s_nop 0
	v_addc_co_u32_e32 v125, vcc, 0, v125, vcc
	v_mov_b32_e32 v192, 0
	v_mov_b64_e32 v[198:199], 0
	v_mov_b64_e32 v[200:201], 0
	v_mov_b64_e32 v[206:207], 0
	v_mov_b64_e32 v[208:209], 0
	v_mov_b64_e32 v[194:195], 0
	v_mov_b64_e32 v[196:197], 0
	v_mov_b64_e32 v[202:203], 0
	v_mov_b64_e32 v[204:205], 0
	s_and_saveexec_b64 s[42:43], s[26:27]
	s_cbranch_execz .LBB0_767
	ds_read_b128 v[202:205], v238
	ds_read_b128 v[206:209], v238 offset:512
	ds_read_b128 v[194:197], v238 offset:1024
	ds_read_b128 v[198:201], v238 offset:1536

; #define LAS __attribute__((address_space(3)))
; __device__ __forceinline__ float sigmoidf_(float x) { return __builtin_amdgcn_rcpf(1.0f + __expf(-x)); }
;     __device__ __forceinline__ void operator()(AccRef acc, const Unit& u, int wr, int wc, int fr, int fq) const {
;     ...
;                 f32x4 h2v = (f32x4){0.f, 0.f, 0.f, 0.f}, h3v = h2v, h2g = h2v, h3g = h2v;
;                 const int pb = ai * 2 + wr - 1;
;                 if (pb >= 0 && fr == 0) { const LAS float* xp = xch + (pb * 2) * 256 + clb + 4 * n;
;                     h2v = *(const LAS f32x4*)(xp); h3v = *(const LAS f32x4*)(xp + 256); h2g = *(const LAS f32x4*)(xp + 128); h3g = *(const LAS f32x4*)(xp + 256 + 128); }
;                 float o[4][4];
; #pragma unroll
;                 for (int j = 0; j < 4; ++j) {
;                     const float v0 = acc[ai][0][0][n][j], v1 = acc[ai][0][1][n][j], v2 = acc[ai][0][2][n][j], v3 = acc[ai][0][3][n][j];
;                     const float g0 = acc[ai][1][0][n][j], g1 = acc[ai][1][1][n][j], g2 = acc[ai][1][2][n][j], g3 = acc[ai][1][3][n][j];
;                     const float pv3 = dpp_upd<0x111>(h3v[j], v3), pv2 = dpp_upd<0x111>(h2v[j], v2), pg3 = dpp_upd<0x111>(h3g[j], g3), pg2 = dpp_upd<0x111>(h2g[j], g2);
;                     const float hv0 = bvv[j] + w2v[j] * v0 + w1v[j] * pv3 + w0v[j] * pv2, hv1 = bvv[j] + w2v[j] * v1 + w1v[j] * v0 + w0v[j] * pv3;
;                     const float hv2 = bvv[j] + w2v[j] * v2 + w1v[j] * v1 + w0v[j] * v0, hv3 = bvv[j] + w2v[j] * v3 + w1v[j] * v2 + w0v[j] * v1;
;                     const float hg0 = bvg[j] + w2g[j] * g0 + w1g[j] * pg3 + w0g[j] * pg2, hg1 = bvg[j] + w2g[j] * g1 + w1g[j] * g0 + w0g[j] * pg3;
;                     const float hg2 = bvg[j] + w2g[j] * g2 + w1g[j] * g1 + w0g[j] * g0, hg3 = bvg[j] + w2g[j] * g3 + w1g[j] * g2 + w0g[j] * g1;
;                     o[0][j] = hg0 * sigmoidf_(hg0) * hv0; o[1][j] = hg1 * sigmoidf_(hg1) * hv1; o[2][j] = hg2 * sigmoidf_(hg2) * hv2; o[3][j] = hg3 * sigmoidf_(hg3) * hv3; }
; #pragma unroll
;                 for (int m = 0; m < 4; ++m) { u32x2 w; w.x = cvt_pk_bf16(o[m][0], o[m][1]); w.y = cvt_pk_bf16(o[m][2], o[m][3]);
;                     *(u32x2*)(Aout + (size_t)(row0 + ai * 128 + m) * FH + hc0 + 4 * n) = w; } } }
.LBB0_765:
	s_or_b64 exec, exec, s[46:47]
	v_pk_fma_f32 v[248:249], v[152:153], v[184:185], v[188:189]
	v_mov_b32_dpp v206, v128 row_shr:1 row_mask:0xf bank_mask:0xf
	v_mov_b32_dpp v207, v129 row_shr:1 row_mask:0xf bank_mask:0xf
	v_pk_fma_f32 v[248:249], v[180:181], v[198:199], v[248:249]
	v_mov_b32_dpp v194, v148 row_shr:1 row_mask:0xf bank_mask:0xf
	v_pk_fma_f32 v[206:207], v[176:177], v[206:207], v[248:249]
	v_mov_b32_dpp v195, v149 row_shr:1 row_mask:0xf bank_mask:0xf
	v_exp_f32_e32 v248, v206
	v_exp_f32_e32 v249, v207
	v_pk_fma_f32 v[250:251], v[156:157], v[168:169], v[172:173]
	v_pk_add_f32 v[248:249], v[248:249], 1.0 op_sel_hi:[1,0]
	v_rcp_f32_e32 v248, v248
	v_rcp_f32_e32 v249, v249
	v_mov_b32_dpp v202, v136 row_shr:1 row_mask:0xf bank_mask:0xf
	v_mov_b32_dpp v203, v137 row_shr:1 row_mask:0xf bank_mask:0xf
	v_pk_fma_f32 v[250:251], v[164:165], v[194:195], v[250:251]
	v_pk_mul_f32 v[206:207], v[206:207], v[248:249]
	v_pk_fma_f32 v[202:203], v[160:161], v[202:203], v[250:251]
	v_mov_b32_dpp v200, v142 row_shr:1 row_mask:0xf bank_mask:0xf
	v_mov_b32_dpp v201, v143 row_shr:1 row_mask:0xf bank_mask:0xf
	v_pk_mul_f32 v[202:203], v[202:203], v[206:207]
	v_pk_fma_f32 v[206:207], v[154:155], v[186:187], v[190:191]
	v_mov_b32_dpp v208, v130 row_shr:1 row_mask:0xf bank_mask:0xf
	v_mov_b32_dpp v209, v131 row_shr:1 row_mask:0xf bank_mask:0xf
	v_pk_fma_f32 v[206:207], v[182:183], v[200:201], v[206:207]
	v_mov_b32_dpp v196, v150 row_shr:1 row_mask:0xf bank_mask:0xf
	v_pk_fma_f32 v[206:207], v[178:179], v[208:209], v[206:207]
	v_mov_b32_dpp v197, v151 row_shr:1 row_mask:0xf bank_mask:0xf
	v_exp_f32_e32 v193, v206
	v_exp_f32_e32 v209, v207
	v_cvt_pk_bf16_f32 v208, v202, v203
	v_add_f32_e32 v193, 1.0, v193
	v_rcp_f32_e32 v202, v193
	v_add_f32_e32 v193, 1.0, v209
	v_rcp_f32_e32 v203, v193
	v_pk_fma_f32 v[248:249], v[158:159], v[170:171], v[174:175]
	v_mov_b32_dpp v204, v138 row_shr:1 row_mask:0xf bank_mask:0xf
	v_mov_b32_dpp v205, v139 row_shr:1 row_mask:0xf bank_mask:0xf
	v_pk_fma_f32 v[248:249], v[166:167], v[196:197], v[248:249]
	v_pk_mul_f32 v[202:203], v[206:207], v[202:203]
	v_pk_fma_f32 v[204:205], v[162:163], v[204:205], v[248:249]
	v_lshl_add_u32 v246, s40, 8, v236
	v_pk_mul_f32 v[202:203], v[204:205], v[202:203]
	v_lshlrev_b64 v[204:205], 1, v[232:233]
	v_pk_fma_f32 v[232:233], v[132:133], v[184:185], v[188:189]
	v_mov_b64_e32 v[206:207], s[60:61]
	v_pk_fma_f32 v[232:233], v[152:153], v[180:181], v[232:233]
	v_cvt_pk_bf16_f32 v209, v202, v203
	v_pk_fma_f32 v[198:199], v[176:177], v[198:199], v[232:233]
	v_mad_i64_i32 v[202:203], s[40:41], v246, s76, v[206:207]
	v_exp_f32_e32 v193, v198
	v_exp_f32_e32 v232, v199
	v_lshl_add_u64 v[202:203], v[202:203], 0, v[204:205]
	v_add_f32_e32 v193, 1.0, v193
	v_mov_b32_e32 v247, v208
	v_mov_b32_e32 v248, v209
	v_rcp_f32_e32 v208, v193
	v_add_f32_e32 v193, 1.0, v232
	v_rcp_f32_e32 v209, v193
	v_pk_fma_f32 v[232:233], v[144:145], v[168:169], v[172:173]
	v_pk_fma_f32 v[140:141], v[140:141], v[184:185], v[188:189]
	v_pk_fma_f32 v[232:233], v[156:157], v[164:165], v[232:233]
	v_pk_mul_f32 v[198:199], v[198:199], v[208:209]
	v_pk_fma_f32 v[194:195], v[160:161], v[194:195], v[232:233]
	v_pk_fma_f32 v[208:209], v[146:147], v[170:171], v[174:175]
	v_pk_mul_f32 v[194:195], v[194:195], v[198:199]
	v_pk_fma_f32 v[198:199], v[134:135], v[186:187], v[190:191]
	v_pk_fma_f32 v[208:209], v[158:159], v[166:167], v[208:209]
	v_pk_fma_f32 v[198:199], v[154:155], v[182:183], v[198:199]
	v_pk_fma_f32 v[196:197], v[162:163], v[196:197], v[208:209]
	v_pk_fma_f32 v[198:199], v[178:179], v[200:201], v[198:199]
	v_cvt_pk_bf16_f32 v194, v194, v195
	v_exp_f32_e32 v200, v198
	v_exp_f32_e32 v201, v199
	v_pk_fma_f32 v[148:149], v[148:149], v[168:169], v[172:173]
	v_pk_add_f32 v[200:201], v[200:201], 1.0 op_sel_hi:[1,0]
	v_rcp_f32_e32 v200, v200
	v_rcp_f32_e32 v201, v201
	v_or_b32_e32 v193, 1, v246
	v_pk_mul_f32 v[198:199], v[198:199], v[200:201]
	s_nop 0
	v_pk_mul_f32 v[196:197], v[196:197], v[198:199]
	v_pk_fma_f32 v[198:199], v[128:129], v[184:185], v[188:189]
	v_cvt_pk_bf16_f32 v195, v196, v197
	v_pk_fma_f32 v[198:199], v[132:133], v[180:181], v[198:199]
	v_mad_i64_i32 v[196:197], s[40:41], v193, s76, v[206:207]
	v_pk_fma_f32 v[152:153], v[152:153], v[176:177], v[198:199]
	v_lshl_add_u64 v[196:197], v[196:197], 0, v[204:205]
	v_exp_f32_e32 v193, v152
	v_exp_f32_e32 v198, v153
	v_mov_b32_e32 v249, v194
	v_mov_b32_e32 v250, v195
	v_add_f32_e32 v193, 1.0, v193
	v_rcp_f32_e32 v194, v193
	v_add_f32_e32 v193, 1.0, v198
	v_rcp_f32_e32 v195, v193
	v_pk_fma_f32 v[198:199], v[136:137], v[168:169], v[172:173]
	v_pk_fma_f32 v[128:129], v[128:129], v[180:181], v[140:141]
	v_pk_fma_f32 v[198:199], v[144:145], v[164:165], v[198:199]
	v_pk_fma_f32 v[128:129], v[132:133], v[176:177], v[128:129]
	v_pk_fma_f32 v[156:157], v[156:157], v[160:161], v[198:199]
	v_pk_mul_f32 v[152:153], v[152:153], v[194:195]
	v_pk_mul_f32 v[152:153], v[156:157], v[152:153]
	v_pk_fma_f32 v[156:157], v[130:131], v[186:187], v[190:191]
	v_exp_f32_e32 v140, v128
	v_pk_fma_f32 v[132:133], v[142:143], v[186:187], v[190:191]
	v_pk_fma_f32 v[156:157], v[134:135], v[182:183], v[156:157]
	v_pk_fma_f32 v[130:131], v[130:131], v[182:183], v[132:133]
	v_pk_fma_f32 v[154:155], v[154:155], v[178:179], v[156:157]
	v_pk_fma_f32 v[130:131], v[134:135], v[178:179], v[130:131]
	v_exp_f32_e32 v157, v154
	v_exp_f32_e32 v141, v129
	v_exp_f32_e32 v132, v130
	v_exp_f32_e32 v133, v131
	v_exp_f32_e32 v193, v155
	v_pk_add_f32 v[140:141], v[140:141], 1.0 op_sel_hi:[1,0]
	v_pk_add_f32 v[132:133], v[132:133], 1.0 op_sel_hi:[1,0]
	v_cvt_pk_bf16_f32 v156, v152, v153
	v_add_f32_e32 v152, 1.0, v157
; #define LAS __attribute__((address_space(3)))
; __device__ __forceinline__ float sigmoidf_(float x) { return __builtin_amdgcn_rcpf(1.0f + __expf(-x)); }
;     __device__ __forceinline__ void operator()(AccRef acc, const Unit& u, int wr, int wc, int fr, int fq) const {
;     ...
;                 f32x4 h2v = (f32x4){0.f, 0.f, 0.f, 0.f}, h3v = h2v, h2g = h2v, h3g = h2v;
;                 const int pb = ai * 2 + wr - 1;
;                 if (pb >= 0 && fr == 0) { const LAS float* xp = xch + (pb * 2) * 256 + clb + 4 * n;
;                     h2v = *(const LAS f32x4*)(xp); h3v = *(const LAS f32x4*)(xp + 256); h2g = *(const LAS f32x4*)(xp + 128); h3g = *(const LAS f32x4*)(xp + 256 + 128); }
;                 float o[4][4];
; #pragma unroll
;                 for (int j = 0; j < 4; ++j) {
;                     const float v0 = acc[ai][0][0][n][j], v1 = acc[ai][0][1][n][j], v2 = acc[ai][0][2][n][j], v3 = acc[ai][0][3][n][j];
;                     const float g0 = acc[ai][1][0][n][j], g1 = acc[ai][1][1][n][j], g2 = acc[ai][1][2][n][j], g3 = acc[ai][1][3][n][j];
;                     const float pv3 = dpp_upd<0x111>(h3v[j], v3), pv2 = dpp_upd<0x111>(h2v[j], v2), pg3 = dpp_upd<0x111>(h3g[j], g3), pg2 = dpp_upd<0x111>(h2g[j], g2);
;                     const float hv0 = bvv[j] + w2v[j] * v0 + w1v[j] * pv3 + w0v[j] * pv2, hv1 = bvv[j] + w2v[j] * v1 + w1v[j] * v0 + w0v[j] * pv3;
;                     const float hv2 = bvv[j] + w2v[j] * v2 + w1v[j] * v1 + w0v[j] * v0, hv3 = bvv[j] + w2v[j] * v3 + w1v[j] * v2 + w0v[j] * v1;
;                     const float hg0 = bvg[j] + w2g[j] * g0 + w1g[j] * pg3 + w0g[j] * pg2, hg1 = bvg[j] + w2g[j] * g1 + w1g[j] * g0 + w0g[j] * pg3;
;                     const float hg2 = bvg[j] + w2g[j] * g2 + w1g[j] * g1 + w0g[j] * g0, hg3 = bvg[j] + w2g[j] * g3 + w1g[j] * g2 + w0g[j] * g1;
;                     o[0][j] = hg0 * sigmoidf_(hg0) * hv0; o[1][j] = hg1 * sigmoidf_(hg1) * hv1; o[2][j] = hg2 * sigmoidf_(hg2) * hv2; o[3][j] = hg3 * sigmoidf_(hg3) * hv3; }
; #pragma unroll
;                 for (int m = 0; m < 4; ++m) { u32x2 w; w.x = cvt_pk_bf16(o[m][0], o[m][1]); w.y = cvt_pk_bf16(o[m][2], o[m][3]);
;                     *(u32x2*)(Aout + (size_t)(row0 + ai * 128 + m) * FH + hc0 + 4 * n) = w; } } }
	v_add_f32_e32 v153, 1.0, v193
	v_rcp_f32_e32 v140, v140
	v_rcp_f32_e32 v141, v141
	v_rcp_f32_e32 v132, v132
	v_rcp_f32_e32 v133, v133
	v_rcp_f32_e32 v152, v152
	v_rcp_f32_e32 v153, v153
	v_pk_fma_f32 v[142:143], v[150:151], v[170:171], v[174:175]
	v_pk_fma_f32 v[194:195], v[138:139], v[170:171], v[174:175]
	v_pk_fma_f32 v[136:137], v[136:137], v[164:165], v[148:149]
	v_pk_fma_f32 v[134:135], v[138:139], v[166:167], v[142:143]
	v_pk_fma_f32 v[194:195], v[146:147], v[166:167], v[194:195]
	v_pk_fma_f32 v[136:137], v[144:145], v[160:161], v[136:137]
	v_pk_mul_f32 v[128:129], v[128:129], v[140:141]
	v_pk_fma_f32 v[134:135], v[146:147], v[162:163], v[134:135]
	v_pk_mul_f32 v[130:131], v[130:131], v[132:133]
	v_pk_fma_f32 v[158:159], v[158:159], v[162:163], v[194:195]
	v_pk_mul_f32 v[152:153], v[154:155], v[152:153]
	v_pk_mul_f32 v[128:129], v[136:137], v[128:129]
	v_pk_mul_f32 v[130:131], v[134:135], v[130:131]
	v_pk_mul_f32 v[152:153], v[158:159], v[152:153]
	v_cvt_pk_bf16_f32 v128, v128, v129
	v_cvt_pk_bf16_f32 v129, v130, v131
	v_or_b32_e32 v130, 3, v246
	v_cvt_pk_bf16_f32 v157, v152, v153
	v_or_b32_e32 v152, 2, v246
	v_mad_i64_i32 v[130:131], s[40:41], v130, s76, v[206:207]
	v_mad_i64_i32 v[152:153], s[40:41], v152, s76, v[206:207]
	v_lshl_add_u64 v[140:141], v[130:131], 0, v[204:205]
	v_lshl_add_u64 v[152:153], v[152:153], 0, v[204:205]
	v_mov_b32_e32 v251, v128
	v_mov_b32_e32 v253, v129
	v_mov_b32_e32 v193, 0
	v_mov_b64_e32 v[194:195], 0
	v_mov_b64_e32 v[136:137], 0
	v_mov_b64_e32 v[138:139], 0
	v_mov_b64_e32 v[128:129], 0
	v_mov_b64_e32 v[130:131], 0
	v_mov_b64_e32 v[132:133], 0
	v_mov_b64_e32 v[134:135], 0
	v_mov_b32_e32 v254, v156
	v_mov_b32_e32 v255, v157
	s_and_saveexec_b64 s[40:41], s[28:29]
	s_cbranch_execz .LBB0_769
	ds_read_b128 v[132:135], v237 offset:2048
	ds_read_b128 v[136:139], v237 offset:2560
	ds_read_b128 v[128:131], v237 offset:3072
	ds_read_b128 v[192:195], v237 offset:3584
.LBB0_769:
	s_or_b64 exec, exec, s[40:41]
	s_waitcnt lgkmcnt(0)
	v_mov_b32_dpp v192, v72 row_shr:1 row_mask:0xf bank_mask:0xf
	v_mov_b32_dpp v193, v73 row_shr:1 row_mask:0xf bank_mask:0xf
	v_pk_fma_f32 v[142:143], v[88:89], v[184:185], v[188:189]
	v_mov_b32_dpp v136, v64 row_shr:1 row_mask:0xf bank_mask:0xf
	v_mov_b32_dpp v137, v65 row_shr:1 row_mask:0xf bank_mask:0xf
	v_pk_fma_f32 v[142:143], v[180:181], v[192:193], v[142:143]
	v_mov_b32_dpp v128, v84 row_shr:1 row_mask:0xf bank_mask:0xf
	v_pk_fma_f32 v[136:137], v[176:177], v[136:137], v[142:143]
	v_mov_b32_dpp v129, v85 row_shr:1 row_mask:0xf bank_mask:0xf
	v_exp_f32_e32 v142, v136
	v_exp_f32_e32 v143, v137
	v_pk_fma_f32 v[144:145], v[92:93], v[168:169], v[172:173]
	v_mov_b32_dpp v132, v76 row_shr:1 row_mask:0xf bank_mask:0xf
	v_pk_add_f32 v[142:143], v[142:143], 1.0 op_sel_hi:[1,0]
	v_rcp_f32_e32 v142, v142
	v_rcp_f32_e32 v143, v143
	v_mov_b32_dpp v133, v77 row_shr:1 row_mask:0xf bank_mask:0xf
	v_pk_fma_f32 v[144:145], v[164:165], v[128:129], v[144:145]
	v_mov_b32_dpp v194, v74 row_shr:1 row_mask:0xf bank_mask:0xf
	v_pk_fma_f32 v[132:133], v[160:161], v[132:133], v[144:145]
	v_pk_mul_f32 v[136:137], v[136:137], v[142:143]
	v_mov_b32_dpp v195, v75 row_shr:1 row_mask:0xf bank_mask:0xf
	v_pk_mul_f32 v[132:133], v[132:133], v[136:137]
	v_pk_fma_f32 v[136:137], v[90:91], v[186:187], v[190:191]
	v_mov_b32_dpp v138, v66 row_shr:1 row_mask:0xf bank_mask:0xf
	v_mov_b32_dpp v139, v67 row_shr:1 row_mask:0xf bank_mask:0xf
	v_pk_fma_f32 v[136:137], v[182:183], v[194:195], v[136:137]
	v_mov_b32_dpp v130, v86 row_shr:1 row_mask:0xf bank_mask:0xf
	v_pk_fma_f32 v[136:137], v[178:179], v[138:139], v[136:137]
	v_mov_b32_dpp v131, v87 row_shr:1 row_mask:0xf bank_mask:0xf
	v_exp_f32_e32 v139, v136
	v_exp_f32_e32 v142, v137
	v_cvt_pk_bf16_f32 v138, v132, v133
	v_add_f32_e32 v132, 1.0, v139
	v_rcp_f32_e32 v132, v132
	v_add_f32_e32 v133, 1.0, v142
	v_rcp_f32_e32 v133, v133
	v_pk_fma_f32 v[142:143], v[94:95], v[170:171], v[174:175]
	v_mov_b32_dpp v134, v78 row_shr:1 row_mask:0xf bank_mask:0xf
	v_mov_b32_dpp v135, v79 row_shr:1 row_mask:0xf bank_mask:0xf
	v_pk_mul_f32 v[132:133], v[136:137], v[132:133]
	v_pk_fma_f32 v[136:137], v[68:69], v[184:185], v[188:189]
	v_pk_fma_f32 v[142:143], v[166:167], v[130:131], v[142:143]
	v_pk_fma_f32 v[136:137], v[88:89], v[180:181], v[136:137]
	v_pk_fma_f32 v[134:135], v[162:163], v[134:135], v[142:143]
	v_pk_fma_f32 v[136:137], v[176:177], v[192:193], v[136:137]
	v_add_u32_e32 v146, 0x80, v246
	v_exp_f32_e32 v142, v136
	v_exp_f32_e32 v143, v137
	v_pk_mul_f32 v[132:133], v[134:135], v[132:133]
	v_mov_b64_e32 v[134:135], s[60:61]
	v_cvt_pk_bf16_f32 v139, v132, v133
	v_mad_i64_i32 v[132:133], s[40:41], v146, s76, v[134:135]
	v_lshl_add_u64 v[132:133], v[132:133], 0, v[204:205]
	v_mov_b32_e32 v144, v138
	v_mov_b32_e32 v145, v139
	v_add_f32_e32 v138, 1.0, v142
	v_add_f32_e32 v139, 1.0, v143
	v_rcp_f32_e32 v138, v138
	v_rcp_f32_e32 v139, v139
	v_pk_fma_f32 v[142:143], v[80:81], v[168:169], v[172:173]
	v_pk_fma_f32 v[72:73], v[72:73], v[184:185], v[188:189]
	v_pk_fma_f32 v[142:143], v[92:93], v[164:165], v[142:143]
	v_pk_mul_f32 v[136:137], v[136:137], v[138:139]
	v_pk_fma_f32 v[128:129], v[160:161], v[128:129], v[142:143]
	v_pk_fma_f32 v[84:85], v[84:85], v[168:169], v[172:173]
	v_pk_mul_f32 v[128:129], v[128:129], v[136:137]
	v_pk_fma_f32 v[136:137], v[70:71], v[186:187], v[190:191]
	s_nop 0
	v_pk_fma_f32 v[136:137], v[90:91], v[182:183], v[136:137]
	s_nop 0
	v_pk_fma_f32 v[136:137], v[178:179], v[194:195], v[136:137]
	s_nop 0
	v_exp_f32_e32 v139, v136
	v_exp_f32_e32 v142, v137
	v_cvt_pk_bf16_f32 v138, v128, v129
	v_add_f32_e32 v128, 1.0, v139
	v_rcp_f32_e32 v128, v128
	v_add_f32_e32 v129, 1.0, v142
; #define LAS __attribute__((address_space(3)))
; __device__ __forceinline__ float sigmoidf_(float x) { return __builtin_amdgcn_rcpf(1.0f + __expf(-x)); }
;     __device__ __forceinline__ void operator()(AccRef acc, const Unit& u, int wr, int wc, int fr, int fq) const {
;     ...
;                 f32x4 h2v = (f32x4){0.f, 0.f, 0.f, 0.f}, h3v = h2v, h2g = h2v, h3g = h2v;
;                 const int pb = ai * 2 + wr - 1;
;                 if (pb >= 0 && fr == 0) { const LAS float* xp = xch + (pb * 2) * 256 + clb + 4 * n;
;                     h2v = *(const LAS f32x4*)(xp); h3v = *(const LAS f32x4*)(xp + 256); h2g = *(const LAS f32x4*)(xp + 128); h3g = *(const LAS f32x4*)(xp + 256 + 128); }
;                 float o[4][4];
; #pragma unroll
;                 for (int j = 0; j < 4; ++j) {
;                     const float v0 = acc[ai][0][0][n][j], v1 = acc[ai][0][1][n][j], v2 = acc[ai][0][2][n][j], v3 = acc[ai][0][3][n][j];
;                     const float g0 = acc[ai][1][0][n][j], g1 = acc[ai][1][1][n][j], g2 = acc[ai][1][2][n][j], g3 = acc[ai][1][3][n][j];
;                     const float pv3 = dpp_upd<0x111>(h3v[j], v3), pv2 = dpp_upd<0x111>(h2v[j], v2), pg3 = dpp_upd<0x111>(h3g[j], g3), pg2 = dpp_upd<0x111>(h2g[j], g2);
;                     const float hv0 = bvv[j] + w2v[j] * v0 + w1v[j] * pv3 + w0v[j] * pv2, hv1 = bvv[j] + w2v[j] * v1 + w1v[j] * v0 + w0v[j] * pv3;
;                     const float hv2 = bvv[j] + w2v[j] * v2 + w1v[j] * v1 + w0v[j] * v0, hv3 = bvv[j] + w2v[j] * v3 + w1v[j] * v2 + w0v[j] * v1;
;                     const float hg0 = bvg[j] + w2g[j] * g0 + w1g[j] * pg3 + w0g[j] * pg2, hg1 = bvg[j] + w2g[j] * g1 + w1g[j] * g0 + w0g[j] * pg3;
;                     const float hg2 = bvg[j] + w2g[j] * g2 + w1g[j] * g1 + w0g[j] * g0, hg3 = bvg[j] + w2g[j] * g3 + w1g[j] * g2 + w0g[j] * g1;
;                     o[0][j] = hg0 * sigmoidf_(hg0) * hv0; o[1][j] = hg1 * sigmoidf_(hg1) * hv1; o[2][j] = hg2 * sigmoidf_(hg2) * hv2; o[3][j] = hg3 * sigmoidf_(hg3) * hv3; }
; #pragma unroll
;                 for (int m = 0; m < 4; ++m) { u32x2 w; w.x = cvt_pk_bf16(o[m][0], o[m][1]); w.y = cvt_pk_bf16(o[m][2], o[m][3]);
;                     *(u32x2*)(Aout + (size_t)(row0 + ai * 128 + m) * FH + hc0 + 4 * n) = w; } } }
	v_rcp_f32_e32 v129, v129
	v_pk_fma_f32 v[142:143], v[82:83], v[170:171], v[174:175]
	v_pk_mul_f32 v[128:129], v[136:137], v[128:129]
	v_pk_fma_f32 v[142:143], v[94:95], v[166:167], v[142:143]
	v_pk_fma_f32 v[136:137], v[76:77], v[168:169], v[172:173]
	v_pk_fma_f32 v[130:131], v[162:163], v[130:131], v[142:143]
	v_pk_fma_f32 v[136:137], v[80:81], v[164:165], v[136:137]
	v_pk_mul_f32 v[128:129], v[130:131], v[128:129]
	v_pk_fma_f32 v[130:131], v[64:65], v[184:185], v[188:189]
	v_pk_fma_f32 v[64:65], v[64:65], v[180:181], v[72:73]
	v_pk_fma_f32 v[130:131], v[68:69], v[180:181], v[130:131]
	v_pk_fma_f32 v[64:65], v[68:69], v[176:177], v[64:65]
	v_pk_fma_f32 v[88:89], v[88:89], v[176:177], v[130:131]
	v_pk_fma_f32 v[92:93], v[92:93], v[160:161], v[136:137]
	v_exp_f32_e32 v130, v88
	v_exp_f32_e32 v131, v89
	v_exp_f32_e32 v72, v64
	v_pk_add_f32 v[130:131], v[130:131], 1.0 op_sel_hi:[1,0]
	v_rcp_f32_e32 v130, v130
	v_rcp_f32_e32 v131, v131
	v_pk_fma_f32 v[68:69], v[74:75], v[186:187], v[190:191]
	v_exp_f32_e32 v73, v65
	v_pk_mul_f32 v[88:89], v[88:89], v[130:131]
	v_pk_mul_f32 v[88:89], v[92:93], v[88:89]
	v_pk_fma_f32 v[92:93], v[66:67], v[186:187], v[190:191]
	v_pk_fma_f32 v[66:67], v[66:67], v[182:183], v[68:69]
	v_pk_fma_f32 v[92:93], v[70:71], v[182:183], v[92:93]
	v_pk_fma_f32 v[66:67], v[70:71], v[178:179], v[66:67]
	v_pk_fma_f32 v[90:91], v[90:91], v[178:179], v[92:93]
	v_exp_f32_e32 v93, v90
	v_exp_f32_e32 v68, v66
	v_exp_f32_e32 v69, v67
	v_exp_f32_e32 v130, v91
	v_pk_add_f32 v[72:73], v[72:73], 1.0 op_sel_hi:[1,0]
	v_pk_add_f32 v[68:69], v[68:69], 1.0 op_sel_hi:[1,0]
	v_cvt_pk_bf16_f32 v92, v88, v89
	v_add_f32_e32 v88, 1.0, v93
	v_add_f32_e32 v89, 1.0, v130
	v_rcp_f32_e32 v72, v72
	v_rcp_f32_e32 v73, v73
	v_rcp_f32_e32 v68, v68
	v_rcp_f32_e32 v69, v69
	v_rcp_f32_e32 v88, v88
	v_rcp_f32_e32 v89, v89
	v_pk_fma_f32 v[74:75], v[86:87], v[170:171], v[174:175]
	v_pk_fma_f32 v[130:131], v[78:79], v[170:171], v[174:175]
	v_pk_fma_f32 v[76:77], v[76:77], v[164:165], v[84:85]
	v_pk_fma_f32 v[70:71], v[78:79], v[166:167], v[74:75]
	v_pk_fma_f32 v[130:131], v[82:83], v[166:167], v[130:131]
	v_pk_fma_f32 v[76:77], v[80:81], v[160:161], v[76:77]
	v_pk_mul_f32 v[64:65], v[64:65], v[72:73]
	v_pk_fma_f32 v[70:71], v[82:83], v[162:163], v[70:71]
	v_pk_mul_f32 v[66:67], v[66:67], v[68:69]
	v_pk_fma_f32 v[94:95], v[94:95], v[162:163], v[130:131]
	v_pk_mul_f32 v[88:89], v[90:91], v[88:89]
	v_pk_mul_f32 v[64:65], v[76:77], v[64:65]
	v_pk_mul_f32 v[66:67], v[70:71], v[66:67]
	v_pk_mul_f32 v[88:89], v[94:95], v[88:89]
	v_cvt_pk_bf16_f32 v64, v64, v65
	v_cvt_pk_bf16_f32 v65, v66, v67
	v_add_u32_e32 v66, 0x83, v246
	v_cvt_pk_bf16_f32 v139, v128, v129
	v_add_u32_e32 v128, 0x81, v246
	v_cvt_pk_bf16_f32 v93, v88, v89
	v_add_u32_e32 v88, 0x82, v246
	v_mad_i64_i32 v[66:67], s[40:41], v66, s76, v[134:135]
	v_mad_i64_i32 v[128:129], s[40:41], v128, s76, v[134:135]
	v_mad_i64_i32 v[88:89], s[40:41], v88, s76, v[134:135]
	v_lshl_add_u64 v[82:83], v[66:67], 0, v[204:205]
	v_lshl_add_u64 v[128:129], v[128:129], 0, v[204:205]
	v_lshl_add_u64 v[88:89], v[88:89], 0, v[204:205]
	v_mov_b32_e32 v148, v64
	v_mov_b32_e32 v149, v65
	v_mov_b32_e32 v64, 0
	v_mov_b64_e32 v[70:71], 0
	v_mov_b64_e32 v[72:73], 0
	v_mov_b64_e32 v[78:79], 0
	v_mov_b64_e32 v[80:81], 0
	v_mov_b64_e32 v[66:67], 0
	v_mov_b64_e32 v[68:69], 0
	v_mov_b64_e32 v[74:75], 0
	v_mov_b64_e32 v[76:77], 0
	v_mov_b32_e32 v154, v138
	v_mov_b32_e32 v155, v139
	v_mov_b32_e32 v198, v92
	v_mov_b32_e32 v199, v93
	s_and_saveexec_b64 s[40:41], s[26:27]
	s_cbranch_execz .LBB0_771
	ds_read_b128 v[74:77], v242
	ds_read_b128 v[66:69], v241
	ds_read_b128 v[78:81], v240
	ds_read_b128 v[70:73], v239
; __device__ __forceinline__ float sigmoidf_(float x) { return __builtin_amdgcn_rcpf(1.0f + __expf(-x)); }
;     __device__ __forceinline__ void operator()(AccRef acc, const Unit& u, int wr, int wc, int fr, int fq) const {
;     ...
;                 float o[4][4];
; #pragma unroll
;                 for (int j = 0; j < 4; ++j) {
;                     const float v0 = acc[ai][0][0][n][j], v1 = acc[ai][0][1][n][j], v2 = acc[ai][0][2][n][j], v3 = acc[ai][0][3][n][j];
;                     const float g0 = acc[ai][1][0][n][j], g1 = acc[ai][1][1][n][j], g2 = acc[ai][1][2][n][j], g3 = acc[ai][1][3][n][j];
;                     const float pv3 = dpp_upd<0x111>(h3v[j], v3), pv2 = dpp_upd<0x111>(h2v[j], v2), pg3 = dpp_upd<0x111>(h3g[j], g3), pg2 = dpp_upd<0x111>(h2g[j], g2);
;                     const float hv0 = bvv[j] + w2v[j] * v0 + w1v[j] * pv3 + w0v[j] * pv2, hv1 = bvv[j] + w2v[j] * v1 + w1v[j] * v0 + w0v[j] * pv3;
;                     const float hv2 = bvv[j] + w2v[j] * v2 + w1v[j] * v1 + w0v[j] * v0, hv3 = bvv[j] + w2v[j] * v3 + w1v[j] * v2 + w0v[j] * v1;
;                     const float hg0 = bvg[j] + w2g[j] * g0 + w1g[j] * pg3 + w0g[j] * pg2, hg1 = bvg[j] + w2g[j] * g1 + w1g[j] * g0 + w0g[j] * pg3;
;                     const float hg2 = bvg[j] + w2g[j] * g2 + w1g[j] * g1 + w0g[j] * g0, hg3 = bvg[j] + w2g[j] * g3 + w1g[j] * g2 + w0g[j] * g1;
;                     o[0][j] = hg0 * sigmoidf_(hg0) * hv0; o[1][j] = hg1 * sigmoidf_(hg1) * hv1; o[2][j] = hg2 * sigmoidf_(hg2) * hv2; o[3][j] = hg3 * sigmoidf_(hg3) * hv3; }
; #pragma unroll
;                 for (int m = 0; m < 4; ++m) { u32x2 w; w.x = cvt_pk_bf16(o[m][0], o[m][1]); w.y = cvt_pk_bf16(o[m][2], o[m][3]);
;                     *(u32x2*)(Aout + (size_t)(row0 + ai * 128 + m) * FH + hc0 + 4 * n) = w; } } }
.LBB0_771:
	s_or_b64 exec, exec, s[40:41]
	s_waitcnt lgkmcnt(0)
	v_mov_b32_dpp v70, v44 row_shr:1 row_mask:0xf bank_mask:0xf
	v_mov_b32_dpp v71, v45 row_shr:1 row_mask:0xf bank_mask:0xf
	s_waitcnt vmcnt(0)
	v_pk_fma_f32 v[84:85], v[56:57], v[120:121], v[124:125]
	v_mov_b32_dpp v78, v32 row_shr:1 row_mask:0xf bank_mask:0xf
	v_mov_b32_dpp v79, v33 row_shr:1 row_mask:0xf bank_mask:0xf
	v_pk_fma_f32 v[84:85], v[116:117], v[70:71], v[84:85]
	v_mov_b32_dpp v66, v52 row_shr:1 row_mask:0xf bank_mask:0xf
	v_pk_fma_f32 v[78:79], v[112:113], v[78:79], v[84:85]
	v_mov_b32_dpp v67, v53 row_shr:1 row_mask:0xf bank_mask:0xf
	v_exp_f32_e32 v84, v78
	v_exp_f32_e32 v85, v79
	v_pk_fma_f32 v[86:87], v[60:61], v[104:105], v[108:109]
	v_pk_add_f32 v[84:85], v[84:85], 1.0 op_sel_hi:[1,0]
	v_rcp_f32_e32 v84, v84
	v_rcp_f32_e32 v85, v85
	v_mov_b32_dpp v74, v40 row_shr:1 row_mask:0xf bank_mask:0xf
	v_mov_b32_dpp v75, v41 row_shr:1 row_mask:0xf bank_mask:0xf
	v_pk_fma_f32 v[86:87], v[100:101], v[66:67], v[86:87]
	v_pk_mul_f32 v[78:79], v[78:79], v[84:85]
	v_pk_fma_f32 v[74:75], v[96:97], v[74:75], v[86:87]
	v_mov_b32_dpp v72, v46 row_shr:1 row_mask:0xf bank_mask:0xf
	v_mov_b32_dpp v73, v47 row_shr:1 row_mask:0xf bank_mask:0xf
	v_pk_mul_f32 v[74:75], v[74:75], v[78:79]
	v_pk_fma_f32 v[78:79], v[58:59], v[122:123], v[126:127]
	v_mov_b32_dpp v80, v34 row_shr:1 row_mask:0xf bank_mask:0xf
	v_mov_b32_dpp v81, v35 row_shr:1 row_mask:0xf bank_mask:0xf
	v_pk_fma_f32 v[78:79], v[118:119], v[72:73], v[78:79]
	v_mov_b32_dpp v68, v54 row_shr:1 row_mask:0xf bank_mask:0xf
	v_pk_fma_f32 v[78:79], v[114:115], v[80:81], v[78:79]
	v_mov_b32_dpp v69, v55 row_shr:1 row_mask:0xf bank_mask:0xf
	v_exp_f32_e32 v80, v78
	v_exp_f32_e32 v81, v79
	v_pk_fma_f32 v[84:85], v[62:63], v[106:107], v[110:111]
	v_pk_add_f32 v[80:81], v[80:81], 1.0 op_sel_hi:[1,0]
	v_rcp_f32_e32 v80, v80
	v_rcp_f32_e32 v81, v81
	v_mov_b32_dpp v76, v42 row_shr:1 row_mask:0xf bank_mask:0xf
	v_mov_b32_dpp v77, v43 row_shr:1 row_mask:0xf bank_mask:0xf
	v_pk_fma_f32 v[84:85], v[102:103], v[68:69], v[84:85]
	v_pk_mul_f32 v[78:79], v[78:79], v[80:81]
	v_pk_fma_f32 v[76:77], v[98:99], v[76:77], v[84:85]
	v_cvt_pk_bf16_f32 v74, v74, v75
	v_pk_mul_f32 v[76:77], v[76:77], v[78:79]
	v_pk_fma_f32 v[44:45], v[44:45], v[120:121], v[124:125]
	v_cvt_pk_bf16_f32 v75, v76, v77
	v_pk_fma_f32 v[76:77], v[36:37], v[120:121], v[124:125]
	v_mov_b32_e32 v90, v247
	v_mov_b32_e32 v91, v248
	v_mov_b32_e32 v92, v74
	v_mov_b32_e32 v93, v75
	global_store_dwordx4 v[202:203], v[90:93], off
	v_pk_fma_f32 v[76:77], v[56:57], v[116:117], v[76:77]
	v_pk_fma_f32 v[52:53], v[52:53], v[104:105], v[108:109]
	v_pk_fma_f32 v[70:71], v[112:113], v[70:71], v[76:77]
	s_nop 0
	v_exp_f32_e32 v74, v70
	v_exp_f32_e32 v75, v71
	s_nop 0
	v_pk_add_f32 v[74:75], v[74:75], 1.0 op_sel_hi:[1,0]
	v_rcp_f32_e32 v74, v74
	v_rcp_f32_e32 v75, v75
	v_pk_fma_f32 v[76:77], v[48:49], v[104:105], v[108:109]
	v_pk_mul_f32 v[70:71], v[70:71], v[74:75]
	v_pk_fma_f32 v[76:77], v[60:61], v[100:101], v[76:77]
	v_pk_fma_f32 v[74:75], v[50:51], v[106:107], v[110:111]
	v_pk_fma_f32 v[66:67], v[96:97], v[66:67], v[76:77]
	v_pk_fma_f32 v[74:75], v[62:63], v[102:103], v[74:75]
	v_pk_mul_f32 v[66:67], v[66:67], v[70:71]
	v_pk_fma_f32 v[70:71], v[38:39], v[122:123], v[126:127]
	v_pk_fma_f32 v[68:69], v[98:99], v[68:69], v[74:75]
	v_pk_fma_f32 v[70:71], v[58:59], v[118:119], v[70:71]
	v_cvt_pk_bf16_f32 v66, v66, v67
	v_pk_fma_f32 v[70:71], v[114:115], v[72:73], v[70:71]
	s_nop 0
	v_exp_f32_e32 v72, v70
	v_exp_f32_e32 v73, v71
	s_nop 0
	v_pk_add_f32 v[72:73], v[72:73], 1.0 op_sel_hi:[1,0]
	v_rcp_f32_e32 v72, v72
	v_rcp_f32_e32 v73, v73
	s_nop 0
	v_pk_mul_f32 v[70:71], v[70:71], v[72:73]
	s_nop 0
	v_pk_mul_f32 v[68:69], v[68:69], v[70:71]
	s_nop 0
	v_cvt_pk_bf16_f32 v67, v68, v69
	v_pk_fma_f32 v[68:69], v[32:33], v[120:121], v[124:125]
	v_mov_b32_e32 v134, v249
	v_mov_b32_e32 v135, v250
	v_mov_b32_e32 v136, v66
	v_mov_b32_e32 v137, v67
	global_store_dwordx4 v[196:197], v[134:137], off
	v_pk_fma_f32 v[68:69], v[36:37], v[116:117], v[68:69]
	v_pk_fma_f32 v[32:33], v[32:33], v[116:117], v[44:45]
	v_pk_fma_f32 v[56:57], v[56:57], v[112:113], v[68:69]
	v_pk_fma_f32 v[32:33], v[36:37], v[112:113], v[32:33]
	v_exp_f32_e32 v66, v56
	v_exp_f32_e32 v67, v57
	s_nop 0
	v_pk_add_f32 v[66:67], v[66:67], 1.0 op_sel_hi:[1,0]
	v_rcp_f32_e32 v66, v66
	v_rcp_f32_e32 v67, v67
	v_pk_fma_f32 v[68:69], v[40:41], v[104:105], v[108:109]
	v_exp_f32_e32 v44, v32
	v_pk_fma_f32 v[68:69], v[48:49], v[100:101], v[68:69]
	v_pk_mul_f32 v[56:57], v[56:57], v[66:67]
	v_pk_fma_f32 v[60:61], v[60:61], v[96:97], v[68:69]
	v_pk_fma_f32 v[36:37], v[46:47], v[122:123], v[126:127]
	v_pk_mul_f32 v[56:57], v[60:61], v[56:57]
	v_pk_fma_f32 v[60:61], v[34:35], v[122:123], v[126:127]
	v_pk_fma_f32 v[34:35], v[34:35], v[118:119], v[36:37]
	v_pk_fma_f32 v[60:61], v[38:39], v[118:119], v[60:61]
	v_pk_fma_f32 v[34:35], v[38:39], v[114:115], v[34:35]
	v_pk_fma_f32 v[58:59], v[58:59], v[114:115], v[60:61]
	v_exp_f32_e32 v60, v58
	v_exp_f32_e32 v45, v33
	v_exp_f32_e32 v36, v34
	v_exp_f32_e32 v37, v35
	v_exp_f32_e32 v61, v59
	v_cvt_pk_bf16_f32 v56, v56, v57
	v_pk_add_f32 v[44:45], v[44:45], 1.0 op_sel_hi:[1,0]
	v_pk_add_f32 v[36:37], v[36:37], 1.0 op_sel_hi:[1,0]
	v_pk_add_f32 v[60:61], v[60:61], 1.0 op_sel_hi:[1,0]
	v_rcp_f32_e32 v44, v44
	v_rcp_f32_e32 v45, v45
	v_rcp_f32_e32 v36, v36
	v_rcp_f32_e32 v37, v37
	v_rcp_f32_e32 v60, v60
	v_rcp_f32_e32 v61, v61
	v_pk_fma_f32 v[46:47], v[54:55], v[106:107], v[110:111]
	v_pk_fma_f32 v[66:67], v[42:43], v[106:107], v[110:111]
	v_pk_fma_f32 v[40:41], v[40:41], v[100:101], v[52:53]
	v_pk_fma_f32 v[38:39], v[42:43], v[102:103], v[46:47]
	v_pk_fma_f32 v[66:67], v[50:51], v[102:103], v[66:67]
	v_pk_fma_f32 v[40:41], v[48:49], v[96:97], v[40:41]
	v_pk_mul_f32 v[32:33], v[32:33], v[44:45]
	v_pk_fma_f32 v[38:39], v[50:51], v[98:99], v[38:39]
	v_pk_mul_f32 v[34:35], v[34:35], v[36:37]
	v_pk_fma_f32 v[62:63], v[62:63], v[98:99], v[66:67]
	v_pk_mul_f32 v[58:59], v[58:59], v[60:61]
	v_pk_mul_f32 v[32:33], v[40:41], v[32:33]
	v_pk_mul_f32 v[34:35], v[38:39], v[34:35]
	v_pk_mul_f32 v[58:59], v[62:63], v[58:59]
	v_cvt_pk_bf16_f32 v32, v32, v33
	v_cvt_pk_bf16_f32 v33, v34, v35
	v_cvt_pk_bf16_f32 v57, v58, v59
	v_mov_b32_e32 v158, v251
	v_mov_b32_e32 v159, v253
	v_mov_b32_e32 v160, v32
	v_mov_b32_e32 v161, v33
	global_store_dwordx4 v[140:141], v[158:161], off
	v_mov_b32_e32 v65, 0
	v_mov_b64_e32 v[66:67], 0
	v_mov_b64_e32 v[40:41], 0
	v_mov_b64_e32 v[42:43], 0
	v_mov_b64_e32 v[32:33], 0
	v_mov_b64_e32 v[34:35], 0
	v_mov_b64_e32 v[36:37], 0
	v_mov_b64_e32 v[38:39], 0
	v_mov_b32_e32 v162, v254
	v_mov_b32_e32 v163, v255
	v_mov_b32_e32 v164, v56
	v_mov_b32_e32 v165, v57
	global_store_dwordx4 v[152:153], v[162:165], off
	s_and_saveexec_b64 s[40:41], s[28:29]
	s_cbranch_execz .LBB0_754
	ds_read_b128 v[36:39], v237 offset:2064
	ds_read_b128 v[40:43], v237 offset:2576
	ds_read_b128 v[32:35], v237 offset:3088
	ds_read_b128 v[64:67], v237 offset:3600
	s_branch .LBB0_754

; #define LAS __attribute__((address_space(3)))
;     __device__ __forceinline__ void operator()(AccRef acc, const Unit& u, int wr, int wc, int fr, int fq) const {
;     ...
;         asm volatile("s_waitcnt lgkmcnt(0)" ::: "memory"); __builtin_amdgcn_s_barrier(); __builtin_amdgcn_s_barrier(); asm volatile("" ::: "memory");
; #pragma unroll
;         for (int bj = 0; bj < 2; ++bj)
; #pragma unroll
;             for (int n = 0; n < 2; ++n) {
;                 const int c0 = col0 + bj * 128 + 4 * n;
;                 const f32x4 w0 = *(const f32x4*)(cw + c0), w1 = *(const f32x4*)(cw + D + c0), w2 = *(const f32x4*)(cw + 2 * D + c0), w3 = *(const f32x4*)(cw + 3 * D + c0), bb = *(const f32x4*)(cb + c0);
; #pragma unroll
;                 for (int ai = 0; ai < 2; ++ai) {
;                     f32x4 h1 = (f32x4){0.f, 0.f, 0.f, 0.f}, h2 = h1, h3 = h1;
;                     const int pb = ai * 2 + wr - 1;
;                     if (pb >= 0 && fr == 0) { const LAS float* xp = xch + (pb * 3) * 256 + bj * 128 + clb + 4 * n; h1 = *(const LAS f32x4*)(xp); h2 = *(const LAS f32x4*)(xp + 256); h3 = *(const LAS f32x4*)(xp + 512); }
;                     float o[4][4];
; #pragma unroll
;                     for (int j = 0; j < 4; ++j) {
;                         const float v0 = acc[ai][bj][0][n][j], v1 = acc[ai][bj][1][n][j], v2 = acc[ai][bj][2][n][j], v3 = acc[ai][bj][3][n][j];
;                         const float p3 = dpp_upd<0x111>(h3[j], v3), p2 = dpp_upd<0x111>(h2[j], v2), p1 = dpp_upd<0x111>(h1[j], v1);
;                         o[0][j] = bb[j] + w3[j] * v0 + w2[j] * p3 + w1[j] * p2 + w0[j] * p1;
;                         o[1][j] = bb[j] + w3[j] * v1 + w2[j] * v0 + w1[j] * p3 + w0[j] * p2;
;                         o[2][j] = bb[j] + w3[j] * v2 + w2[j] * v1 + w1[j] * v0 + w0[j] * p3;
;                         o[3][j] = bb[j] + w3[j] * v3 + w2[j] * v2 + w1[j] * v1 + w0[j] * v0; }
; #pragma unroll
;                     for (int m = 0; m < 4; ++m) *(u32x2*)(REC + (size_t)(row0 + ai * 128 + m) * D + c0) = (u32x2){cvt_pk_bf16(o[m][0], o[m][1]), cvt_pk_bf16(o[m][2], o[m][3])};
.LBB0_998:
	s_or_b64 exec, exec, s[78:79]
	s_waitcnt lgkmcnt(0)
	s_barrier
	s_barrier
	v_lshlrev_b32_e32 v192, 2, v220
	global_load_dwordx4 v[128:131], v192, s[38:39]
	global_load_dwordx4 v[136:139], v192, s[40:41]
	global_load_dwordx4 v[140:143], v192, s[42:43]
	global_load_dwordx4 v[132:135], v192, s[20:21]
	global_load_dwordx4 v[144:147], v192, s[22:23]
	v_mov_b32_e32 v148, 0
	v_mov_b64_e32 v[158:159], 0
	v_mov_b64_e32 v[160:161], 0
	v_mov_b64_e32 v[154:155], 0
	v_mov_b64_e32 v[156:157], 0
	v_mov_b64_e32 v[150:151], 0
	v_mov_b64_e32 v[152:153], 0
	s_and_saveexec_b64 s[76:77], s[34:35]
	s_cbranch_execz .LBB0_1000
	ds_read_b128 v[158:161], v206
	ds_read_b128 v[154:157], v206 offset:1024
	ds_read_b128 v[150:153], v206 offset:2048
.LBB0_1000:
	s_or_b64 exec, exec, s[76:77]
	s_waitcnt lgkmcnt(0)
	v_mov_b32_dpp v150, v76 row_shr:1 row_mask:0xf bank_mask:0xf
	v_mov_b32_dpp v151, v77 row_shr:1 row_mask:0xf bank_mask:0xf
	s_waitcnt vmcnt(0)
	v_pk_fma_f32 v[184:185], v[124:125], v[140:141], v[144:145]
	v_mov_b32_dpp v154, v92 row_shr:1 row_mask:0xf bank_mask:0xf
	v_mov_b32_dpp v155, v93 row_shr:1 row_mask:0xf bank_mask:0xf
	v_pk_fma_f32 v[184:185], v[136:137], v[150:151], v[184:185]
	v_mov_b32_dpp v158, v108 row_shr:1 row_mask:0xf bank_mask:0xf
	v_mov_b32_dpp v159, v109 row_shr:1 row_mask:0xf bank_mask:0xf
	v_pk_fma_f32 v[184:185], v[128:129], v[154:155], v[184:185]
	v_mov_b32_dpp v152, v78 row_shr:1 row_mask:0xf bank_mask:0xf
	v_mov_b32_dpp v153, v79 row_shr:1 row_mask:0xf bank_mask:0xf
	v_pk_fma_f32 v[158:159], v[132:133], v[158:159], v[184:185]
	v_pk_fma_f32 v[184:185], v[126:127], v[142:143], v[146:147]
	v_mov_b32_dpp v156, v94 row_shr:1 row_mask:0xf bank_mask:0xf
	v_mov_b32_dpp v157, v95 row_shr:1 row_mask:0xf bank_mask:0xf
	v_pk_fma_f32 v[184:185], v[138:139], v[152:153], v[184:185]
	v_mov_b32_dpp v160, v110 row_shr:1 row_mask:0xf bank_mask:0xf
	v_mov_b32_dpp v161, v111 row_shr:1 row_mask:0xf bank_mask:0xf
	v_pk_fma_f32 v[184:185], v[130:131], v[156:157], v[184:185]
	v_ashrrev_i32_e32 v183, 31, v182
	v_pk_fma_f32 v[160:161], v[134:135], v[160:161], v[184:185]
	v_cvt_pk_bf16_f32 v158, v158, v159
	v_cvt_pk_bf16_f32 v159, v160, v161
	v_lshlrev_b64 v[160:161], 11, v[182:183]
	v_lshl_add_u64 v[160:161], s[18:19], 0, v[160:161]
	v_lshlrev_b32_e32 v170, 1, v220
	v_lshl_add_u64 v[184:185], v[160:161], 0, v[170:171]
	global_store_dwordx2 v[184:185], v[158:159], off
	v_pk_fma_f32 v[158:159], v[108:109], v[140:141], v[144:145]
	v_mov_b32_e32 v149, 0
	v_pk_fma_f32 v[158:159], v[124:125], v[136:137], v[158:159]
	s_nop 0
	v_pk_fma_f32 v[158:159], v[128:129], v[150:151], v[158:159]
	s_nop 0
	v_pk_fma_f32 v[154:155], v[132:133], v[154:155], v[158:159]
	v_pk_fma_f32 v[158:159], v[110:111], v[142:143], v[146:147]
	v_cvt_pk_bf16_f32 v154, v154, v155
	v_pk_fma_f32 v[158:159], v[126:127], v[138:139], v[158:159]
	s_nop 0
	v_pk_fma_f32 v[158:159], v[130:131], v[152:153], v[158:159]
	s_nop 0
	v_pk_fma_f32 v[156:157], v[134:135], v[156:157], v[158:159]
	v_mov_b32_e32 v158, 0
	v_cvt_pk_bf16_f32 v155, v156, v157
	v_or_b32_e32 v156, 1, v182
	v_ashrrev_i32_e32 v157, 31, v156
	v_lshlrev_b64 v[156:157], 11, v[156:157]
	v_lshl_add_u64 v[156:157], s[18:19], 0, v[156:157]
	v_lshl_add_u64 v[186:187], v[156:157], 0, v[170:171]
	global_store_dwordx2 v[186:187], v[154:155], off
	v_pk_fma_f32 v[154:155], v[92:93], v[140:141], v[144:145]
	v_mov_b32_e32 v156, 0
	v_pk_fma_f32 v[154:155], v[108:109], v[136:137], v[154:155]
	v_mov_b32_e32 v157, 0
	v_pk_fma_f32 v[154:155], v[124:125], v[128:129], v[154:155]
	v_mov_b32_e32 v159, 0
	v_pk_fma_f32 v[150:151], v[132:133], v[150:151], v[154:155]
	v_pk_fma_f32 v[154:155], v[94:95], v[142:143], v[146:147]
	v_cvt_pk_bf16_f32 v150, v150, v151
	v_pk_fma_f32 v[154:155], v[110:111], v[138:139], v[154:155]
	s_nop 0
	v_pk_fma_f32 v[154:155], v[126:127], v[130:131], v[154:155]
	s_nop 0
	v_pk_fma_f32 v[152:153], v[134:135], v[152:153], v[154:155]
	v_mov_b32_e32 v154, 0
	v_cvt_pk_bf16_f32 v151, v152, v153
	v_or_b32_e32 v152, 2, v182
	v_ashrrev_i32_e32 v153, 31, v152
	v_lshlrev_b64 v[152:153], 11, v[152:153]
	v_lshl_add_u64 v[152:153], s[18:19], 0, v[152:153]
	v_lshl_add_u64 v[188:189], v[152:153], 0, v[170:171]
	global_store_dwordx2 v[188:189], v[150:151], off
	v_pk_fma_f32 v[150:151], v[78:79], v[142:143], v[146:147]
	v_pk_fma_f32 v[152:153], v[76:77], v[140:141], v[144:145]
	v_pk_fma_f32 v[150:151], v[94:95], v[138:139], v[150:151]
	v_pk_fma_f32 v[152:153], v[92:93], v[136:137], v[152:153]
	v_pk_fma_f32 v[150:151], v[110:111], v[130:131], v[150:151]
	v_pk_fma_f32 v[152:153], v[108:109], v[128:129], v[152:153]
	v_pk_fma_f32 v[150:151], v[126:127], v[134:135], v[150:151]
	v_pk_fma_f32 v[152:153], v[124:125], v[132:133], v[152:153]
	v_mov_b32_e32 v155, 0
	v_cvt_pk_bf16_f32 v152, v152, v153
	v_cvt_pk_bf16_f32 v153, v150, v151
	v_or_b32_e32 v150, 3, v182
	v_ashrrev_i32_e32 v151, 31, v150
	v_lshlrev_b64 v[150:151], 11, v[150:151]
	v_lshl_add_u64 v[150:151], s[18:19], 0, v[150:151]
	v_lshl_add_u64 v[190:191], v[150:151], 0, v[170:171]
	global_store_dwordx2 v[190:191], v[152:153], off
	v_mov_b64_e32 v[150:151], 0
	v_mov_b64_e32 v[152:153], 0
	s_and_saveexec_b64 s[76:77], s[36:37]
	s_cbranch_execz .LBB0_1002
	ds_read_b128 v[148:151], v205 offset:3072
	ds_read_b128 v[156:159], v205 offset:4096
	ds_read_b128 v[152:155], v205 offset:5120
; #define LAS __attribute__((address_space(3)))
;     __device__ __forceinline__ void operator()(AccRef acc, const Unit& u, int wr, int wc, int fr, int fq) const {
;     ...
;                 const int c0 = col0 + bj * 128 + 4 * n;
;                 const f32x4 w0 = *(const f32x4*)(cw + c0), w1 = *(const f32x4*)(cw + D + c0), w2 = *(const f32x4*)(cw + 2 * D + c0), w3 = *(const f32x4*)(cw + 3 * D + c0), bb = *(const f32x4*)(cb + c0);
; #pragma unroll
;                 for (int ai = 0; ai < 2; ++ai) {
;                     f32x4 h1 = (f32x4){0.f, 0.f, 0.f, 0.f}, h2 = h1, h3 = h1;
;                     const int pb = ai * 2 + wr - 1;
;                     if (pb >= 0 && fr == 0) { const LAS float* xp = xch + (pb * 3) * 256 + bj * 128 + clb + 4 * n; h1 = *(const LAS f32x4*)(xp); h2 = *(const LAS f32x4*)(xp + 256); h3 = *(const LAS f32x4*)(xp + 512); }
;                     float o[4][4];
; #pragma unroll
;                     for (int j = 0; j < 4; ++j) {
;                         const float v0 = acc[ai][bj][0][n][j], v1 = acc[ai][bj][1][n][j], v2 = acc[ai][bj][2][n][j], v3 = acc[ai][bj][3][n][j];
;                         const float p3 = dpp_upd<0x111>(h3[j], v3), p2 = dpp_upd<0x111>(h2[j], v2), p1 = dpp_upd<0x111>(h1[j], v1);
;                         o[0][j] = bb[j] + w3[j] * v0 + w2[j] * p3 + w1[j] * p2 + w0[j] * p1;
;                         o[1][j] = bb[j] + w3[j] * v1 + w2[j] * v0 + w1[j] * p3 + w0[j] * p2;
;                         o[2][j] = bb[j] + w3[j] * v2 + w2[j] * v1 + w1[j] * v0 + w0[j] * p3;
;                         o[3][j] = bb[j] + w3[j] * v3 + w2[j] * v2 + w1[j] * v1 + w0[j] * v0; }
; #pragma unroll
;                     for (int m = 0; m < 4; ++m) *(u32x2*)(REC + (size_t)(row0 + ai * 128 + m) * D + c0) = (u32x2){cvt_pk_bf16(o[m][0], o[m][1]), cvt_pk_bf16(o[m][2], o[m][3])};
.LBB0_1002:
	s_or_b64 exec, exec, s[76:77]
	s_waitcnt lgkmcnt(0)
	v_mov_b32_dpp v152, v12 row_shr:1 row_mask:0xf bank_mask:0xf
	v_mov_b32_dpp v153, v13 row_shr:1 row_mask:0xf bank_mask:0xf
	v_pk_fma_f32 v[160:161], v[60:61], v[140:141], v[144:145]
	v_mov_b32_dpp v156, v28 row_shr:1 row_mask:0xf bank_mask:0xf
	v_mov_b32_dpp v157, v29 row_shr:1 row_mask:0xf bank_mask:0xf
	v_pk_fma_f32 v[160:161], v[136:137], v[152:153], v[160:161]
	v_mov_b32_dpp v148, v44 row_shr:1 row_mask:0xf bank_mask:0xf
	v_mov_b32_dpp v149, v45 row_shr:1 row_mask:0xf bank_mask:0xf
	v_pk_fma_f32 v[160:161], v[128:129], v[156:157], v[160:161]
	v_mov_b32_dpp v154, v14 row_shr:1 row_mask:0xf bank_mask:0xf
	v_mov_b32_dpp v155, v15 row_shr:1 row_mask:0xf bank_mask:0xf
	v_pk_fma_f32 v[148:149], v[132:133], v[148:149], v[160:161]
	v_pk_fma_f32 v[160:161], v[62:63], v[142:143], v[146:147]
	v_mov_b32_dpp v158, v30 row_shr:1 row_mask:0xf bank_mask:0xf
	v_mov_b32_dpp v159, v31 row_shr:1 row_mask:0xf bank_mask:0xf
	v_pk_fma_f32 v[160:161], v[138:139], v[154:155], v[160:161]
	v_mov_b32_dpp v150, v46 row_shr:1 row_mask:0xf bank_mask:0xf
	v_mov_b32_dpp v151, v47 row_shr:1 row_mask:0xf bank_mask:0xf
	v_pk_fma_f32 v[160:161], v[130:131], v[158:159], v[160:161]
	v_cvt_pk_bf16_f32 v148, v148, v149
	v_pk_fma_f32 v[150:151], v[134:135], v[150:151], v[160:161]
	v_mov_b32_e32 v193, v171
	v_cvt_pk_bf16_f32 v149, v150, v151
	v_add_co_u32_e32 v150, vcc, s6, v184
	v_lshl_add_u64 v[194:195], s[20:21], 0, v[192:193]
	s_nop 0
	v_addc_co_u32_e32 v151, vcc, 0, v185, vcc
	v_add_co_u32_e32 v160, vcc, s7, v184
	v_lshl_add_u64 v[192:193], s[22:23], 0, v[192:193]
	s_nop 0
	v_addc_co_u32_e32 v161, vcc, 0, v185, vcc
	global_store_dwordx2 v[160:161], v[148:149], off offset:-4096
	v_pk_fma_f32 v[148:149], v[44:45], v[140:141], v[144:145]
	s_nop 0
	v_pk_fma_f32 v[148:149], v[60:61], v[136:137], v[148:149]
	s_nop 0
	v_pk_fma_f32 v[148:149], v[128:129], v[152:153], v[148:149]
	s_nop 0
	v_pk_fma_f32 v[148:149], v[132:133], v[156:157], v[148:149]
	v_pk_fma_f32 v[156:157], v[46:47], v[142:143], v[146:147]
	v_cvt_pk_bf16_f32 v148, v148, v149
	v_pk_fma_f32 v[156:157], v[62:63], v[138:139], v[156:157]
	s_nop 0
	v_pk_fma_f32 v[156:157], v[130:131], v[154:155], v[156:157]
	s_nop 0
	v_pk_fma_f32 v[156:157], v[134:135], v[158:159], v[156:157]
	v_mov_b32_e32 v158, 0
	v_cvt_pk_bf16_f32 v149, v156, v157
	global_store_dwordx2 v[150:151], v[148:149], off offset:2048
	v_pk_fma_f32 v[148:149], v[28:29], v[140:141], v[144:145]
	v_pk_fma_f32 v[140:141], v[12:13], v[140:141], v[144:145]
	v_pk_fma_f32 v[148:149], v[44:45], v[136:137], v[148:149]
	v_pk_fma_f32 v[136:137], v[28:29], v[136:137], v[140:141]
	v_pk_fma_f32 v[148:149], v[60:61], v[128:129], v[148:149]
	v_pk_fma_f32 v[150:151], v[30:31], v[142:143], v[146:147]
	v_pk_fma_f32 v[142:143], v[14:15], v[142:143], v[146:147]
	v_pk_fma_f32 v[128:129], v[44:45], v[128:129], v[136:137]
	v_pk_fma_f32 v[148:149], v[132:133], v[152:153], v[148:149]
	v_pk_fma_f32 v[150:151], v[46:47], v[138:139], v[150:151]
	v_pk_fma_f32 v[128:129], v[60:61], v[132:133], v[128:129]
	v_pk_fma_f32 v[132:133], v[30:31], v[138:139], v[142:143]
	v_pk_fma_f32 v[150:151], v[62:63], v[130:131], v[150:151]
	v_pk_fma_f32 v[130:131], v[46:47], v[130:131], v[132:133]
	v_pk_fma_f32 v[150:151], v[134:135], v[154:155], v[150:151]
	v_pk_fma_f32 v[130:131], v[62:63], v[134:135], v[130:131]
	v_cvt_pk_bf16_f32 v148, v148, v149
	v_cvt_pk_bf16_f32 v149, v150, v151
	v_cvt_pk_bf16_f32 v128, v128, v129
	v_cvt_pk_bf16_f32 v129, v130, v131
	global_store_dwordx2 v[160:161], v[148:149], off
	global_store_dwordx2 v[160:161], v[128:129], off offset:2048
	v_lshl_or_b32 v140, v220, 2, 16
	global_load_dwordx4 v[128:131], v[194:195], off offset:16
	global_load_dwordx4 v[132:135], v140, s[38:39]
	global_load_dwordx4 v[136:139], v140, s[40:41]
	s_nop 0
	global_load_dwordx4 v[140:143], v140, s[42:43]
	s_nop 0
	global_load_dwordx4 v[144:147], v[192:193], off offset:16
	v_mov_b32_e32 v148, 0
	v_mov_b32_e32 v159, 0
	v_mov_b64_e32 v[160:161], 0
	v_mov_b64_e32 v[154:155], 0
	v_mov_b64_e32 v[156:157], 0
	v_mov_b64_e32 v[150:151], 0
	v_mov_b64_e32 v[152:153], 0
	s_and_saveexec_b64 s[76:77], s[34:35]
	s_cbranch_execz .LBB0_1004
	ds_read_b128 v[158:161], v209
	ds_read_b128 v[154:157], v208
	ds_read_b128 v[150:153], v207
; #define LAS __attribute__((address_space(3)))
;     __device__ __forceinline__ void operator()(AccRef acc, const Unit& u, int wr, int wc, int fr, int fq) const {
;     ...
;                 for (int ai = 0; ai < 2; ++ai) {
;                     f32x4 h1 = (f32x4){0.f, 0.f, 0.f, 0.f}, h2 = h1, h3 = h1;
;                     const int pb = ai * 2 + wr - 1;
;                     if (pb >= 0 && fr == 0) { const LAS float* xp = xch + (pb * 3) * 256 + bj * 128 + clb + 4 * n; h1 = *(const LAS f32x4*)(xp); h2 = *(const LAS f32x4*)(xp + 256); h3 = *(const LAS f32x4*)(xp + 512); }
;                     float o[4][4];
; #pragma unroll
;                     for (int j = 0; j < 4; ++j) {
;                         const float v0 = acc[ai][bj][0][n][j], v1 = acc[ai][bj][1][n][j], v2 = acc[ai][bj][2][n][j], v3 = acc[ai][bj][3][n][j];
;                         const float p3 = dpp_upd<0x111>(h3[j], v3), p2 = dpp_upd<0x111>(h2[j], v2), p1 = dpp_upd<0x111>(h1[j], v1);
;                         o[0][j] = bb[j] + w3[j] * v0 + w2[j] * p3 + w1[j] * p2 + w0[j] * p1;
;                         o[1][j] = bb[j] + w3[j] * v1 + w2[j] * v0 + w1[j] * p3 + w0[j] * p2;
;                         o[2][j] = bb[j] + w3[j] * v2 + w2[j] * v1 + w1[j] * v0 + w0[j] * p3;
;                         o[3][j] = bb[j] + w3[j] * v3 + w2[j] * v2 + w1[j] * v1 + w0[j] * v0; }
; #pragma unroll
;                     for (int m = 0; m < 4; ++m) *(u32x2*)(REC + (size_t)(row0 + ai * 128 + m) * D + c0) = (u32x2){cvt_pk_bf16(o[m][0], o[m][1]), cvt_pk_bf16(o[m][2], o[m][3])};
.LBB0_1004:
	s_or_b64 exec, exec, s[76:77]
	s_waitcnt lgkmcnt(0)
	v_mov_b32_dpp v150, v72 row_shr:1 row_mask:0xf bank_mask:0xf
	v_mov_b32_dpp v151, v73 row_shr:1 row_mask:0xf bank_mask:0xf
	s_waitcnt vmcnt(0)
	v_pk_fma_f32 v[196:197], v[120:121], v[140:141], v[144:145]
	v_mov_b32_dpp v154, v88 row_shr:1 row_mask:0xf bank_mask:0xf
	v_mov_b32_dpp v155, v89 row_shr:1 row_mask:0xf bank_mask:0xf
	v_pk_fma_f32 v[196:197], v[136:137], v[150:151], v[196:197]
	v_mov_b32_dpp v158, v104 row_shr:1 row_mask:0xf bank_mask:0xf
	v_mov_b32_dpp v159, v105 row_shr:1 row_mask:0xf bank_mask:0xf
	v_pk_fma_f32 v[196:197], v[132:133], v[154:155], v[196:197]
	v_mov_b32_dpp v152, v74 row_shr:1 row_mask:0xf bank_mask:0xf
	v_mov_b32_dpp v153, v75 row_shr:1 row_mask:0xf bank_mask:0xf
	v_pk_fma_f32 v[158:159], v[128:129], v[158:159], v[196:197]
	v_pk_fma_f32 v[196:197], v[122:123], v[142:143], v[146:147]
	v_mov_b32_dpp v156, v90 row_shr:1 row_mask:0xf bank_mask:0xf
	v_mov_b32_dpp v157, v91 row_shr:1 row_mask:0xf bank_mask:0xf
	v_pk_fma_f32 v[196:197], v[138:139], v[152:153], v[196:197]
	v_mov_b32_dpp v160, v106 row_shr:1 row_mask:0xf bank_mask:0xf
	v_mov_b32_dpp v161, v107 row_shr:1 row_mask:0xf bank_mask:0xf
	v_pk_fma_f32 v[196:197], v[134:135], v[156:157], v[196:197]
	v_cvt_pk_bf16_f32 v158, v158, v159
	v_pk_fma_f32 v[160:161], v[130:131], v[160:161], v[196:197]
	v_mov_b32_e32 v149, 0
	v_cvt_pk_bf16_f32 v159, v160, v161
	global_store_dwordx2 v[184:185], v[158:159], off offset:8
	v_pk_fma_f32 v[158:159], v[104:105], v[140:141], v[144:145]
	s_nop 0
	v_pk_fma_f32 v[158:159], v[120:121], v[136:137], v[158:159]
	s_nop 0
	v_pk_fma_f32 v[158:159], v[132:133], v[150:151], v[158:159]
	s_nop 0
	v_pk_fma_f32 v[154:155], v[128:129], v[154:155], v[158:159]
	v_pk_fma_f32 v[158:159], v[106:107], v[142:143], v[146:147]
	v_cvt_pk_bf16_f32 v154, v154, v155
	v_pk_fma_f32 v[158:159], v[122:123], v[138:139], v[158:159]
	s_nop 0
	v_pk_fma_f32 v[158:159], v[134:135], v[152:153], v[158:159]
	s_nop 0
	v_pk_fma_f32 v[156:157], v[130:131], v[156:157], v[158:159]
	v_mov_b32_e32 v158, 0
	v_cvt_pk_bf16_f32 v155, v156, v157
	global_store_dwordx2 v[186:187], v[154:155], off offset:8
	v_pk_fma_f32 v[154:155], v[88:89], v[140:141], v[144:145]
	v_mov_b32_e32 v156, 0
	v_pk_fma_f32 v[154:155], v[104:105], v[136:137], v[154:155]
	v_mov_b32_e32 v157, 0
	v_pk_fma_f32 v[154:155], v[120:121], v[132:133], v[154:155]
	v_mov_b32_e32 v159, 0
	v_pk_fma_f32 v[150:151], v[128:129], v[150:151], v[154:155]
	v_pk_fma_f32 v[154:155], v[90:91], v[142:143], v[146:147]
	v_cvt_pk_bf16_f32 v150, v150, v151
	v_pk_fma_f32 v[154:155], v[106:107], v[138:139], v[154:155]
	s_nop 0
	v_pk_fma_f32 v[154:155], v[122:123], v[134:135], v[154:155]
	s_nop 0
	v_pk_fma_f32 v[152:153], v[130:131], v[152:153], v[154:155]
	v_mov_b32_e32 v154, 0
	v_cvt_pk_bf16_f32 v151, v152, v153
	global_store_dwordx2 v[188:189], v[150:151], off offset:8
	v_pk_fma_f32 v[150:151], v[74:75], v[142:143], v[146:147]
	v_pk_fma_f32 v[152:153], v[72:73], v[140:141], v[144:145]
	v_pk_fma_f32 v[150:151], v[90:91], v[138:139], v[150:151]
	v_pk_fma_f32 v[152:153], v[88:89], v[136:137], v[152:153]
	v_pk_fma_f32 v[150:151], v[106:107], v[134:135], v[150:151]
	v_pk_fma_f32 v[152:153], v[104:105], v[132:133], v[152:153]
	v_pk_fma_f32 v[150:151], v[122:123], v[130:131], v[150:151]
	v_pk_fma_f32 v[152:153], v[120:121], v[128:129], v[152:153]
	v_mov_b32_e32 v155, 0
	v_cvt_pk_bf16_f32 v152, v152, v153
	v_cvt_pk_bf16_f32 v153, v150, v151
	global_store_dwordx2 v[190:191], v[152:153], off offset:8
	v_mov_b64_e32 v[150:151], 0
	v_mov_b64_e32 v[152:153], 0
	s_and_saveexec_b64 s[76:77], s[36:37]
	s_cbranch_execz .LBB0_1006
	ds_read_b128 v[148:151], v205 offset:3088
	ds_read_b128 v[156:159], v205 offset:4112
	ds_read_b128 v[152:155], v205 offset:5136
.LBB0_1006:
	s_or_b64 exec, exec, s[76:77]
	s_waitcnt lgkmcnt(0)
	v_mov_b32_dpp v152, v8 row_shr:1 row_mask:0xf bank_mask:0xf
	v_mov_b32_dpp v153, v9 row_shr:1 row_mask:0xf bank_mask:0xf
	v_pk_fma_f32 v[160:161], v[56:57], v[140:141], v[144:145]
	v_mov_b32_dpp v156, v24 row_shr:1 row_mask:0xf bank_mask:0xf
	v_mov_b32_dpp v157, v25 row_shr:1 row_mask:0xf bank_mask:0xf
	v_pk_fma_f32 v[160:161], v[136:137], v[152:153], v[160:161]
	v_mov_b32_dpp v148, v40 row_shr:1 row_mask:0xf bank_mask:0xf
	v_mov_b32_dpp v149, v41 row_shr:1 row_mask:0xf bank_mask:0xf
	v_pk_fma_f32 v[160:161], v[132:133], v[156:157], v[160:161]
	v_mov_b32_dpp v154, v10 row_shr:1 row_mask:0xf bank_mask:0xf
	v_mov_b32_dpp v155, v11 row_shr:1 row_mask:0xf bank_mask:0xf
	v_pk_fma_f32 v[148:149], v[128:129], v[148:149], v[160:161]
	v_pk_fma_f32 v[160:161], v[58:59], v[142:143], v[146:147]
	v_mov_b32_dpp v158, v26 row_shr:1 row_mask:0xf bank_mask:0xf
	v_mov_b32_dpp v159, v27 row_shr:1 row_mask:0xf bank_mask:0xf
	v_pk_fma_f32 v[160:161], v[138:139], v[154:155], v[160:161]
	v_mov_b32_dpp v150, v42 row_shr:1 row_mask:0xf bank_mask:0xf
	v_mov_b32_dpp v151, v43 row_shr:1 row_mask:0xf bank_mask:0xf
	v_pk_fma_f32 v[160:161], v[134:135], v[158:159], v[160:161]
	v_lshl_add_u64 v[202:203], v[184:185], 0, s[26:27]
	v_pk_fma_f32 v[150:151], v[130:131], v[150:151], v[160:161]
	v_cvt_pk_bf16_f32 v148, v148, v149
	v_cvt_pk_bf16_f32 v149, v150, v151
	global_store_dwordx2 v[202:203], v[148:149], off offset:8
	v_pk_fma_f32 v[148:149], v[40:41], v[140:141], v[144:145]
	v_pk_fma_f32 v[150:151], v[42:43], v[142:143], v[146:147]
	v_pk_fma_f32 v[148:149], v[56:57], v[136:137], v[148:149]
	v_pk_fma_f32 v[150:151], v[58:59], v[138:139], v[150:151]
	v_pk_fma_f32 v[148:149], v[132:133], v[152:153], v[148:149]
	v_pk_fma_f32 v[150:151], v[134:135], v[154:155], v[150:151]
	v_pk_fma_f32 v[148:149], v[128:129], v[156:157], v[148:149]
; #define LAS __attribute__((address_space(3)))
;     __device__ __forceinline__ void operator()(AccRef acc, const Unit& u, int wr, int wc, int fr, int fq) const {
;     ...
;         for (int bj = 0; bj < 2; ++bj)
; #pragma unroll
;             for (int n = 0; n < 2; ++n) {
;                 const int c0 = col0 + bj * 128 + 4 * n;
;                 const f32x4 w0 = *(const f32x4*)(cw + c0), w1 = *(const f32x4*)(cw + D + c0), w2 = *(const f32x4*)(cw + 2 * D + c0), w3 = *(const f32x4*)(cw + 3 * D + c0), bb = *(const f32x4*)(cb + c0);
; #pragma unroll
;                 for (int ai = 0; ai < 2; ++ai) {
;                     f32x4 h1 = (f32x4){0.f, 0.f, 0.f, 0.f}, h2 = h1, h3 = h1;
;                     const int pb = ai * 2 + wr - 1;
;                     if (pb >= 0 && fr == 0) { const LAS float* xp = xch + (pb * 3) * 256 + bj * 128 + clb + 4 * n; h1 = *(const LAS f32x4*)(xp); h2 = *(const LAS f32x4*)(xp + 256); h3 = *(const LAS f32x4*)(xp + 512); }
;                     float o[4][4];
; #pragma unroll
;                     for (int j = 0; j < 4; ++j) {
;                         const float v0 = acc[ai][bj][0][n][j], v1 = acc[ai][bj][1][n][j], v2 = acc[ai][bj][2][n][j], v3 = acc[ai][bj][3][n][j];
;                         const float p3 = dpp_upd<0x111>(h3[j], v3), p2 = dpp_upd<0x111>(h2[j], v2), p1 = dpp_upd<0x111>(h1[j], v1);
;                         o[0][j] = bb[j] + w3[j] * v0 + w2[j] * p3 + w1[j] * p2 + w0[j] * p1;
;                         o[1][j] = bb[j] + w3[j] * v1 + w2[j] * v0 + w1[j] * p3 + w0[j] * p2;
;                         o[2][j] = bb[j] + w3[j] * v2 + w2[j] * v1 + w1[j] * v0 + w0[j] * p3;
;                         o[3][j] = bb[j] + w3[j] * v3 + w2[j] * v2 + w1[j] * v1 + w0[j] * v0; }
; #pragma unroll
;                     for (int m = 0; m < 4; ++m) *(u32x2*)(REC + (size_t)(row0 + ai * 128 + m) * D + c0) = (u32x2){cvt_pk_bf16(o[m][0], o[m][1]), cvt_pk_bf16(o[m][2], o[m][3])};
	v_pk_fma_f32 v[150:151], v[130:131], v[158:159], v[150:151]
	v_lshl_add_u64 v[200:201], v[184:185], 0, s[44:45]
	v_cvt_pk_bf16_f32 v148, v148, v149
	v_cvt_pk_bf16_f32 v149, v150, v151
	global_store_dwordx2 v[200:201], v[148:149], off offset:8
	v_pk_fma_f32 v[148:149], v[24:25], v[140:141], v[144:145]
	v_pk_fma_f32 v[140:141], v[8:9], v[140:141], v[144:145]
	v_pk_fma_f32 v[148:149], v[40:41], v[136:137], v[148:149]
	v_pk_fma_f32 v[136:137], v[24:25], v[136:137], v[140:141]
	v_pk_fma_f32 v[148:149], v[56:57], v[132:133], v[148:149]
	v_pk_fma_f32 v[150:151], v[26:27], v[142:143], v[146:147]
	v_pk_fma_f32 v[142:143], v[10:11], v[142:143], v[146:147]
	v_pk_fma_f32 v[132:133], v[40:41], v[132:133], v[136:137]
	v_pk_fma_f32 v[148:149], v[128:129], v[152:153], v[148:149]
	v_pk_fma_f32 v[150:151], v[42:43], v[138:139], v[150:151]
	v_pk_fma_f32 v[128:129], v[56:57], v[128:129], v[132:133]
	v_pk_fma_f32 v[132:133], v[26:27], v[138:139], v[142:143]
	v_pk_fma_f32 v[150:151], v[58:59], v[134:135], v[150:151]
	v_pk_fma_f32 v[132:133], v[42:43], v[134:135], v[132:133]
	v_pk_fma_f32 v[150:151], v[130:131], v[154:155], v[150:151]
	v_pk_fma_f32 v[130:131], v[58:59], v[130:131], v[132:133]
	v_lshl_add_u64 v[198:199], v[184:185], 0, s[46:47]
	v_lshl_add_u64 v[196:197], v[184:185], 0, s[48:49]
	v_cvt_pk_bf16_f32 v148, v148, v149
	v_cvt_pk_bf16_f32 v149, v150, v151
	v_cvt_pk_bf16_f32 v128, v128, v129
	v_cvt_pk_bf16_f32 v129, v130, v131
	global_store_dwordx2 v[198:199], v[148:149], off offset:8
	global_store_dwordx2 v[196:197], v[128:129], off offset:8
	v_lshl_or_b32 v140, v220, 2, v217
	global_load_dwordx4 v[128:131], v[194:195], off offset:512
	global_load_dwordx4 v[132:135], v140, s[38:39]
	global_load_dwordx4 v[136:139], v140, s[40:41]
	s_nop 0
	global_load_dwordx4 v[140:143], v140, s[42:43]
	s_nop 0
	global_load_dwordx4 v[144:147], v[192:193], off offset:512
	v_mov_b32_e32 v148, 0
	v_mov_b64_e32 v[158:159], 0
	v_mov_b64_e32 v[160:161], 0
	v_mov_b64_e32 v[154:155], 0
	v_mov_b64_e32 v[156:157], 0
	v_mov_b64_e32 v[150:151], 0
	v_mov_b64_e32 v[152:153], 0
	s_and_saveexec_b64 s[76:77], s[34:35]
	s_cbranch_execz .LBB0_1008
	ds_read_b128 v[158:161], v210
	ds_read_b128 v[154:157], v210 offset:1024
	ds_read_b128 v[150:153], v210 offset:2048
.LBB0_1008:
	s_or_b64 exec, exec, s[76:77]
	s_waitcnt lgkmcnt(0)
	v_mov_b32_dpp v150, v68 row_shr:1 row_mask:0xf bank_mask:0xf
	v_mov_b32_dpp v151, v69 row_shr:1 row_mask:0xf bank_mask:0xf
	s_waitcnt vmcnt(0)
	v_pk_fma_f32 v[222:223], v[116:117], v[140:141], v[144:145]
	v_mov_b32_dpp v154, v84 row_shr:1 row_mask:0xf bank_mask:0xf
	v_mov_b32_dpp v155, v85 row_shr:1 row_mask:0xf bank_mask:0xf
	v_pk_fma_f32 v[222:223], v[136:137], v[150:151], v[222:223]
	v_mov_b32_dpp v158, v100 row_shr:1 row_mask:0xf bank_mask:0xf
	v_mov_b32_dpp v159, v101 row_shr:1 row_mask:0xf bank_mask:0xf
	v_pk_fma_f32 v[222:223], v[132:133], v[154:155], v[222:223]
	v_mov_b32_dpp v152, v70 row_shr:1 row_mask:0xf bank_mask:0xf
	v_mov_b32_dpp v153, v71 row_shr:1 row_mask:0xf bank_mask:0xf
	v_pk_fma_f32 v[158:159], v[128:129], v[158:159], v[222:223]
	v_pk_fma_f32 v[222:223], v[118:119], v[142:143], v[146:147]
	v_mov_b32_dpp v156, v86 row_shr:1 row_mask:0xf bank_mask:0xf
	v_mov_b32_dpp v157, v87 row_shr:1 row_mask:0xf bank_mask:0xf
	v_pk_fma_f32 v[222:223], v[138:139], v[152:153], v[222:223]
	v_mov_b32_dpp v160, v102 row_shr:1 row_mask:0xf bank_mask:0xf
	v_mov_b32_dpp v161, v103 row_shr:1 row_mask:0xf bank_mask:0xf
	v_pk_fma_f32 v[222:223], v[134:135], v[156:157], v[222:223]
	v_cvt_pk_bf16_f32 v158, v158, v159
	v_pk_fma_f32 v[160:161], v[130:131], v[160:161], v[222:223]
	v_mov_b32_e32 v149, 0
	v_cvt_pk_bf16_f32 v159, v160, v161
	global_store_dwordx2 v[184:185], v[158:159], off offset:256
	v_pk_fma_f32 v[158:159], v[100:101], v[140:141], v[144:145]
	s_nop 0
	v_pk_fma_f32 v[158:159], v[116:117], v[136:137], v[158:159]
	s_nop 0
	v_pk_fma_f32 v[158:159], v[132:133], v[150:151], v[158:159]
	s_nop 0
	v_pk_fma_f32 v[154:155], v[128:129], v[154:155], v[158:159]
	v_pk_fma_f32 v[158:159], v[102:103], v[142:143], v[146:147]
	v_cvt_pk_bf16_f32 v154, v154, v155
	v_pk_fma_f32 v[158:159], v[118:119], v[138:139], v[158:159]
	s_nop 0
	v_pk_fma_f32 v[158:159], v[134:135], v[152:153], v[158:159]
	s_nop 0
	v_pk_fma_f32 v[156:157], v[130:131], v[156:157], v[158:159]
	v_mov_b32_e32 v158, 0
	v_cvt_pk_bf16_f32 v155, v156, v157
	global_store_dwordx2 v[186:187], v[154:155], off offset:256
	v_pk_fma_f32 v[154:155], v[84:85], v[140:141], v[144:145]
	v_mov_b32_e32 v156, 0
	v_pk_fma_f32 v[154:155], v[100:101], v[136:137], v[154:155]
	v_mov_b32_e32 v157, 0
	v_pk_fma_f32 v[154:155], v[116:117], v[132:133], v[154:155]
	v_mov_b32_e32 v159, 0
	v_pk_fma_f32 v[150:151], v[128:129], v[150:151], v[154:155]
	v_pk_fma_f32 v[154:155], v[86:87], v[142:143], v[146:147]
	v_cvt_pk_bf16_f32 v150, v150, v151
	v_pk_fma_f32 v[154:155], v[102:103], v[138:139], v[154:155]
	s_nop 0
	v_pk_fma_f32 v[154:155], v[118:119], v[134:135], v[154:155]
	s_nop 0
	v_pk_fma_f32 v[152:153], v[130:131], v[152:153], v[154:155]
	v_mov_b32_e32 v154, 0
	v_cvt_pk_bf16_f32 v151, v152, v153
	global_store_dwordx2 v[188:189], v[150:151], off offset:256
	v_pk_fma_f32 v[150:151], v[70:71], v[142:143], v[146:147]
	v_pk_fma_f32 v[152:153], v[68:69], v[140:141], v[144:145]
	v_pk_fma_f32 v[150:151], v[86:87], v[138:139], v[150:151]
	v_pk_fma_f32 v[152:153], v[84:85], v[136:137], v[152:153]
	v_pk_fma_f32 v[150:151], v[102:103], v[134:135], v[150:151]
	v_pk_fma_f32 v[152:153], v[100:101], v[132:133], v[152:153]
	v_pk_fma_f32 v[150:151], v[118:119], v[130:131], v[150:151]
	v_pk_fma_f32 v[152:153], v[116:117], v[128:129], v[152:153]
	v_mov_b32_e32 v155, 0
	v_cvt_pk_bf16_f32 v152, v152, v153
	v_cvt_pk_bf16_f32 v153, v150, v151
	global_store_dwordx2 v[190:191], v[152:153], off offset:256
	v_mov_b64_e32 v[150:151], 0
	v_mov_b64_e32 v[152:153], 0
	s_and_saveexec_b64 s[76:77], s[36:37]
	s_cbranch_execz .LBB0_1010
	ds_read_b128 v[148:151], v205 offset:3584
	ds_read_b128 v[156:159], v205 offset:4608
	ds_read_b128 v[152:155], v205 offset:5632
; #define LAS __attribute__((address_space(3)))
;     __device__ __forceinline__ void operator()(AccRef acc, const Unit& u, int wr, int wc, int fr, int fq) const {
;     ...
;         for (int bj = 0; bj < 2; ++bj)
; #pragma unroll
;             for (int n = 0; n < 2; ++n) {
;                 const int c0 = col0 + bj * 128 + 4 * n;
;                 const f32x4 w0 = *(const f32x4*)(cw + c0), w1 = *(const f32x4*)(cw + D + c0), w2 = *(const f32x4*)(cw + 2 * D + c0), w3 = *(const f32x4*)(cw + 3 * D + c0), bb = *(const f32x4*)(cb + c0);
; #pragma unroll
;                 for (int ai = 0; ai < 2; ++ai) {
;                     f32x4 h1 = (f32x4){0.f, 0.f, 0.f, 0.f}, h2 = h1, h3 = h1;
;                     const int pb = ai * 2 + wr - 1;
;                     if (pb >= 0 && fr == 0) { const LAS float* xp = xch + (pb * 3) * 256 + bj * 128 + clb + 4 * n; h1 = *(const LAS f32x4*)(xp); h2 = *(const LAS f32x4*)(xp + 256); h3 = *(const LAS f32x4*)(xp + 512); }
;                     float o[4][4];
; #pragma unroll
;                     for (int j = 0; j < 4; ++j) {
;                         const float v0 = acc[ai][bj][0][n][j], v1 = acc[ai][bj][1][n][j], v2 = acc[ai][bj][2][n][j], v3 = acc[ai][bj][3][n][j];
;                         const float p3 = dpp_upd<0x111>(h3[j], v3), p2 = dpp_upd<0x111>(h2[j], v2), p1 = dpp_upd<0x111>(h1[j], v1);
;                         o[0][j] = bb[j] + w3[j] * v0 + w2[j] * p3 + w1[j] * p2 + w0[j] * p1;
;                         o[1][j] = bb[j] + w3[j] * v1 + w2[j] * v0 + w1[j] * p3 + w0[j] * p2;
;                         o[2][j] = bb[j] + w3[j] * v2 + w2[j] * v1 + w1[j] * v0 + w0[j] * p3;
;                         o[3][j] = bb[j] + w3[j] * v3 + w2[j] * v2 + w1[j] * v1 + w0[j] * v0; }
; #pragma unroll
;                     for (int m = 0; m < 4; ++m) *(u32x2*)(REC + (size_t)(row0 + ai * 128 + m) * D + c0) = (u32x2){cvt_pk_bf16(o[m][0], o[m][1]), cvt_pk_bf16(o[m][2], o[m][3])};
.LBB0_1010:
	s_or_b64 exec, exec, s[76:77]
	s_waitcnt lgkmcnt(0)
	v_mov_b32_dpp v152, v4 row_shr:1 row_mask:0xf bank_mask:0xf
	v_mov_b32_dpp v153, v5 row_shr:1 row_mask:0xf bank_mask:0xf
	v_pk_fma_f32 v[160:161], v[52:53], v[140:141], v[144:145]
	v_mov_b32_dpp v156, v20 row_shr:1 row_mask:0xf bank_mask:0xf
	v_mov_b32_dpp v157, v21 row_shr:1 row_mask:0xf bank_mask:0xf
	v_pk_fma_f32 v[160:161], v[136:137], v[152:153], v[160:161]
	v_mov_b32_dpp v148, v36 row_shr:1 row_mask:0xf bank_mask:0xf
	v_mov_b32_dpp v149, v37 row_shr:1 row_mask:0xf bank_mask:0xf
	v_pk_fma_f32 v[160:161], v[132:133], v[156:157], v[160:161]
	v_mov_b32_dpp v154, v6 row_shr:1 row_mask:0xf bank_mask:0xf
	v_mov_b32_dpp v155, v7 row_shr:1 row_mask:0xf bank_mask:0xf
	v_pk_fma_f32 v[148:149], v[128:129], v[148:149], v[160:161]
	v_pk_fma_f32 v[160:161], v[54:55], v[142:143], v[146:147]
	v_mov_b32_dpp v158, v22 row_shr:1 row_mask:0xf bank_mask:0xf
	v_mov_b32_dpp v159, v23 row_shr:1 row_mask:0xf bank_mask:0xf
	v_pk_fma_f32 v[160:161], v[138:139], v[154:155], v[160:161]
	v_mov_b32_dpp v150, v38 row_shr:1 row_mask:0xf bank_mask:0xf
	v_mov_b32_dpp v151, v39 row_shr:1 row_mask:0xf bank_mask:0xf
	v_pk_fma_f32 v[160:161], v[134:135], v[158:159], v[160:161]
	v_cvt_pk_bf16_f32 v148, v148, v149
	v_pk_fma_f32 v[150:151], v[130:131], v[150:151], v[160:161]
	v_mov_b32_e32 v160, 0
	v_cvt_pk_bf16_f32 v149, v150, v151
	global_store_dwordx2 v[202:203], v[148:149], off offset:256
	v_pk_fma_f32 v[148:149], v[36:37], v[140:141], v[144:145]
	v_pk_fma_f32 v[150:151], v[38:39], v[142:143], v[146:147]
	v_pk_fma_f32 v[148:149], v[52:53], v[136:137], v[148:149]
	v_pk_fma_f32 v[150:151], v[54:55], v[138:139], v[150:151]
	v_pk_fma_f32 v[148:149], v[132:133], v[152:153], v[148:149]
	v_pk_fma_f32 v[150:151], v[134:135], v[154:155], v[150:151]
	v_pk_fma_f32 v[148:149], v[128:129], v[156:157], v[148:149]
	v_pk_fma_f32 v[150:151], v[130:131], v[158:159], v[150:151]
	v_cvt_pk_bf16_f32 v148, v148, v149
	v_cvt_pk_bf16_f32 v149, v150, v151
	global_store_dwordx2 v[200:201], v[148:149], off offset:256
	v_pk_fma_f32 v[148:149], v[20:21], v[140:141], v[144:145]
	v_pk_fma_f32 v[140:141], v[4:5], v[140:141], v[144:145]
	v_pk_fma_f32 v[148:149], v[36:37], v[136:137], v[148:149]
	v_pk_fma_f32 v[136:137], v[20:21], v[136:137], v[140:141]
	v_pk_fma_f32 v[148:149], v[52:53], v[132:133], v[148:149]
	v_pk_fma_f32 v[150:151], v[22:23], v[142:143], v[146:147]
	v_pk_fma_f32 v[142:143], v[6:7], v[142:143], v[146:147]
	v_pk_fma_f32 v[132:133], v[36:37], v[132:133], v[136:137]
	v_pk_fma_f32 v[148:149], v[128:129], v[152:153], v[148:149]
	v_pk_fma_f32 v[150:151], v[38:39], v[138:139], v[150:151]
	v_pk_fma_f32 v[128:129], v[52:53], v[128:129], v[132:133]
	v_pk_fma_f32 v[132:133], v[22:23], v[138:139], v[142:143]
	v_pk_fma_f32 v[150:151], v[54:55], v[134:135], v[150:151]
	v_pk_fma_f32 v[132:133], v[38:39], v[134:135], v[132:133]
	v_pk_fma_f32 v[150:151], v[130:131], v[154:155], v[150:151]
	v_pk_fma_f32 v[130:131], v[54:55], v[130:131], v[132:133]
	v_cvt_pk_bf16_f32 v148, v148, v149
	v_cvt_pk_bf16_f32 v149, v150, v151
	v_cvt_pk_bf16_f32 v128, v128, v129
	v_cvt_pk_bf16_f32 v129, v130, v131
	global_store_dwordx2 v[198:199], v[148:149], off offset:256
	global_store_dwordx2 v[196:197], v[128:129], off offset:256
	v_lshl_or_b32 v140, v220, 2, v218
	global_load_dwordx4 v[128:131], v[194:195], off offset:528
	global_load_dwordx4 v[132:135], v140, s[38:39]
	global_load_dwordx4 v[136:139], v140, s[40:41]
	s_nop 0
	global_load_dwordx4 v[140:143], v140, s[42:43]
	s_nop 0
	global_load_dwordx4 v[144:147], v[192:193], off offset:528
	v_mov_b32_e32 v148, 0
	v_mov_b64_e32 v[158:159], 0
	v_mov_b32_e32 v161, 0
	v_mov_b64_e32 v[154:155], 0
	v_mov_b64_e32 v[156:157], 0
	v_mov_b64_e32 v[150:151], 0
	v_mov_b64_e32 v[152:153], 0
	s_and_saveexec_b64 s[76:77], s[34:35]
	s_cbranch_execz .LBB0_1012
	ds_read_b128 v[158:161], v213
	ds_read_b128 v[154:157], v212
	ds_read_b128 v[150:153], v211
; #define LAS __attribute__((address_space(3)))
;     __device__ __forceinline__ void operator()(AccRef acc, const Unit& u, int wr, int wc, int fr, int fq) const {
;     ...
;         for (int bj = 0; bj < 2; ++bj)
; #pragma unroll
;             for (int n = 0; n < 2; ++n) {
;                 const int c0 = col0 + bj * 128 + 4 * n;
;                 const f32x4 w0 = *(const f32x4*)(cw + c0), w1 = *(const f32x4*)(cw + D + c0), w2 = *(const f32x4*)(cw + 2 * D + c0), w3 = *(const f32x4*)(cw + 3 * D + c0), bb = *(const f32x4*)(cb + c0);
; #pragma unroll
;                 for (int ai = 0; ai < 2; ++ai) {
;                     f32x4 h1 = (f32x4){0.f, 0.f, 0.f, 0.f}, h2 = h1, h3 = h1;
;                     const int pb = ai * 2 + wr - 1;
;                     if (pb >= 0 && fr == 0) { const LAS float* xp = xch + (pb * 3) * 256 + bj * 128 + clb + 4 * n; h1 = *(const LAS f32x4*)(xp); h2 = *(const LAS f32x4*)(xp + 256); h3 = *(const LAS f32x4*)(xp + 512); }
;                     float o[4][4];
; #pragma unroll
;                     for (int j = 0; j < 4; ++j) {
;                         const float v0 = acc[ai][bj][0][n][j], v1 = acc[ai][bj][1][n][j], v2 = acc[ai][bj][2][n][j], v3 = acc[ai][bj][3][n][j];
;                         const float p3 = dpp_upd<0x111>(h3[j], v3), p2 = dpp_upd<0x111>(h2[j], v2), p1 = dpp_upd<0x111>(h1[j], v1);
;                         o[0][j] = bb[j] + w3[j] * v0 + w2[j] * p3 + w1[j] * p2 + w0[j] * p1;
;                         o[1][j] = bb[j] + w3[j] * v1 + w2[j] * v0 + w1[j] * p3 + w0[j] * p2;
;                         o[2][j] = bb[j] + w3[j] * v2 + w2[j] * v1 + w1[j] * v0 + w0[j] * p3;
;                         o[3][j] = bb[j] + w3[j] * v3 + w2[j] * v2 + w1[j] * v1 + w0[j] * v0; }
; #pragma unroll
;                     for (int m = 0; m < 4; ++m) *(u32x2*)(REC + (size_t)(row0 + ai * 128 + m) * D + c0) = (u32x2){cvt_pk_bf16(o[m][0], o[m][1]), cvt_pk_bf16(o[m][2], o[m][3])};
.LBB0_1012:
	s_or_b64 exec, exec, s[76:77]
	s_waitcnt lgkmcnt(0)
	v_mov_b32_dpp v150, v64 row_shr:1 row_mask:0xf bank_mask:0xf
	v_mov_b32_dpp v151, v65 row_shr:1 row_mask:0xf bank_mask:0xf
	s_waitcnt vmcnt(0)
	v_pk_fma_f32 v[192:193], v[112:113], v[140:141], v[144:145]
	v_mov_b32_dpp v154, v80 row_shr:1 row_mask:0xf bank_mask:0xf
	v_mov_b32_dpp v155, v81 row_shr:1 row_mask:0xf bank_mask:0xf
	v_pk_fma_f32 v[192:193], v[136:137], v[150:151], v[192:193]
	v_mov_b32_dpp v158, v96 row_shr:1 row_mask:0xf bank_mask:0xf
	v_mov_b32_dpp v159, v97 row_shr:1 row_mask:0xf bank_mask:0xf
	v_pk_fma_f32 v[192:193], v[132:133], v[154:155], v[192:193]
	v_mov_b32_dpp v152, v66 row_shr:1 row_mask:0xf bank_mask:0xf
	v_mov_b32_dpp v153, v67 row_shr:1 row_mask:0xf bank_mask:0xf
	v_pk_fma_f32 v[158:159], v[128:129], v[158:159], v[192:193]
	v_pk_fma_f32 v[192:193], v[114:115], v[142:143], v[146:147]
	v_mov_b32_dpp v156, v82 row_shr:1 row_mask:0xf bank_mask:0xf
	v_mov_b32_dpp v157, v83 row_shr:1 row_mask:0xf bank_mask:0xf
	v_pk_fma_f32 v[192:193], v[138:139], v[152:153], v[192:193]
	v_mov_b32_dpp v160, v98 row_shr:1 row_mask:0xf bank_mask:0xf
	v_mov_b32_dpp v161, v99 row_shr:1 row_mask:0xf bank_mask:0xf
	v_pk_fma_f32 v[192:193], v[134:135], v[156:157], v[192:193]
	v_cvt_pk_bf16_f32 v158, v158, v159
	v_pk_fma_f32 v[160:161], v[130:131], v[160:161], v[192:193]
	v_mov_b32_e32 v149, 0
	v_cvt_pk_bf16_f32 v159, v160, v161
	global_store_dwordx2 v[184:185], v[158:159], off offset:264
	v_pk_fma_f32 v[158:159], v[96:97], v[140:141], v[144:145]
	s_nop 0
	v_pk_fma_f32 v[158:159], v[112:113], v[136:137], v[158:159]
	s_nop 0
	v_pk_fma_f32 v[158:159], v[132:133], v[150:151], v[158:159]
	s_nop 0
	v_pk_fma_f32 v[154:155], v[128:129], v[154:155], v[158:159]
	v_pk_fma_f32 v[158:159], v[98:99], v[142:143], v[146:147]
	v_cvt_pk_bf16_f32 v154, v154, v155
	v_pk_fma_f32 v[158:159], v[114:115], v[138:139], v[158:159]
	s_nop 0
	v_pk_fma_f32 v[158:159], v[134:135], v[152:153], v[158:159]
	s_nop 0
	v_pk_fma_f32 v[156:157], v[130:131], v[156:157], v[158:159]
	v_mov_b32_e32 v158, 0
	v_cvt_pk_bf16_f32 v155, v156, v157
	global_store_dwordx2 v[186:187], v[154:155], off offset:264
	v_pk_fma_f32 v[154:155], v[80:81], v[140:141], v[144:145]
	v_mov_b32_e32 v156, 0
	v_pk_fma_f32 v[154:155], v[96:97], v[136:137], v[154:155]
	v_mov_b32_e32 v157, 0
	v_pk_fma_f32 v[154:155], v[112:113], v[132:133], v[154:155]
	v_mov_b32_e32 v159, 0
	v_pk_fma_f32 v[150:151], v[128:129], v[150:151], v[154:155]
	v_pk_fma_f32 v[154:155], v[82:83], v[142:143], v[146:147]
	v_cvt_pk_bf16_f32 v150, v150, v151
	v_pk_fma_f32 v[154:155], v[98:99], v[138:139], v[154:155]
	s_nop 0
	v_pk_fma_f32 v[154:155], v[114:115], v[134:135], v[154:155]
	s_nop 0
	v_pk_fma_f32 v[152:153], v[130:131], v[152:153], v[154:155]
	v_mov_b32_e32 v154, 0
	v_cvt_pk_bf16_f32 v151, v152, v153
	global_store_dwordx2 v[188:189], v[150:151], off offset:264
	v_pk_fma_f32 v[150:151], v[66:67], v[142:143], v[146:147]
	v_pk_fma_f32 v[152:153], v[64:65], v[140:141], v[144:145]
	v_pk_fma_f32 v[150:151], v[82:83], v[138:139], v[150:151]
	v_pk_fma_f32 v[152:153], v[80:81], v[136:137], v[152:153]
	v_pk_fma_f32 v[150:151], v[98:99], v[134:135], v[150:151]
	v_pk_fma_f32 v[152:153], v[96:97], v[132:133], v[152:153]
	v_pk_fma_f32 v[150:151], v[114:115], v[130:131], v[150:151]
	v_pk_fma_f32 v[152:153], v[112:113], v[128:129], v[152:153]
	v_mov_b32_e32 v155, 0
	v_cvt_pk_bf16_f32 v152, v152, v153
	v_cvt_pk_bf16_f32 v153, v150, v151
	global_store_dwordx2 v[190:191], v[152:153], off offset:264
	v_mov_b64_e32 v[150:151], 0
	v_mov_b64_e32 v[152:153], 0
	s_and_saveexec_b64 s[76:77], s[36:37]
	s_cbranch_execz .LBB0_1014
	ds_read_b128 v[148:151], v205 offset:3600
	ds_read_b128 v[156:159], v205 offset:4624
	ds_read_b128 v[152:155], v205 offset:5648

;     __device__ __forceinline__ void operator()(AccRef acc, const Unit& u, int wr, int wc, int fr, int fq) const {
;     ...
;         float* rawu = raw + (size_t)(u.pm * 22 + u.pn) * 1024;
;         if (wr == 0 && fr == 0) {
; #pragma unroll
;             for (int bj = 0; bj < 2; ++bj)
; #pragma unroll
;                 for (int n = 0; n < 2; ++n) { *(f32x4*)(rawu + 0 * 256 + bj * 128 + clb + 4 * n) = acc[0][bj][0][n]; *(f32x4*)(rawu + 1 * 256 + bj * 128 + clb + 4 * n) = acc[0][bj][1][n]; }
;         }
;         if (wr == 1 && fr == 15) {
; #pragma unroll
;             for (int bj = 0; bj < 2; ++bj)
; #pragma unroll
;                 for (int n = 0; n < 2; ++n) { *(f32x4*)(rawu + 2 * 256 + bj * 128 + clb + 4 * n) = acc[1][bj][2][n]; *(f32x4*)(rawu + 3 * 256 + bj * 128 + clb + 4 * n) = acc[1][bj][3][n]; }
;         }
;         asm volatile("s_waitcnt lgkmcnt(0)" ::: "memory"); __builtin_amdgcn_s_barrier(); __builtin_amdgcn_s_barrier(); asm volatile("" ::: "memory");
;         const int hc0 = 128 * u.pn + clb, row0 = u.pm * 256 + wr * 64 + 4 * fr;
; #pragma unroll
;         for (int n = 0; n < 2; ++n) {
;             const f32x4 w0v = cwv[n][0], w1v = cwv[n][1], w2v = cwv[n][2], bvv = cwv[n][3], w0g = cwv[n][4], w1g = cwv[n][5], w2g = cwv[n][6], bvg = cwv[n][7];
; #pragma unroll
;             for (int ai = 0; ai < 2; ++ai) {
;                 if (n == 0 && ai == 0) {
;                     asm volatile("" ::: "memory");
;                     const float* cv = cw + hc0 + 4; const float* cg = cv + FH; const float* bp = cb + hc0 + 4;
;                     cwv[1][0] = *(const f32x4*)(cv); cwv[1][1] = *(const f32x4*)(cv + F2); cwv[1][2] = *(const f32x4*)(cv + 2 * F2); cwv[1][3] = *(const f32x4*)(bp);
;                     cwv[1][4] = *(const f32x4*)(cg); cwv[1][5] = *(const f32x4*)(cg + F2); cwv[1][6] = *(const f32x4*)(cg + 2 * F2); cwv[1][7] = *(const f32x4*)(bp + FH);
;                     asm volatile("" ::: "memory"); }
;                 f32x4 h2v = (f32x4){0.f, 0.f, 0.f, 0.f}, h3v = h2v, h2g = h2v, h3g = h2v;
;                 const int pb = ai * 2 + wr - 1;
;                 if (pb >= 0 && fr == 0) { const LAS float* xp = xch + (pb * 2) * 256 + clb + 4 * n;
;                     h2v = *(const LAS f32x4*)(xp); h3v = *(const LAS f32x4*)(xp + 256); h2g = *(const LAS f32x4*)(xp + 128); h3g = *(const LAS f32x4*)(xp + 256 + 128); }
.LBB0_1362:
	s_or_b64 exec, exec, s[46:47]
	s_mul_i32 s35, s42, 22
	s_add_i32 s46, s35, s43
	s_ashr_i32 s47, s46, 31
	s_lshl_b64 s[46:47], s[46:47], 12
	s_add_u32 s46, s64, s46
	s_addc_u32 s47, s65, s47
	v_lshlrev_b32_e32 v96, 2, v218
	v_or_b32_e32 v232, s44, v218
	v_ashrrev_i32_e32 v233, 31, v232
	v_lshlrev_b64 v[96:97], 2, v[232:233]
	v_lshl_add_u64 v[120:121], s[16:17], 0, v[96:97]
	v_add_co_u32_e32 v100, vcc, 0x5000, v120
	s_waitcnt lgkmcnt(0)
	s_barrier
	s_nop 0
	v_addc_co_u32_e32 v101, vcc, 0, v121, vcc
	v_add_co_u32_e32 v104, vcc, 0xb000, v120
	s_barrier
	s_nop 0
	v_addc_co_u32_e32 v105, vcc, 0, v121, vcc
	v_add_co_u32_e32 v112, vcc, s76, v120
	v_lshl_add_u64 v[124:125], s[22:23], 0, v[96:97]
	s_nop 0
	v_addc_co_u32_e32 v113, vcc, 0, v121, vcc
	v_add_co_u32_e32 v116, vcc, 0x8000, v120
	s_nop 0
	s_nop 0
	v_addc_co_u32_e32 v117, vcc, 0, v121, vcc
	v_add_co_u32_e32 v120, vcc, 0xd000, v120
	s_nop 0
	s_nop 0
	v_addc_co_u32_e32 v121, vcc, 0, v121, vcc
	v_add_co_u32_e32 v124, vcc, 0x2000, v124
	s_nop 0
	s_nop 0
	v_addc_co_u32_e32 v125, vcc, 0, v125, vcc
	v_mov_b32_e32 v192, 0
	v_mov_b64_e32 v[198:199], 0
	v_mov_b64_e32 v[200:201], 0
	v_mov_b64_e32 v[206:207], 0
	v_mov_b64_e32 v[208:209], 0
	v_mov_b64_e32 v[194:195], 0
	v_mov_b64_e32 v[196:197], 0
	v_mov_b64_e32 v[202:203], 0
	v_mov_b64_e32 v[204:205], 0
	s_and_saveexec_b64 s[44:45], s[28:29]
	s_cbranch_execz .LBB0_1368
	ds_read_b128 v[202:205], v238
	ds_read_b128 v[206:209], v238 offset:512
	ds_read_b128 v[194:197], v238 offset:1024
	ds_read_b128 v[198:201], v238 offset:1536

; __device__ __forceinline__ float sigmoidf_(float x) { return __builtin_amdgcn_rcpf(1.0f + __expf(-x)); }
;     __device__ __forceinline__ void operator()(AccRef acc, const Unit& u, int wr, int wc, int fr, int fq) const {
;     ...
;                 float o[4][4];
; #pragma unroll
;                 for (int j = 0; j < 4; ++j) {
;                     const float v0 = acc[ai][0][0][n][j], v1 = acc[ai][0][1][n][j], v2 = acc[ai][0][2][n][j], v3 = acc[ai][0][3][n][j];
;                     const float g0 = acc[ai][1][0][n][j], g1 = acc[ai][1][1][n][j], g2 = acc[ai][1][2][n][j], g3 = acc[ai][1][3][n][j];
;                     const float pv3 = dpp_upd<0x111>(h3v[j], v3), pv2 = dpp_upd<0x111>(h2v[j], v2), pg3 = dpp_upd<0x111>(h3g[j], g3), pg2 = dpp_upd<0x111>(h2g[j], g2);
;                     const float hv0 = bvv[j] + w2v[j] * v0 + w1v[j] * pv3 + w0v[j] * pv2, hv1 = bvv[j] + w2v[j] * v1 + w1v[j] * v0 + w0v[j] * pv3;
;                     const float hv2 = bvv[j] + w2v[j] * v2 + w1v[j] * v1 + w0v[j] * v0, hv3 = bvv[j] + w2v[j] * v3 + w1v[j] * v2 + w0v[j] * v1;
;                     const float hg0 = bvg[j] + w2g[j] * g0 + w1g[j] * pg3 + w0g[j] * pg2, hg1 = bvg[j] + w2g[j] * g1 + w1g[j] * g0 + w0g[j] * pg3;
;                     const float hg2 = bvg[j] + w2g[j] * g2 + w1g[j] * g1 + w0g[j] * g0, hg3 = bvg[j] + w2g[j] * g3 + w1g[j] * g2 + w0g[j] * g1;
;                     o[0][j] = hg0 * sigmoidf_(hg0) * hv0; o[1][j] = hg1 * sigmoidf_(hg1) * hv1; o[2][j] = hg2 * sigmoidf_(hg2) * hv2; o[3][j] = hg3 * sigmoidf_(hg3) * hv3; }
; #pragma unroll
;                 for (int m = 0; m < 4; ++m) { u32x2 w; w.x = cvt_pk_bf16(o[m][0], o[m][1]); w.y = cvt_pk_bf16(o[m][2], o[m][3]);
;                     *(u32x2*)(Aout + (size_t)(row0 + ai * 128 + m) * FH + hc0 + 4 * n) = w; } } }
.LBB0_1366:
	s_or_b64 exec, exec, s[48:49]
	v_pk_fma_f32 v[248:249], v[152:153], v[184:185], v[188:189]
	v_mov_b32_dpp v206, v128 row_shr:1 row_mask:0xf bank_mask:0xf
	v_mov_b32_dpp v207, v129 row_shr:1 row_mask:0xf bank_mask:0xf
	v_pk_fma_f32 v[248:249], v[180:181], v[198:199], v[248:249]
	v_mov_b32_dpp v194, v148 row_shr:1 row_mask:0xf bank_mask:0xf
	v_pk_fma_f32 v[206:207], v[176:177], v[206:207], v[248:249]
	v_mov_b32_dpp v195, v149 row_shr:1 row_mask:0xf bank_mask:0xf
	v_exp_f32_e32 v248, v206
	v_exp_f32_e32 v249, v207
	v_pk_fma_f32 v[250:251], v[156:157], v[168:169], v[172:173]
	v_pk_add_f32 v[248:249], v[248:249], 1.0 op_sel_hi:[1,0]
	v_rcp_f32_e32 v248, v248
	v_rcp_f32_e32 v249, v249
	v_mov_b32_dpp v202, v136 row_shr:1 row_mask:0xf bank_mask:0xf
	v_mov_b32_dpp v203, v137 row_shr:1 row_mask:0xf bank_mask:0xf
	v_pk_fma_f32 v[250:251], v[164:165], v[194:195], v[250:251]
	v_pk_mul_f32 v[206:207], v[206:207], v[248:249]
	v_pk_fma_f32 v[202:203], v[160:161], v[202:203], v[250:251]
	v_mov_b32_dpp v200, v142 row_shr:1 row_mask:0xf bank_mask:0xf
	v_mov_b32_dpp v201, v143 row_shr:1 row_mask:0xf bank_mask:0xf
	v_pk_mul_f32 v[202:203], v[202:203], v[206:207]
	v_pk_fma_f32 v[206:207], v[154:155], v[186:187], v[190:191]
	v_mov_b32_dpp v208, v130 row_shr:1 row_mask:0xf bank_mask:0xf
	v_mov_b32_dpp v209, v131 row_shr:1 row_mask:0xf bank_mask:0xf
	v_pk_fma_f32 v[206:207], v[182:183], v[200:201], v[206:207]
	v_mov_b32_dpp v196, v150 row_shr:1 row_mask:0xf bank_mask:0xf
	v_pk_fma_f32 v[206:207], v[178:179], v[208:209], v[206:207]
	v_mov_b32_dpp v197, v151 row_shr:1 row_mask:0xf bank_mask:0xf
	v_exp_f32_e32 v193, v206
	v_exp_f32_e32 v209, v207
	v_cvt_pk_bf16_f32 v208, v202, v203
	v_add_f32_e32 v193, 1.0, v193
	v_rcp_f32_e32 v202, v193
	v_add_f32_e32 v193, 1.0, v209
	v_rcp_f32_e32 v203, v193
	v_pk_fma_f32 v[248:249], v[158:159], v[170:171], v[174:175]
	v_mov_b32_dpp v204, v138 row_shr:1 row_mask:0xf bank_mask:0xf
	v_mov_b32_dpp v205, v139 row_shr:1 row_mask:0xf bank_mask:0xf
	v_pk_fma_f32 v[248:249], v[166:167], v[196:197], v[248:249]
	v_pk_mul_f32 v[202:203], v[206:207], v[202:203]
	v_pk_fma_f32 v[204:205], v[162:163], v[204:205], v[248:249]
	v_lshl_add_u32 v246, s42, 8, v236
	v_pk_mul_f32 v[202:203], v[204:205], v[202:203]
	v_lshlrev_b64 v[204:205], 1, v[232:233]
	v_pk_fma_f32 v[232:233], v[132:133], v[184:185], v[188:189]
	v_mov_b64_e32 v[206:207], s[60:61]
	v_pk_fma_f32 v[232:233], v[152:153], v[180:181], v[232:233]
	v_cvt_pk_bf16_f32 v209, v202, v203
	v_pk_fma_f32 v[198:199], v[176:177], v[198:199], v[232:233]
	v_mad_i64_i32 v[202:203], s[42:43], v246, s82, v[206:207]
	v_exp_f32_e32 v193, v198
	v_exp_f32_e32 v232, v199
	v_lshl_add_u64 v[202:203], v[202:203], 0, v[204:205]
	v_add_f32_e32 v193, 1.0, v193
	v_mov_b32_e32 v247, v208
	v_mov_b32_e32 v248, v209
	v_rcp_f32_e32 v208, v193
	v_add_f32_e32 v193, 1.0, v232
	v_rcp_f32_e32 v209, v193
	v_pk_fma_f32 v[232:233], v[144:145], v[168:169], v[172:173]
	v_pk_fma_f32 v[140:141], v[140:141], v[184:185], v[188:189]
	v_pk_fma_f32 v[232:233], v[156:157], v[164:165], v[232:233]
	v_pk_mul_f32 v[198:199], v[198:199], v[208:209]
	v_pk_fma_f32 v[194:195], v[160:161], v[194:195], v[232:233]
	v_pk_fma_f32 v[208:209], v[146:147], v[170:171], v[174:175]
	v_pk_mul_f32 v[194:195], v[194:195], v[198:199]
	v_pk_fma_f32 v[198:199], v[134:135], v[186:187], v[190:191]
	v_pk_fma_f32 v[208:209], v[158:159], v[166:167], v[208:209]
	v_pk_fma_f32 v[198:199], v[154:155], v[182:183], v[198:199]
	v_pk_fma_f32 v[196:197], v[162:163], v[196:197], v[208:209]
	v_pk_fma_f32 v[198:199], v[178:179], v[200:201], v[198:199]
	v_cvt_pk_bf16_f32 v194, v194, v195
	v_exp_f32_e32 v200, v198
	v_exp_f32_e32 v201, v199
	v_pk_fma_f32 v[148:149], v[148:149], v[168:169], v[172:173]
	v_pk_add_f32 v[200:201], v[200:201], 1.0 op_sel_hi:[1,0]
	v_rcp_f32_e32 v200, v200
	v_rcp_f32_e32 v201, v201
	v_or_b32_e32 v193, 1, v246
	v_pk_mul_f32 v[198:199], v[198:199], v[200:201]
	s_nop 0
	v_pk_mul_f32 v[196:197], v[196:197], v[198:199]
	v_pk_fma_f32 v[198:199], v[128:129], v[184:185], v[188:189]
	v_cvt_pk_bf16_f32 v195, v196, v197
	v_pk_fma_f32 v[198:199], v[132:133], v[180:181], v[198:199]
	v_mad_i64_i32 v[196:197], s[42:43], v193, s82, v[206:207]
	v_pk_fma_f32 v[152:153], v[152:153], v[176:177], v[198:199]
	v_lshl_add_u64 v[196:197], v[196:197], 0, v[204:205]
	v_exp_f32_e32 v193, v152
	v_exp_f32_e32 v198, v153
	v_mov_b32_e32 v249, v194
	v_mov_b32_e32 v250, v195
	v_add_f32_e32 v193, 1.0, v193
	v_rcp_f32_e32 v194, v193
	v_add_f32_e32 v193, 1.0, v198
	v_rcp_f32_e32 v195, v193
	v_pk_fma_f32 v[198:199], v[136:137], v[168:169], v[172:173]
	v_pk_fma_f32 v[128:129], v[128:129], v[180:181], v[140:141]
	v_pk_fma_f32 v[198:199], v[144:145], v[164:165], v[198:199]
	v_pk_fma_f32 v[128:129], v[132:133], v[176:177], v[128:129]
	v_pk_fma_f32 v[156:157], v[156:157], v[160:161], v[198:199]
	v_pk_mul_f32 v[152:153], v[152:153], v[194:195]
	v_pk_mul_f32 v[152:153], v[156:157], v[152:153]
	v_pk_fma_f32 v[156:157], v[130:131], v[186:187], v[190:191]
	v_exp_f32_e32 v140, v128
	v_pk_fma_f32 v[132:133], v[142:143], v[186:187], v[190:191]
	v_pk_fma_f32 v[156:157], v[134:135], v[182:183], v[156:157]
	v_pk_fma_f32 v[130:131], v[130:131], v[182:183], v[132:133]
	v_pk_fma_f32 v[154:155], v[154:155], v[178:179], v[156:157]
	v_pk_fma_f32 v[130:131], v[134:135], v[178:179], v[130:131]
	v_exp_f32_e32 v157, v154
	v_exp_f32_e32 v141, v129
	v_exp_f32_e32 v132, v130
	v_exp_f32_e32 v133, v131
	v_exp_f32_e32 v193, v155
	v_pk_add_f32 v[140:141], v[140:141], 1.0 op_sel_hi:[1,0]
	v_pk_add_f32 v[132:133], v[132:133], 1.0 op_sel_hi:[1,0]
	v_cvt_pk_bf16_f32 v156, v152, v153
	v_add_f32_e32 v152, 1.0, v157
; #define LAS __attribute__((address_space(3)))
; __device__ __forceinline__ float sigmoidf_(float x) { return __builtin_amdgcn_rcpf(1.0f + __expf(-x)); }
;     __device__ __forceinline__ void operator()(AccRef acc, const Unit& u, int wr, int wc, int fr, int fq) const {
;     ...
;                 f32x4 h2v = (f32x4){0.f, 0.f, 0.f, 0.f}, h3v = h2v, h2g = h2v, h3g = h2v;
;                 const int pb = ai * 2 + wr - 1;
;                 if (pb >= 0 && fr == 0) { const LAS float* xp = xch + (pb * 2) * 256 + clb + 4 * n;
;                     h2v = *(const LAS f32x4*)(xp); h3v = *(const LAS f32x4*)(xp + 256); h2g = *(const LAS f32x4*)(xp + 128); h3g = *(const LAS f32x4*)(xp + 256 + 128); }
;                 float o[4][4];
; #pragma unroll
;                 for (int j = 0; j < 4; ++j) {
;                     const float v0 = acc[ai][0][0][n][j], v1 = acc[ai][0][1][n][j], v2 = acc[ai][0][2][n][j], v3 = acc[ai][0][3][n][j];
;                     const float g0 = acc[ai][1][0][n][j], g1 = acc[ai][1][1][n][j], g2 = acc[ai][1][2][n][j], g3 = acc[ai][1][3][n][j];
;                     const float pv3 = dpp_upd<0x111>(h3v[j], v3), pv2 = dpp_upd<0x111>(h2v[j], v2), pg3 = dpp_upd<0x111>(h3g[j], g3), pg2 = dpp_upd<0x111>(h2g[j], g2);
;                     const float hv0 = bvv[j] + w2v[j] * v0 + w1v[j] * pv3 + w0v[j] * pv2, hv1 = bvv[j] + w2v[j] * v1 + w1v[j] * v0 + w0v[j] * pv3;
;                     const float hv2 = bvv[j] + w2v[j] * v2 + w1v[j] * v1 + w0v[j] * v0, hv3 = bvv[j] + w2v[j] * v3 + w1v[j] * v2 + w0v[j] * v1;
;                     const float hg0 = bvg[j] + w2g[j] * g0 + w1g[j] * pg3 + w0g[j] * pg2, hg1 = bvg[j] + w2g[j] * g1 + w1g[j] * g0 + w0g[j] * pg3;
;                     const float hg2 = bvg[j] + w2g[j] * g2 + w1g[j] * g1 + w0g[j] * g0, hg3 = bvg[j] + w2g[j] * g3 + w1g[j] * g2 + w0g[j] * g1;
;                     o[0][j] = hg0 * sigmoidf_(hg0) * hv0; o[1][j] = hg1 * sigmoidf_(hg1) * hv1; o[2][j] = hg2 * sigmoidf_(hg2) * hv2; o[3][j] = hg3 * sigmoidf_(hg3) * hv3; }
; #pragma unroll
;                 for (int m = 0; m < 4; ++m) { u32x2 w; w.x = cvt_pk_bf16(o[m][0], o[m][1]); w.y = cvt_pk_bf16(o[m][2], o[m][3]);
;                     *(u32x2*)(Aout + (size_t)(row0 + ai * 128 + m) * FH + hc0 + 4 * n) = w; } } }
	v_add_f32_e32 v153, 1.0, v193
	v_rcp_f32_e32 v140, v140
	v_rcp_f32_e32 v141, v141
	v_rcp_f32_e32 v132, v132
	v_rcp_f32_e32 v133, v133
	v_rcp_f32_e32 v152, v152
	v_rcp_f32_e32 v153, v153
	v_pk_fma_f32 v[142:143], v[150:151], v[170:171], v[174:175]
	v_pk_fma_f32 v[194:195], v[138:139], v[170:171], v[174:175]
	v_pk_fma_f32 v[136:137], v[136:137], v[164:165], v[148:149]
	v_pk_fma_f32 v[134:135], v[138:139], v[166:167], v[142:143]
	v_pk_fma_f32 v[194:195], v[146:147], v[166:167], v[194:195]
	v_pk_fma_f32 v[136:137], v[144:145], v[160:161], v[136:137]
	v_pk_mul_f32 v[128:129], v[128:129], v[140:141]
	v_pk_fma_f32 v[134:135], v[146:147], v[162:163], v[134:135]
	v_pk_mul_f32 v[130:131], v[130:131], v[132:133]
	v_pk_fma_f32 v[158:159], v[158:159], v[162:163], v[194:195]
	v_pk_mul_f32 v[152:153], v[154:155], v[152:153]
	v_pk_mul_f32 v[128:129], v[136:137], v[128:129]
	v_pk_mul_f32 v[130:131], v[134:135], v[130:131]
	v_pk_mul_f32 v[152:153], v[158:159], v[152:153]
	v_cvt_pk_bf16_f32 v128, v128, v129
	v_cvt_pk_bf16_f32 v129, v130, v131
	v_or_b32_e32 v130, 3, v246
	v_cvt_pk_bf16_f32 v157, v152, v153
	v_or_b32_e32 v152, 2, v246
	v_mad_i64_i32 v[130:131], s[42:43], v130, s82, v[206:207]
	v_mad_i64_i32 v[152:153], s[42:43], v152, s82, v[206:207]
	v_lshl_add_u64 v[140:141], v[130:131], 0, v[204:205]
	v_lshl_add_u64 v[152:153], v[152:153], 0, v[204:205]
	v_mov_b32_e32 v251, v128
	v_mov_b32_e32 v253, v129
	v_mov_b32_e32 v193, 0
	v_mov_b64_e32 v[194:195], 0
	v_mov_b64_e32 v[136:137], 0
	v_mov_b64_e32 v[138:139], 0
	v_mov_b64_e32 v[128:129], 0
	v_mov_b64_e32 v[130:131], 0
	v_mov_b64_e32 v[132:133], 0
	v_mov_b64_e32 v[134:135], 0
	v_mov_b32_e32 v254, v156
	v_mov_b32_e32 v255, v157
	s_and_saveexec_b64 s[42:43], s[30:31]
	s_cbranch_execz .LBB0_1370
	ds_read_b128 v[132:135], v237 offset:2048
	ds_read_b128 v[136:139], v237 offset:2560
	ds_read_b128 v[128:131], v237 offset:3072
	ds_read_b128 v[192:195], v237 offset:3584
.LBB0_1370:
	s_or_b64 exec, exec, s[42:43]
	s_waitcnt lgkmcnt(0)
	v_mov_b32_dpp v192, v72 row_shr:1 row_mask:0xf bank_mask:0xf
	v_mov_b32_dpp v193, v73 row_shr:1 row_mask:0xf bank_mask:0xf
	v_pk_fma_f32 v[142:143], v[88:89], v[184:185], v[188:189]
	v_mov_b32_dpp v136, v64 row_shr:1 row_mask:0xf bank_mask:0xf
	v_mov_b32_dpp v137, v65 row_shr:1 row_mask:0xf bank_mask:0xf
	v_pk_fma_f32 v[142:143], v[180:181], v[192:193], v[142:143]
	v_mov_b32_dpp v128, v84 row_shr:1 row_mask:0xf bank_mask:0xf
	v_pk_fma_f32 v[136:137], v[176:177], v[136:137], v[142:143]
	v_mov_b32_dpp v129, v85 row_shr:1 row_mask:0xf bank_mask:0xf
	v_exp_f32_e32 v142, v136
	v_exp_f32_e32 v143, v137
	v_pk_fma_f32 v[144:145], v[92:93], v[168:169], v[172:173]
	v_mov_b32_dpp v132, v76 row_shr:1 row_mask:0xf bank_mask:0xf
	v_pk_add_f32 v[142:143], v[142:143], 1.0 op_sel_hi:[1,0]
	v_rcp_f32_e32 v142, v142
	v_rcp_f32_e32 v143, v143
	v_mov_b32_dpp v133, v77 row_shr:1 row_mask:0xf bank_mask:0xf
	v_pk_fma_f32 v[144:145], v[164:165], v[128:129], v[144:145]
	v_mov_b32_dpp v194, v74 row_shr:1 row_mask:0xf bank_mask:0xf
	v_pk_fma_f32 v[132:133], v[160:161], v[132:133], v[144:145]
	v_pk_mul_f32 v[136:137], v[136:137], v[142:143]
	v_mov_b32_dpp v195, v75 row_shr:1 row_mask:0xf bank_mask:0xf
	v_pk_mul_f32 v[132:133], v[132:133], v[136:137]
	v_pk_fma_f32 v[136:137], v[90:91], v[186:187], v[190:191]
	v_mov_b32_dpp v138, v66 row_shr:1 row_mask:0xf bank_mask:0xf
	v_mov_b32_dpp v139, v67 row_shr:1 row_mask:0xf bank_mask:0xf
	v_pk_fma_f32 v[136:137], v[182:183], v[194:195], v[136:137]
	v_mov_b32_dpp v130, v86 row_shr:1 row_mask:0xf bank_mask:0xf
	v_pk_fma_f32 v[136:137], v[178:179], v[138:139], v[136:137]
	v_mov_b32_dpp v131, v87 row_shr:1 row_mask:0xf bank_mask:0xf
	v_exp_f32_e32 v139, v136
	v_exp_f32_e32 v142, v137
	v_cvt_pk_bf16_f32 v138, v132, v133
	v_add_f32_e32 v132, 1.0, v139
	v_rcp_f32_e32 v132, v132
	v_add_f32_e32 v133, 1.0, v142
	v_rcp_f32_e32 v133, v133
	v_pk_fma_f32 v[142:143], v[94:95], v[170:171], v[174:175]
	v_mov_b32_dpp v134, v78 row_shr:1 row_mask:0xf bank_mask:0xf
	v_mov_b32_dpp v135, v79 row_shr:1 row_mask:0xf bank_mask:0xf
	v_pk_mul_f32 v[132:133], v[136:137], v[132:133]
	v_pk_fma_f32 v[136:137], v[68:69], v[184:185], v[188:189]
	v_pk_fma_f32 v[142:143], v[166:167], v[130:131], v[142:143]
	v_pk_fma_f32 v[136:137], v[88:89], v[180:181], v[136:137]
	v_pk_fma_f32 v[134:135], v[162:163], v[134:135], v[142:143]
	v_pk_fma_f32 v[136:137], v[176:177], v[192:193], v[136:137]
	v_add_u32_e32 v146, 0x80, v246
	v_exp_f32_e32 v142, v136
	v_exp_f32_e32 v143, v137
	v_pk_mul_f32 v[132:133], v[134:135], v[132:133]
	v_mov_b64_e32 v[134:135], s[60:61]
	v_cvt_pk_bf16_f32 v139, v132, v133
	v_mad_i64_i32 v[132:133], s[42:43], v146, s82, v[134:135]
	v_lshl_add_u64 v[132:133], v[132:133], 0, v[204:205]
	v_mov_b32_e32 v144, v138
	v_mov_b32_e32 v145, v139
	v_add_f32_e32 v138, 1.0, v142
	v_add_f32_e32 v139, 1.0, v143
	v_rcp_f32_e32 v138, v138
	v_rcp_f32_e32 v139, v139
	v_pk_fma_f32 v[142:143], v[80:81], v[168:169], v[172:173]
	v_pk_fma_f32 v[72:73], v[72:73], v[184:185], v[188:189]
	v_pk_fma_f32 v[142:143], v[92:93], v[164:165], v[142:143]
	v_pk_mul_f32 v[136:137], v[136:137], v[138:139]
	v_pk_fma_f32 v[128:129], v[160:161], v[128:129], v[142:143]
	v_pk_fma_f32 v[84:85], v[84:85], v[168:169], v[172:173]
	v_pk_mul_f32 v[128:129], v[128:129], v[136:137]
	v_pk_fma_f32 v[136:137], v[70:71], v[186:187], v[190:191]
	s_nop 0
	v_pk_fma_f32 v[136:137], v[90:91], v[182:183], v[136:137]
	s_nop 0
	v_pk_fma_f32 v[136:137], v[178:179], v[194:195], v[136:137]
	s_nop 0
	v_exp_f32_e32 v139, v136
	v_exp_f32_e32 v142, v137
	v_cvt_pk_bf16_f32 v138, v128, v129
	v_add_f32_e32 v128, 1.0, v139
	v_rcp_f32_e32 v128, v128
; #define LAS __attribute__((address_space(3)))
; __device__ __forceinline__ float sigmoidf_(float x) { return __builtin_amdgcn_rcpf(1.0f + __expf(-x)); }
;     __device__ __forceinline__ void operator()(AccRef acc, const Unit& u, int wr, int wc, int fr, int fq) const {
;     ...
;                 f32x4 h2v = (f32x4){0.f, 0.f, 0.f, 0.f}, h3v = h2v, h2g = h2v, h3g = h2v;
;                 const int pb = ai * 2 + wr - 1;
;                 if (pb >= 0 && fr == 0) { const LAS float* xp = xch + (pb * 2) * 256 + clb + 4 * n;
;                     h2v = *(const LAS f32x4*)(xp); h3v = *(const LAS f32x4*)(xp + 256); h2g = *(const LAS f32x4*)(xp + 128); h3g = *(const LAS f32x4*)(xp + 256 + 128); }
;                 float o[4][4];
; #pragma unroll
;                 for (int j = 0; j < 4; ++j) {
;                     const float v0 = acc[ai][0][0][n][j], v1 = acc[ai][0][1][n][j], v2 = acc[ai][0][2][n][j], v3 = acc[ai][0][3][n][j];
;                     const float g0 = acc[ai][1][0][n][j], g1 = acc[ai][1][1][n][j], g2 = acc[ai][1][2][n][j], g3 = acc[ai][1][3][n][j];
;                     const float pv3 = dpp_upd<0x111>(h3v[j], v3), pv2 = dpp_upd<0x111>(h2v[j], v2), pg3 = dpp_upd<0x111>(h3g[j], g3), pg2 = dpp_upd<0x111>(h2g[j], g2);
;                     const float hv0 = bvv[j] + w2v[j] * v0 + w1v[j] * pv3 + w0v[j] * pv2, hv1 = bvv[j] + w2v[j] * v1 + w1v[j] * v0 + w0v[j] * pv3;
;                     const float hv2 = bvv[j] + w2v[j] * v2 + w1v[j] * v1 + w0v[j] * v0, hv3 = bvv[j] + w2v[j] * v3 + w1v[j] * v2 + w0v[j] * v1;
;                     const float hg0 = bvg[j] + w2g[j] * g0 + w1g[j] * pg3 + w0g[j] * pg2, hg1 = bvg[j] + w2g[j] * g1 + w1g[j] * g0 + w0g[j] * pg3;
;                     const float hg2 = bvg[j] + w2g[j] * g2 + w1g[j] * g1 + w0g[j] * g0, hg3 = bvg[j] + w2g[j] * g3 + w1g[j] * g2 + w0g[j] * g1;
;                     o[0][j] = hg0 * sigmoidf_(hg0) * hv0; o[1][j] = hg1 * sigmoidf_(hg1) * hv1; o[2][j] = hg2 * sigmoidf_(hg2) * hv2; o[3][j] = hg3 * sigmoidf_(hg3) * hv3; }
; #pragma unroll
;                 for (int m = 0; m < 4; ++m) { u32x2 w; w.x = cvt_pk_bf16(o[m][0], o[m][1]); w.y = cvt_pk_bf16(o[m][2], o[m][3]);
;                     *(u32x2*)(Aout + (size_t)(row0 + ai * 128 + m) * FH + hc0 + 4 * n) = w; } } }
	v_add_f32_e32 v129, 1.0, v142
	v_rcp_f32_e32 v129, v129
	v_pk_fma_f32 v[142:143], v[82:83], v[170:171], v[174:175]
	v_pk_mul_f32 v[128:129], v[136:137], v[128:129]
	v_pk_fma_f32 v[142:143], v[94:95], v[166:167], v[142:143]
	v_pk_fma_f32 v[136:137], v[76:77], v[168:169], v[172:173]
	v_pk_fma_f32 v[130:131], v[162:163], v[130:131], v[142:143]
	v_pk_fma_f32 v[136:137], v[80:81], v[164:165], v[136:137]
	v_pk_mul_f32 v[128:129], v[130:131], v[128:129]
	v_pk_fma_f32 v[130:131], v[64:65], v[184:185], v[188:189]
	v_pk_fma_f32 v[64:65], v[64:65], v[180:181], v[72:73]
	v_pk_fma_f32 v[130:131], v[68:69], v[180:181], v[130:131]
	v_pk_fma_f32 v[64:65], v[68:69], v[176:177], v[64:65]
	v_pk_fma_f32 v[88:89], v[88:89], v[176:177], v[130:131]
	v_pk_fma_f32 v[92:93], v[92:93], v[160:161], v[136:137]
	v_exp_f32_e32 v130, v88
	v_exp_f32_e32 v131, v89
	v_exp_f32_e32 v72, v64
	v_pk_add_f32 v[130:131], v[130:131], 1.0 op_sel_hi:[1,0]
	v_rcp_f32_e32 v130, v130
	v_rcp_f32_e32 v131, v131
	v_pk_fma_f32 v[68:69], v[74:75], v[186:187], v[190:191]
	v_exp_f32_e32 v73, v65
	v_pk_mul_f32 v[88:89], v[88:89], v[130:131]
	v_pk_mul_f32 v[88:89], v[92:93], v[88:89]
	v_pk_fma_f32 v[92:93], v[66:67], v[186:187], v[190:191]
	v_pk_fma_f32 v[66:67], v[66:67], v[182:183], v[68:69]
	v_pk_fma_f32 v[92:93], v[70:71], v[182:183], v[92:93]
	v_pk_fma_f32 v[66:67], v[70:71], v[178:179], v[66:67]
	v_pk_fma_f32 v[90:91], v[90:91], v[178:179], v[92:93]
	v_exp_f32_e32 v93, v90
	v_exp_f32_e32 v68, v66
	v_exp_f32_e32 v69, v67
	v_exp_f32_e32 v130, v91
	v_pk_add_f32 v[72:73], v[72:73], 1.0 op_sel_hi:[1,0]
	v_pk_add_f32 v[68:69], v[68:69], 1.0 op_sel_hi:[1,0]
	v_cvt_pk_bf16_f32 v92, v88, v89
	v_add_f32_e32 v88, 1.0, v93
	v_add_f32_e32 v89, 1.0, v130
	v_rcp_f32_e32 v72, v72
	v_rcp_f32_e32 v73, v73
	v_rcp_f32_e32 v68, v68
	v_rcp_f32_e32 v69, v69
	v_rcp_f32_e32 v88, v88
	v_rcp_f32_e32 v89, v89
	v_pk_fma_f32 v[74:75], v[86:87], v[170:171], v[174:175]
	v_pk_fma_f32 v[130:131], v[78:79], v[170:171], v[174:175]
	v_pk_fma_f32 v[76:77], v[76:77], v[164:165], v[84:85]
	v_pk_fma_f32 v[70:71], v[78:79], v[166:167], v[74:75]
	v_pk_fma_f32 v[130:131], v[82:83], v[166:167], v[130:131]
	v_pk_fma_f32 v[76:77], v[80:81], v[160:161], v[76:77]
	v_pk_mul_f32 v[64:65], v[64:65], v[72:73]
	v_pk_fma_f32 v[70:71], v[82:83], v[162:163], v[70:71]
	v_pk_mul_f32 v[66:67], v[66:67], v[68:69]
	v_pk_fma_f32 v[94:95], v[94:95], v[162:163], v[130:131]
	v_pk_mul_f32 v[88:89], v[90:91], v[88:89]
	v_pk_mul_f32 v[64:65], v[76:77], v[64:65]
	v_pk_mul_f32 v[66:67], v[70:71], v[66:67]
	v_pk_mul_f32 v[88:89], v[94:95], v[88:89]
	v_cvt_pk_bf16_f32 v64, v64, v65
	v_cvt_pk_bf16_f32 v65, v66, v67
	v_add_u32_e32 v66, 0x83, v246
	v_cvt_pk_bf16_f32 v139, v128, v129
	v_add_u32_e32 v128, 0x81, v246
	v_cvt_pk_bf16_f32 v93, v88, v89
	v_add_u32_e32 v88, 0x82, v246
	v_mad_i64_i32 v[66:67], s[42:43], v66, s82, v[134:135]
	v_mad_i64_i32 v[128:129], s[42:43], v128, s82, v[134:135]
	v_mad_i64_i32 v[88:89], s[42:43], v88, s82, v[134:135]
	v_lshl_add_u64 v[82:83], v[66:67], 0, v[204:205]
	v_lshl_add_u64 v[128:129], v[128:129], 0, v[204:205]
	v_lshl_add_u64 v[88:89], v[88:89], 0, v[204:205]
	v_mov_b32_e32 v148, v64
	v_mov_b32_e32 v149, v65
	v_mov_b32_e32 v64, 0
	v_mov_b64_e32 v[70:71], 0
	v_mov_b64_e32 v[72:73], 0
	v_mov_b64_e32 v[78:79], 0
	v_mov_b64_e32 v[80:81], 0
	v_mov_b64_e32 v[66:67], 0
	v_mov_b64_e32 v[68:69], 0
	v_mov_b64_e32 v[74:75], 0
	v_mov_b64_e32 v[76:77], 0
	v_mov_b32_e32 v154, v138
	v_mov_b32_e32 v155, v139
	v_mov_b32_e32 v198, v92
	v_mov_b32_e32 v199, v93
	s_and_saveexec_b64 s[42:43], s[28:29]
	s_cbranch_execz .LBB0_1372
	ds_read_b128 v[74:77], v242
	ds_read_b128 v[66:69], v241
	ds_read_b128 v[78:81], v240
	ds_read_b128 v[70:73], v239
; #define LAS __attribute__((address_space(3)))
;     __device__ __forceinline__ void operator()(AccRef acc, const Unit& u, int wr, int wc, int fr, int fq) const {
;     ...
;         const int hc0 = 128 * u.pn + clb, row0 = u.pm * 256 + wr * 64 + 4 * fr;
; #pragma unroll
;         for (int n = 0; n < 2; ++n) {
;             const f32x4 w0v = cwv[n][0], w1v = cwv[n][1], w2v = cwv[n][2], bvv = cwv[n][3], w0g = cwv[n][4], w1g = cwv[n][5], w2g = cwv[n][6], bvg = cwv[n][7];
; #pragma unroll
;             for (int ai = 0; ai < 2; ++ai) {
;                 if (n == 0 && ai == 0) {
;                     asm volatile("" ::: "memory");
;                     const float* cv = cw + hc0 + 4; const float* cg = cv + FH; const float* bp = cb + hc0 + 4;
;                     cwv[1][0] = *(const f32x4*)(cv); cwv[1][1] = *(const f32x4*)(cv + F2); cwv[1][2] = *(const f32x4*)(cv + 2 * F2); cwv[1][3] = *(const f32x4*)(bp);
;                     cwv[1][4] = *(const f32x4*)(cg); cwv[1][5] = *(const f32x4*)(cg + F2); cwv[1][6] = *(const f32x4*)(cg + 2 * F2); cwv[1][7] = *(const f32x4*)(bp + FH);
;                     asm volatile("" ::: "memory"); }
;                 f32x4 h2v = (f32x4){0.f, 0.f, 0.f, 0.f}, h3v = h2v, h2g = h2v, h3g = h2v;
;                 const int pb = ai * 2 + wr - 1;
;                 if (pb >= 0 && fr == 0) { const LAS float* xp = xch + (pb * 2) * 256 + clb + 4 * n;
;                     h2v = *(const LAS f32x4*)(xp); h3v = *(const LAS f32x4*)(xp + 256); h2g = *(const LAS f32x4*)(xp + 128); h3g = *(const LAS f32x4*)(xp + 256 + 128); }
;                 float o[4][4];
; #pragma unroll
;                 for (int j = 0; j < 4; ++j) {
;                     const float v0 = acc[ai][0][0][n][j], v1 = acc[ai][0][1][n][j], v2 = acc[ai][0][2][n][j], v3 = acc[ai][0][3][n][j];
;                     const float g0 = acc[ai][1][0][n][j], g1 = acc[ai][1][1][n][j], g2 = acc[ai][1][2][n][j], g3 = acc[ai][1][3][n][j];
;                     const float pv3 = dpp_upd<0x111>(h3v[j], v3), pv2 = dpp_upd<0x111>(h2v[j], v2), pg3 = dpp_upd<0x111>(h3g[j], g3), pg2 = dpp_upd<0x111>(h2g[j], g2);
;                     const float hv0 = bvv[j] + w2v[j] * v0 + w1v[j] * pv3 + w0v[j] * pv2, hv1 = bvv[j] + w2v[j] * v1 + w1v[j] * v0 + w0v[j] * pv3;
;                     const float hv2 = bvv[j] + w2v[j] * v2 + w1v[j] * v1 + w0v[j] * v0, hv3 = bvv[j] + w2v[j] * v3 + w1v[j] * v2 + w0v[j] * v1;
.LBB0_1372:
	s_or_b64 exec, exec, s[42:43]
	s_waitcnt lgkmcnt(0)
	v_mov_b32_dpp v70, v44 row_shr:1 row_mask:0xf bank_mask:0xf
	v_mov_b32_dpp v71, v45 row_shr:1 row_mask:0xf bank_mask:0xf
	s_waitcnt vmcnt(0)
	v_pk_fma_f32 v[84:85], v[56:57], v[120:121], v[124:125]
	v_mov_b32_dpp v78, v32 row_shr:1 row_mask:0xf bank_mask:0xf
	v_mov_b32_dpp v79, v33 row_shr:1 row_mask:0xf bank_mask:0xf
	v_pk_fma_f32 v[84:85], v[116:117], v[70:71], v[84:85]
	v_mov_b32_dpp v66, v52 row_shr:1 row_mask:0xf bank_mask:0xf
	v_pk_fma_f32 v[78:79], v[112:113], v[78:79], v[84:85]
	v_mov_b32_dpp v67, v53 row_shr:1 row_mask:0xf bank_mask:0xf
	v_exp_f32_e32 v84, v78
	v_exp_f32_e32 v85, v79
	v_pk_fma_f32 v[86:87], v[60:61], v[104:105], v[108:109]
	v_pk_add_f32 v[84:85], v[84:85], 1.0 op_sel_hi:[1,0]
	v_rcp_f32_e32 v84, v84
	v_rcp_f32_e32 v85, v85
	v_mov_b32_dpp v74, v40 row_shr:1 row_mask:0xf bank_mask:0xf
	v_mov_b32_dpp v75, v41 row_shr:1 row_mask:0xf bank_mask:0xf
	v_pk_fma_f32 v[86:87], v[100:101], v[66:67], v[86:87]
	v_pk_mul_f32 v[78:79], v[78:79], v[84:85]
	v_pk_fma_f32 v[74:75], v[96:97], v[74:75], v[86:87]
	v_mov_b32_dpp v72, v46 row_shr:1 row_mask:0xf bank_mask:0xf
	v_mov_b32_dpp v73, v47 row_shr:1 row_mask:0xf bank_mask:0xf
	v_pk_mul_f32 v[74:75], v[74:75], v[78:79]
	v_pk_fma_f32 v[78:79], v[58:59], v[122:123], v[126:127]
	v_mov_b32_dpp v80, v34 row_shr:1 row_mask:0xf bank_mask:0xf
	v_mov_b32_dpp v81, v35 row_shr:1 row_mask:0xf bank_mask:0xf
	v_pk_fma_f32 v[78:79], v[118:119], v[72:73], v[78:79]
	v_mov_b32_dpp v68, v54 row_shr:1 row_mask:0xf bank_mask:0xf
	v_pk_fma_f32 v[78:79], v[114:115], v[80:81], v[78:79]
	v_mov_b32_dpp v69, v55 row_shr:1 row_mask:0xf bank_mask:0xf
	v_exp_f32_e32 v80, v78
	v_exp_f32_e32 v81, v79
	v_pk_fma_f32 v[84:85], v[62:63], v[106:107], v[110:111]
	v_pk_add_f32 v[80:81], v[80:81], 1.0 op_sel_hi:[1,0]
	v_rcp_f32_e32 v80, v80
	v_rcp_f32_e32 v81, v81
	v_mov_b32_dpp v76, v42 row_shr:1 row_mask:0xf bank_mask:0xf
	v_mov_b32_dpp v77, v43 row_shr:1 row_mask:0xf bank_mask:0xf
	v_pk_fma_f32 v[84:85], v[102:103], v[68:69], v[84:85]
	v_pk_mul_f32 v[78:79], v[78:79], v[80:81]
	v_pk_fma_f32 v[76:77], v[98:99], v[76:77], v[84:85]
	v_cvt_pk_bf16_f32 v74, v74, v75
	v_pk_mul_f32 v[76:77], v[76:77], v[78:79]
	v_pk_fma_f32 v[44:45], v[44:45], v[120:121], v[124:125]
	v_cvt_pk_bf16_f32 v75, v76, v77
	v_pk_fma_f32 v[76:77], v[36:37], v[120:121], v[124:125]
	v_mov_b32_e32 v90, v247
	v_mov_b32_e32 v91, v248
	v_mov_b32_e32 v92, v74
	v_mov_b32_e32 v93, v75
	global_store_dwordx4 v[202:203], v[90:93], off
	v_pk_fma_f32 v[76:77], v[56:57], v[116:117], v[76:77]
	v_pk_fma_f32 v[52:53], v[52:53], v[104:105], v[108:109]
	v_pk_fma_f32 v[70:71], v[112:113], v[70:71], v[76:77]
	s_nop 0
	v_exp_f32_e32 v74, v70
	v_exp_f32_e32 v75, v71
	s_nop 0
	v_pk_add_f32 v[74:75], v[74:75], 1.0 op_sel_hi:[1,0]
	v_rcp_f32_e32 v74, v74
	v_rcp_f32_e32 v75, v75
	v_pk_fma_f32 v[76:77], v[48:49], v[104:105], v[108:109]
	v_pk_mul_f32 v[70:71], v[70:71], v[74:75]
	v_pk_fma_f32 v[76:77], v[60:61], v[100:101], v[76:77]
	v_pk_fma_f32 v[74:75], v[50:51], v[106:107], v[110:111]
	v_pk_fma_f32 v[66:67], v[96:97], v[66:67], v[76:77]
	v_pk_fma_f32 v[74:75], v[62:63], v[102:103], v[74:75]
	v_pk_mul_f32 v[66:67], v[66:67], v[70:71]
	v_pk_fma_f32 v[70:71], v[38:39], v[122:123], v[126:127]
	v_pk_fma_f32 v[68:69], v[98:99], v[68:69], v[74:75]
	v_pk_fma_f32 v[70:71], v[58:59], v[118:119], v[70:71]
	v_cvt_pk_bf16_f32 v66, v66, v67
	v_pk_fma_f32 v[70:71], v[114:115], v[72:73], v[70:71]
	s_nop 0
	v_exp_f32_e32 v72, v70
	v_exp_f32_e32 v73, v71
	s_nop 0
	v_pk_add_f32 v[72:73], v[72:73], 1.0 op_sel_hi:[1,0]
	v_rcp_f32_e32 v72, v72
	v_rcp_f32_e32 v73, v73
	s_nop 0
	v_pk_mul_f32 v[70:71], v[70:71], v[72:73]
	s_nop 0
	v_pk_mul_f32 v[68:69], v[68:69], v[70:71]
	s_nop 0
	v_cvt_pk_bf16_f32 v67, v68, v69
	v_pk_fma_f32 v[68:69], v[32:33], v[120:121], v[124:125]
	v_mov_b32_e32 v134, v249
	v_mov_b32_e32 v135, v250
	v_mov_b32_e32 v136, v66
	v_mov_b32_e32 v137, v67
	global_store_dwordx4 v[196:197], v[134:137], off
	v_pk_fma_f32 v[68:69], v[36:37], v[116:117], v[68:69]
	v_pk_fma_f32 v[32:33], v[32:33], v[116:117], v[44:45]
	v_pk_fma_f32 v[56:57], v[56:57], v[112:113], v[68:69]
	v_pk_fma_f32 v[32:33], v[36:37], v[112:113], v[32:33]
	v_exp_f32_e32 v66, v56
	v_exp_f32_e32 v67, v57
	s_nop 0
	v_pk_add_f32 v[66:67], v[66:67], 1.0 op_sel_hi:[1,0]
	v_rcp_f32_e32 v66, v66
	v_rcp_f32_e32 v67, v67
	v_pk_fma_f32 v[68:69], v[40:41], v[104:105], v[108:109]
	v_exp_f32_e32 v44, v32
	v_pk_fma_f32 v[68:69], v[48:49], v[100:101], v[68:69]
	v_pk_mul_f32 v[56:57], v[56:57], v[66:67]
	v_pk_fma_f32 v[60:61], v[60:61], v[96:97], v[68:69]
	v_pk_fma_f32 v[36:37], v[46:47], v[122:123], v[126:127]
	v_pk_mul_f32 v[56:57], v[60:61], v[56:57]
	v_pk_fma_f32 v[60:61], v[34:35], v[122:123], v[126:127]
	v_pk_fma_f32 v[34:35], v[34:35], v[118:119], v[36:37]
	v_pk_fma_f32 v[60:61], v[38:39], v[118:119], v[60:61]
	v_pk_fma_f32 v[34:35], v[38:39], v[114:115], v[34:35]
	v_pk_fma_f32 v[58:59], v[58:59], v[114:115], v[60:61]
	v_exp_f32_e32 v60, v58
	v_exp_f32_e32 v45, v33
	v_exp_f32_e32 v36, v34
	v_exp_f32_e32 v37, v35
	v_exp_f32_e32 v61, v59
	v_cvt_pk_bf16_f32 v56, v56, v57
	v_pk_add_f32 v[44:45], v[44:45], 1.0 op_sel_hi:[1,0]
	v_pk_add_f32 v[36:37], v[36:37], 1.0 op_sel_hi:[1,0]
	v_pk_add_f32 v[60:61], v[60:61], 1.0 op_sel_hi:[1,0]
	v_rcp_f32_e32 v44, v44
	v_rcp_f32_e32 v45, v45
	v_rcp_f32_e32 v36, v36
	v_rcp_f32_e32 v37, v37
	v_rcp_f32_e32 v60, v60
	v_rcp_f32_e32 v61, v61
	v_pk_fma_f32 v[46:47], v[54:55], v[106:107], v[110:111]
	v_pk_fma_f32 v[66:67], v[42:43], v[106:107], v[110:111]
	v_pk_fma_f32 v[40:41], v[40:41], v[100:101], v[52:53]
	v_pk_fma_f32 v[38:39], v[42:43], v[102:103], v[46:47]
	v_pk_fma_f32 v[66:67], v[50:51], v[102:103], v[66:67]
	v_pk_fma_f32 v[40:41], v[48:49], v[96:97], v[40:41]
	v_pk_mul_f32 v[32:33], v[32:33], v[44:45]
	v_pk_fma_f32 v[38:39], v[50:51], v[98:99], v[38:39]
	v_pk_mul_f32 v[34:35], v[34:35], v[36:37]
	v_pk_fma_f32 v[62:63], v[62:63], v[98:99], v[66:67]
	v_pk_mul_f32 v[58:59], v[58:59], v[60:61]
	v_pk_mul_f32 v[32:33], v[40:41], v[32:33]
	v_pk_mul_f32 v[34:35], v[38:39], v[34:35]
	v_pk_mul_f32 v[58:59], v[62:63], v[58:59]
	v_cvt_pk_bf16_f32 v32, v32, v33
	v_cvt_pk_bf16_f32 v33, v34, v35
	v_cvt_pk_bf16_f32 v57, v58, v59
	v_mov_b32_e32 v158, v251
	v_mov_b32_e32 v159, v253
	v_mov_b32_e32 v160, v32
	v_mov_b32_e32 v161, v33
	global_store_dwordx4 v[140:141], v[158:161], off
	v_mov_b32_e32 v65, 0
	v_mov_b64_e32 v[66:67], 0
	v_mov_b64_e32 v[40:41], 0
	v_mov_b64_e32 v[42:43], 0
	v_mov_b64_e32 v[32:33], 0
	v_mov_b64_e32 v[34:35], 0
	v_mov_b64_e32 v[36:37], 0
	v_mov_b64_e32 v[38:39], 0
	v_mov_b32_e32 v162, v254
	v_mov_b32_e32 v163, v255
	v_mov_b32_e32 v164, v56
	v_mov_b32_e32 v165, v57
	global_store_dwordx4 v[152:153], v[162:165], off
	s_and_saveexec_b64 s[42:43], s[30:31]
	s_cbranch_execz .LBB0_1355
	ds_read_b128 v[36:39], v237 offset:2064
	ds_read_b128 v[40:43], v237 offset:2576
	ds_read_b128 v[32:35], v237 offset:3088
	ds_read_b128 v[64:67], v237 offset:3600
	s_branch .LBB0_1355

;     __device__ __forceinline__ void operator()(AccRef acc, const Unit& u, int wr, int wc, int fr, int fq) const {
;     ...
;         float* rawu = raw + (size_t)(u.pm * 22 + u.pn) * 1024;
;         if (wr == 0 && fr == 0) {
; #pragma unroll
;             for (int bj = 0; bj < 2; ++bj)
; #pragma unroll
;                 for (int n = 0; n < 2; ++n) { *(f32x4*)(rawu + 0 * 256 + bj * 128 + clb + 4 * n) = acc[0][bj][0][n]; *(f32x4*)(rawu + 1 * 256 + bj * 128 + clb + 4 * n) = acc[0][bj][1][n]; }
;         }
;         if (wr == 1 && fr == 15) {
; #pragma unroll
;             for (int bj = 0; bj < 2; ++bj)
; #pragma unroll
;                 for (int n = 0; n < 2; ++n) { *(f32x4*)(rawu + 2 * 256 + bj * 128 + clb + 4 * n) = acc[1][bj][2][n]; *(f32x4*)(rawu + 3 * 256 + bj * 128 + clb + 4 * n) = acc[1][bj][3][n]; }
;         }
;         asm volatile("s_waitcnt lgkmcnt(0)" ::: "memory"); __builtin_amdgcn_s_barrier(); __builtin_amdgcn_s_barrier(); asm volatile("" ::: "memory");
;         const int hc0 = 128 * u.pn + clb, row0 = u.pm * 256 + wr * 64 + 4 * fr;
; #pragma unroll
;         for (int n = 0; n < 2; ++n) {
;             const f32x4 w0v = cwv[n][0], w1v = cwv[n][1], w2v = cwv[n][2], bvv = cwv[n][3], w0g = cwv[n][4], w1g = cwv[n][5], w2g = cwv[n][6], bvg = cwv[n][7];
; #pragma unroll
;             for (int ai = 0; ai < 2; ++ai) {
;                 if (n == 0 && ai == 0) {
;                     asm volatile("" ::: "memory");
;                     const float* cv = cw + hc0 + 4; const float* cg = cv + FH; const float* bp = cb + hc0 + 4;
;                     cwv[1][0] = *(const f32x4*)(cv); cwv[1][1] = *(const f32x4*)(cv + F2); cwv[1][2] = *(const f32x4*)(cv + 2 * F2); cwv[1][3] = *(const f32x4*)(bp);
;                     cwv[1][4] = *(const f32x4*)(cg); cwv[1][5] = *(const f32x4*)(cg + F2); cwv[1][6] = *(const f32x4*)(cg + 2 * F2); cwv[1][7] = *(const f32x4*)(bp + FH);
;                     asm volatile("" ::: "memory"); }
;                 f32x4 h2v = (f32x4){0.f, 0.f, 0.f, 0.f}, h3v = h2v, h2g = h2v, h3g = h2v;
;                 const int pb = ai * 2 + wr - 1;
;                 if (pb >= 0 && fr == 0) { const LAS float* xp = xch + (pb * 2) * 256 + clb + 4 * n;
;                     h2v = *(const LAS f32x4*)(xp); h3v = *(const LAS f32x4*)(xp + 256); h2g = *(const LAS f32x4*)(xp + 128); h3g = *(const LAS f32x4*)(xp + 256 + 128); }
.LBB0_1943:
	s_or_b64 exec, exec, s[38:39]
	s_mul_i32 s25, s34, 22
	s_add_i32 s38, s25, s35
	s_ashr_i32 s39, s38, 31
	s_lshl_b64 s[38:39], s[38:39], 12
	s_add_u32 s38, s64, s38
	s_addc_u32 s39, s65, s39
	v_lshlrev_b32_e32 v96, 2, v218
	v_or_b32_e32 v232, s36, v218
	v_ashrrev_i32_e32 v233, 31, v232
	v_lshlrev_b64 v[96:97], 2, v[232:233]
	v_lshl_add_u64 v[120:121], s[12:13], 0, v[96:97]
	v_add_co_u32_e32 v100, vcc, 0x5000, v120
	s_waitcnt lgkmcnt(0)
	s_barrier
	s_nop 0
	v_addc_co_u32_e32 v101, vcc, 0, v121, vcc
	v_add_co_u32_e32 v104, vcc, 0xb000, v120
	s_barrier
	s_nop 0
	v_addc_co_u32_e32 v105, vcc, 0, v121, vcc
	v_add_co_u32_e32 v112, vcc, s49, v120
	v_lshl_add_u64 v[124:125], s[14:15], 0, v[96:97]
	s_nop 0
	v_addc_co_u32_e32 v113, vcc, 0, v121, vcc
	v_add_co_u32_e32 v116, vcc, 0x8000, v120
	s_nop 0
	s_nop 0
	v_addc_co_u32_e32 v117, vcc, 0, v121, vcc
	v_add_co_u32_e32 v120, vcc, 0xd000, v120
	s_nop 0
	s_nop 0
	v_addc_co_u32_e32 v121, vcc, 0, v121, vcc
	v_add_co_u32_e32 v124, vcc, 0x2000, v124
	s_nop 0
	s_nop 0
	v_addc_co_u32_e32 v125, vcc, 0, v125, vcc
	v_mov_b32_e32 v192, 0
	v_mov_b64_e32 v[198:199], 0
	v_mov_b64_e32 v[200:201], 0
	v_mov_b64_e32 v[206:207], 0
	v_mov_b64_e32 v[208:209], 0
	v_mov_b64_e32 v[194:195], 0
	v_mov_b64_e32 v[196:197], 0
	v_mov_b64_e32 v[202:203], 0
	v_mov_b64_e32 v[204:205], 0
	s_and_saveexec_b64 s[36:37], s[20:21]
	s_cbranch_execz .LBB0_1949
	ds_read_b128 v[202:205], v237
	ds_read_b128 v[206:209], v237 offset:512
	ds_read_b128 v[194:197], v237 offset:1024
	ds_read_b128 v[198:201], v237 offset:1536

; __device__ __forceinline__ float sigmoidf_(float x) { return __builtin_amdgcn_rcpf(1.0f + __expf(-x)); }
;     __device__ __forceinline__ void operator()(AccRef acc, const Unit& u, int wr, int wc, int fr, int fq) const {
;     ...
;                 float o[4][4];
; #pragma unroll
;                 for (int j = 0; j < 4; ++j) {
;                     const float v0 = acc[ai][0][0][n][j], v1 = acc[ai][0][1][n][j], v2 = acc[ai][0][2][n][j], v3 = acc[ai][0][3][n][j];
;                     const float g0 = acc[ai][1][0][n][j], g1 = acc[ai][1][1][n][j], g2 = acc[ai][1][2][n][j], g3 = acc[ai][1][3][n][j];
;                     const float pv3 = dpp_upd<0x111>(h3v[j], v3), pv2 = dpp_upd<0x111>(h2v[j], v2), pg3 = dpp_upd<0x111>(h3g[j], g3), pg2 = dpp_upd<0x111>(h2g[j], g2);
;                     const float hv0 = bvv[j] + w2v[j] * v0 + w1v[j] * pv3 + w0v[j] * pv2, hv1 = bvv[j] + w2v[j] * v1 + w1v[j] * v0 + w0v[j] * pv3;
;                     const float hv2 = bvv[j] + w2v[j] * v2 + w1v[j] * v1 + w0v[j] * v0, hv3 = bvv[j] + w2v[j] * v3 + w1v[j] * v2 + w0v[j] * v1;
;                     const float hg0 = bvg[j] + w2g[j] * g0 + w1g[j] * pg3 + w0g[j] * pg2, hg1 = bvg[j] + w2g[j] * g1 + w1g[j] * g0 + w0g[j] * pg3;
;                     const float hg2 = bvg[j] + w2g[j] * g2 + w1g[j] * g1 + w0g[j] * g0, hg3 = bvg[j] + w2g[j] * g3 + w1g[j] * g2 + w0g[j] * g1;
;                     o[0][j] = hg0 * sigmoidf_(hg0) * hv0; o[1][j] = hg1 * sigmoidf_(hg1) * hv1; o[2][j] = hg2 * sigmoidf_(hg2) * hv2; o[3][j] = hg3 * sigmoidf_(hg3) * hv3; }
; #pragma unroll
;                 for (int m = 0; m < 4; ++m) { u32x2 w; w.x = cvt_pk_bf16(o[m][0], o[m][1]); w.y = cvt_pk_bf16(o[m][2], o[m][3]);
;                     *(u32x2*)(Aout + (size_t)(row0 + ai * 128 + m) * FH + hc0 + 4 * n) = w; } } }
.LBB0_1947:
	s_or_b64 exec, exec, s[40:41]
	v_pk_fma_f32 v[246:247], v[152:153], v[184:185], v[188:189]
	v_mov_b32_dpp v206, v128 row_shr:1 row_mask:0xf bank_mask:0xf
	v_mov_b32_dpp v207, v129 row_shr:1 row_mask:0xf bank_mask:0xf
	v_pk_fma_f32 v[246:247], v[180:181], v[198:199], v[246:247]
	v_mov_b32_dpp v194, v148 row_shr:1 row_mask:0xf bank_mask:0xf
	v_pk_fma_f32 v[206:207], v[176:177], v[206:207], v[246:247]
	v_mov_b32_dpp v195, v149 row_shr:1 row_mask:0xf bank_mask:0xf
	v_exp_f32_e32 v246, v206
	v_exp_f32_e32 v247, v207
	v_pk_fma_f32 v[248:249], v[156:157], v[168:169], v[172:173]
	v_pk_add_f32 v[246:247], v[246:247], 1.0 op_sel_hi:[1,0]
	v_rcp_f32_e32 v246, v246
	v_rcp_f32_e32 v247, v247
	v_mov_b32_dpp v202, v136 row_shr:1 row_mask:0xf bank_mask:0xf
	v_mov_b32_dpp v203, v137 row_shr:1 row_mask:0xf bank_mask:0xf
	v_pk_fma_f32 v[248:249], v[164:165], v[194:195], v[248:249]
	v_pk_mul_f32 v[206:207], v[206:207], v[246:247]
	v_pk_fma_f32 v[202:203], v[160:161], v[202:203], v[248:249]
	v_mov_b32_dpp v200, v142 row_shr:1 row_mask:0xf bank_mask:0xf
	v_mov_b32_dpp v201, v143 row_shr:1 row_mask:0xf bank_mask:0xf
	v_pk_mul_f32 v[202:203], v[202:203], v[206:207]
	v_pk_fma_f32 v[206:207], v[154:155], v[186:187], v[190:191]
	v_mov_b32_dpp v208, v130 row_shr:1 row_mask:0xf bank_mask:0xf
	v_mov_b32_dpp v209, v131 row_shr:1 row_mask:0xf bank_mask:0xf
	v_pk_fma_f32 v[206:207], v[182:183], v[200:201], v[206:207]
	v_mov_b32_dpp v196, v150 row_shr:1 row_mask:0xf bank_mask:0xf
	v_pk_fma_f32 v[206:207], v[178:179], v[208:209], v[206:207]
	v_mov_b32_dpp v197, v151 row_shr:1 row_mask:0xf bank_mask:0xf
	v_exp_f32_e32 v193, v206
	v_exp_f32_e32 v209, v207
	v_cvt_pk_bf16_f32 v208, v202, v203
	v_add_f32_e32 v193, 1.0, v193
	v_rcp_f32_e32 v202, v193
	v_add_f32_e32 v193, 1.0, v209
	v_rcp_f32_e32 v203, v193
	v_pk_fma_f32 v[246:247], v[158:159], v[170:171], v[174:175]
	v_mov_b32_dpp v204, v138 row_shr:1 row_mask:0xf bank_mask:0xf
	v_mov_b32_dpp v205, v139 row_shr:1 row_mask:0xf bank_mask:0xf
	v_pk_fma_f32 v[246:247], v[166:167], v[196:197], v[246:247]
	v_pk_mul_f32 v[202:203], v[206:207], v[202:203]
	v_pk_fma_f32 v[204:205], v[162:163], v[204:205], v[246:247]
	v_lshl_add_u32 v245, s34, 8, v235
	v_pk_mul_f32 v[202:203], v[204:205], v[202:203]
	v_lshlrev_b64 v[204:205], 1, v[232:233]
	v_pk_fma_f32 v[232:233], v[132:133], v[184:185], v[188:189]
	v_mov_b64_e32 v[206:207], s[60:61]
	v_pk_fma_f32 v[232:233], v[152:153], v[180:181], v[232:233]
	v_cvt_pk_bf16_f32 v209, v202, v203
	v_pk_fma_f32 v[198:199], v[176:177], v[198:199], v[232:233]
	v_mad_i64_i32 v[202:203], s[34:35], v245, s63, v[206:207]
	v_exp_f32_e32 v193, v198
	v_exp_f32_e32 v232, v199
	v_lshl_add_u64 v[202:203], v[202:203], 0, v[204:205]
	v_add_f32_e32 v193, 1.0, v193
	v_mov_b32_e32 v246, v208
	v_mov_b32_e32 v247, v209
	v_rcp_f32_e32 v208, v193
	v_add_f32_e32 v193, 1.0, v232
	v_rcp_f32_e32 v209, v193
	v_pk_fma_f32 v[232:233], v[144:145], v[168:169], v[172:173]
	v_pk_fma_f32 v[140:141], v[140:141], v[184:185], v[188:189]
	v_pk_fma_f32 v[232:233], v[156:157], v[164:165], v[232:233]
	v_pk_mul_f32 v[198:199], v[198:199], v[208:209]
	v_pk_fma_f32 v[194:195], v[160:161], v[194:195], v[232:233]
	v_pk_fma_f32 v[208:209], v[146:147], v[170:171], v[174:175]
	v_pk_mul_f32 v[194:195], v[194:195], v[198:199]
	v_pk_fma_f32 v[198:199], v[134:135], v[186:187], v[190:191]
	v_pk_fma_f32 v[208:209], v[158:159], v[166:167], v[208:209]
	v_pk_fma_f32 v[198:199], v[154:155], v[182:183], v[198:199]
	v_pk_fma_f32 v[196:197], v[162:163], v[196:197], v[208:209]
	v_pk_fma_f32 v[198:199], v[178:179], v[200:201], v[198:199]
	v_cvt_pk_bf16_f32 v194, v194, v195
	v_exp_f32_e32 v200, v198
	v_exp_f32_e32 v201, v199
	v_pk_fma_f32 v[148:149], v[148:149], v[168:169], v[172:173]
	v_pk_add_f32 v[200:201], v[200:201], 1.0 op_sel_hi:[1,0]
	v_rcp_f32_e32 v200, v200
	v_rcp_f32_e32 v201, v201
	v_or_b32_e32 v193, 1, v245
	v_pk_mul_f32 v[198:199], v[198:199], v[200:201]
	s_nop 0
	v_pk_mul_f32 v[196:197], v[196:197], v[198:199]
	v_pk_fma_f32 v[198:199], v[128:129], v[184:185], v[188:189]
	v_cvt_pk_bf16_f32 v195, v196, v197
	v_pk_fma_f32 v[198:199], v[132:133], v[180:181], v[198:199]
	v_mad_i64_i32 v[196:197], s[34:35], v193, s63, v[206:207]
	v_pk_fma_f32 v[152:153], v[152:153], v[176:177], v[198:199]
	v_lshl_add_u64 v[196:197], v[196:197], 0, v[204:205]
	v_exp_f32_e32 v193, v152
	v_exp_f32_e32 v198, v153
	v_mov_b32_e32 v248, v194
	v_mov_b32_e32 v249, v195
	v_add_f32_e32 v193, 1.0, v193
	v_rcp_f32_e32 v194, v193
	v_add_f32_e32 v193, 1.0, v198
	v_rcp_f32_e32 v195, v193
	v_pk_fma_f32 v[198:199], v[136:137], v[168:169], v[172:173]
	v_pk_fma_f32 v[128:129], v[128:129], v[180:181], v[140:141]
	v_pk_fma_f32 v[198:199], v[144:145], v[164:165], v[198:199]
	v_pk_fma_f32 v[128:129], v[132:133], v[176:177], v[128:129]
	v_pk_fma_f32 v[156:157], v[156:157], v[160:161], v[198:199]
	v_pk_mul_f32 v[152:153], v[152:153], v[194:195]
	v_pk_mul_f32 v[152:153], v[156:157], v[152:153]
	v_pk_fma_f32 v[156:157], v[130:131], v[186:187], v[190:191]
	v_exp_f32_e32 v140, v128
	v_pk_fma_f32 v[132:133], v[142:143], v[186:187], v[190:191]
	v_pk_fma_f32 v[156:157], v[134:135], v[182:183], v[156:157]
	v_pk_fma_f32 v[130:131], v[130:131], v[182:183], v[132:133]
	v_pk_fma_f32 v[154:155], v[154:155], v[178:179], v[156:157]
	v_pk_fma_f32 v[130:131], v[134:135], v[178:179], v[130:131]
	v_exp_f32_e32 v157, v154
	v_exp_f32_e32 v141, v129
	v_exp_f32_e32 v132, v130
	v_exp_f32_e32 v133, v131
	v_exp_f32_e32 v193, v155
	v_pk_add_f32 v[140:141], v[140:141], 1.0 op_sel_hi:[1,0]
	v_pk_add_f32 v[132:133], v[132:133], 1.0 op_sel_hi:[1,0]
	v_cvt_pk_bf16_f32 v156, v152, v153
	v_add_f32_e32 v152, 1.0, v157
; #define LAS __attribute__((address_space(3)))
; __device__ __forceinline__ float sigmoidf_(float x) { return __builtin_amdgcn_rcpf(1.0f + __expf(-x)); }
;     __device__ __forceinline__ void operator()(AccRef acc, const Unit& u, int wr, int wc, int fr, int fq) const {
;     ...
;                 f32x4 h2v = (f32x4){0.f, 0.f, 0.f, 0.f}, h3v = h2v, h2g = h2v, h3g = h2v;
;                 const int pb = ai * 2 + wr - 1;
;                 if (pb >= 0 && fr == 0) { const LAS float* xp = xch + (pb * 2) * 256 + clb + 4 * n;
;                     h2v = *(const LAS f32x4*)(xp); h3v = *(const LAS f32x4*)(xp + 256); h2g = *(const LAS f32x4*)(xp + 128); h3g = *(const LAS f32x4*)(xp + 256 + 128); }
;                 float o[4][4];
; #pragma unroll
;                 for (int j = 0; j < 4; ++j) {
;                     const float v0 = acc[ai][0][0][n][j], v1 = acc[ai][0][1][n][j], v2 = acc[ai][0][2][n][j], v3 = acc[ai][0][3][n][j];
;                     const float g0 = acc[ai][1][0][n][j], g1 = acc[ai][1][1][n][j], g2 = acc[ai][1][2][n][j], g3 = acc[ai][1][3][n][j];
;                     const float pv3 = dpp_upd<0x111>(h3v[j], v3), pv2 = dpp_upd<0x111>(h2v[j], v2), pg3 = dpp_upd<0x111>(h3g[j], g3), pg2 = dpp_upd<0x111>(h2g[j], g2);
;                     const float hv0 = bvv[j] + w2v[j] * v0 + w1v[j] * pv3 + w0v[j] * pv2, hv1 = bvv[j] + w2v[j] * v1 + w1v[j] * v0 + w0v[j] * pv3;
;                     const float hv2 = bvv[j] + w2v[j] * v2 + w1v[j] * v1 + w0v[j] * v0, hv3 = bvv[j] + w2v[j] * v3 + w1v[j] * v2 + w0v[j] * v1;
;                     const float hg0 = bvg[j] + w2g[j] * g0 + w1g[j] * pg3 + w0g[j] * pg2, hg1 = bvg[j] + w2g[j] * g1 + w1g[j] * g0 + w0g[j] * pg3;
;                     const float hg2 = bvg[j] + w2g[j] * g2 + w1g[j] * g1 + w0g[j] * g0, hg3 = bvg[j] + w2g[j] * g3 + w1g[j] * g2 + w0g[j] * g1;
;                     o[0][j] = hg0 * sigmoidf_(hg0) * hv0; o[1][j] = hg1 * sigmoidf_(hg1) * hv1; o[2][j] = hg2 * sigmoidf_(hg2) * hv2; o[3][j] = hg3 * sigmoidf_(hg3) * hv3; }
; #pragma unroll
;                 for (int m = 0; m < 4; ++m) { u32x2 w; w.x = cvt_pk_bf16(o[m][0], o[m][1]); w.y = cvt_pk_bf16(o[m][2], o[m][3]);
;                     *(u32x2*)(Aout + (size_t)(row0 + ai * 128 + m) * FH + hc0 + 4 * n) = w; } } }
	v_add_f32_e32 v153, 1.0, v193
	v_rcp_f32_e32 v140, v140
	v_rcp_f32_e32 v141, v141
	v_rcp_f32_e32 v132, v132
	v_rcp_f32_e32 v133, v133
	v_rcp_f32_e32 v152, v152
	v_rcp_f32_e32 v153, v153
	v_pk_fma_f32 v[142:143], v[150:151], v[170:171], v[174:175]
	v_pk_fma_f32 v[194:195], v[138:139], v[170:171], v[174:175]
	v_pk_fma_f32 v[136:137], v[136:137], v[164:165], v[148:149]
	v_pk_fma_f32 v[134:135], v[138:139], v[166:167], v[142:143]
	v_pk_fma_f32 v[194:195], v[146:147], v[166:167], v[194:195]
	v_pk_fma_f32 v[136:137], v[144:145], v[160:161], v[136:137]
	v_pk_mul_f32 v[128:129], v[128:129], v[140:141]
	v_pk_fma_f32 v[134:135], v[146:147], v[162:163], v[134:135]
	v_pk_mul_f32 v[130:131], v[130:131], v[132:133]
	v_pk_fma_f32 v[158:159], v[158:159], v[162:163], v[194:195]
	v_pk_mul_f32 v[152:153], v[154:155], v[152:153]
	v_pk_mul_f32 v[128:129], v[136:137], v[128:129]
	v_pk_mul_f32 v[130:131], v[134:135], v[130:131]
	v_pk_mul_f32 v[152:153], v[158:159], v[152:153]
	v_cvt_pk_bf16_f32 v128, v128, v129
	v_cvt_pk_bf16_f32 v129, v130, v131
	v_or_b32_e32 v130, 3, v245
	v_cvt_pk_bf16_f32 v157, v152, v153
	v_or_b32_e32 v152, 2, v245
	v_mad_i64_i32 v[130:131], s[34:35], v130, s63, v[206:207]
	v_mad_i64_i32 v[152:153], s[34:35], v152, s63, v[206:207]
	v_lshl_add_u64 v[140:141], v[130:131], 0, v[204:205]
	v_lshl_add_u64 v[152:153], v[152:153], 0, v[204:205]
	v_mov_b32_e32 v250, v128
	v_mov_b32_e32 v251, v129
	v_mov_b32_e32 v193, 0
	v_mov_b64_e32 v[194:195], 0
	v_mov_b64_e32 v[136:137], 0
	v_mov_b64_e32 v[138:139], 0
	v_mov_b64_e32 v[128:129], 0
	v_mov_b64_e32 v[130:131], 0
	v_mov_b64_e32 v[132:133], 0
	v_mov_b64_e32 v[134:135], 0
	v_mov_b32_e32 v253, v156
	v_mov_b32_e32 v254, v157
	s_and_saveexec_b64 s[34:35], s[22:23]
	s_cbranch_execz .LBB0_1951
	ds_read_b128 v[132:135], v236 offset:2048
	ds_read_b128 v[136:139], v236 offset:2560
	ds_read_b128 v[128:131], v236 offset:3072
	ds_read_b128 v[192:195], v236 offset:3584
.LBB0_1951:
	s_or_b64 exec, exec, s[34:35]
	s_waitcnt lgkmcnt(0)
	v_mov_b32_dpp v192, v72 row_shr:1 row_mask:0xf bank_mask:0xf
	v_mov_b32_dpp v193, v73 row_shr:1 row_mask:0xf bank_mask:0xf
	v_pk_fma_f32 v[142:143], v[88:89], v[184:185], v[188:189]
	v_mov_b32_dpp v136, v64 row_shr:1 row_mask:0xf bank_mask:0xf
	v_mov_b32_dpp v137, v65 row_shr:1 row_mask:0xf bank_mask:0xf
	v_pk_fma_f32 v[142:143], v[180:181], v[192:193], v[142:143]
	v_mov_b32_dpp v128, v84 row_shr:1 row_mask:0xf bank_mask:0xf
	v_pk_fma_f32 v[136:137], v[176:177], v[136:137], v[142:143]
	v_mov_b32_dpp v129, v85 row_shr:1 row_mask:0xf bank_mask:0xf
	v_exp_f32_e32 v142, v136
	v_exp_f32_e32 v143, v137
	v_pk_fma_f32 v[144:145], v[92:93], v[168:169], v[172:173]
	v_mov_b32_dpp v132, v76 row_shr:1 row_mask:0xf bank_mask:0xf
	v_pk_add_f32 v[142:143], v[142:143], 1.0 op_sel_hi:[1,0]
	v_rcp_f32_e32 v142, v142
	v_rcp_f32_e32 v143, v143
	v_mov_b32_dpp v133, v77 row_shr:1 row_mask:0xf bank_mask:0xf
	v_pk_fma_f32 v[144:145], v[164:165], v[128:129], v[144:145]
	v_mov_b32_dpp v194, v74 row_shr:1 row_mask:0xf bank_mask:0xf
	v_pk_fma_f32 v[132:133], v[160:161], v[132:133], v[144:145]
	v_pk_mul_f32 v[136:137], v[136:137], v[142:143]
	v_mov_b32_dpp v195, v75 row_shr:1 row_mask:0xf bank_mask:0xf
	v_pk_mul_f32 v[132:133], v[132:133], v[136:137]
	v_pk_fma_f32 v[136:137], v[90:91], v[186:187], v[190:191]
	v_mov_b32_dpp v138, v66 row_shr:1 row_mask:0xf bank_mask:0xf
	v_mov_b32_dpp v139, v67 row_shr:1 row_mask:0xf bank_mask:0xf
	v_pk_fma_f32 v[136:137], v[182:183], v[194:195], v[136:137]
	v_mov_b32_dpp v130, v86 row_shr:1 row_mask:0xf bank_mask:0xf
	v_pk_fma_f32 v[136:137], v[178:179], v[138:139], v[136:137]
	v_mov_b32_dpp v131, v87 row_shr:1 row_mask:0xf bank_mask:0xf
	v_exp_f32_e32 v139, v136
	v_exp_f32_e32 v142, v137
	v_cvt_pk_bf16_f32 v138, v132, v133
	v_add_f32_e32 v132, 1.0, v139
	v_rcp_f32_e32 v132, v132
	v_add_f32_e32 v133, 1.0, v142
	v_rcp_f32_e32 v133, v133
	v_pk_fma_f32 v[142:143], v[94:95], v[170:171], v[174:175]
	v_mov_b32_dpp v134, v78 row_shr:1 row_mask:0xf bank_mask:0xf
	v_mov_b32_dpp v135, v79 row_shr:1 row_mask:0xf bank_mask:0xf
	v_pk_mul_f32 v[132:133], v[136:137], v[132:133]
	v_pk_fma_f32 v[136:137], v[68:69], v[184:185], v[188:189]
	v_pk_fma_f32 v[142:143], v[166:167], v[130:131], v[142:143]
	v_pk_fma_f32 v[136:137], v[88:89], v[180:181], v[136:137]
	v_pk_fma_f32 v[134:135], v[162:163], v[134:135], v[142:143]
	v_pk_fma_f32 v[136:137], v[176:177], v[192:193], v[136:137]
	v_add_u32_e32 v146, 0x80, v245
	v_exp_f32_e32 v142, v136
	v_exp_f32_e32 v143, v137
	v_pk_mul_f32 v[132:133], v[134:135], v[132:133]
	v_mov_b64_e32 v[134:135], s[60:61]
	v_cvt_pk_bf16_f32 v139, v132, v133
	v_mad_i64_i32 v[132:133], s[34:35], v146, s63, v[134:135]
	v_lshl_add_u64 v[132:133], v[132:133], 0, v[204:205]
	v_mov_b32_e32 v144, v138
	v_mov_b32_e32 v145, v139
	v_add_f32_e32 v138, 1.0, v142
	v_add_f32_e32 v139, 1.0, v143
	v_rcp_f32_e32 v138, v138
	v_rcp_f32_e32 v139, v139
	v_pk_fma_f32 v[142:143], v[80:81], v[168:169], v[172:173]
	v_pk_fma_f32 v[72:73], v[72:73], v[184:185], v[188:189]
	v_pk_fma_f32 v[142:143], v[92:93], v[164:165], v[142:143]
	v_pk_mul_f32 v[136:137], v[136:137], v[138:139]
	v_pk_fma_f32 v[128:129], v[160:161], v[128:129], v[142:143]
	v_pk_fma_f32 v[84:85], v[84:85], v[168:169], v[172:173]
	v_pk_mul_f32 v[128:129], v[128:129], v[136:137]
	v_pk_fma_f32 v[136:137], v[70:71], v[186:187], v[190:191]
	s_nop 0
	v_pk_fma_f32 v[136:137], v[90:91], v[182:183], v[136:137]
	s_nop 0
	v_pk_fma_f32 v[136:137], v[178:179], v[194:195], v[136:137]
	s_nop 0
	v_exp_f32_e32 v139, v136
	v_exp_f32_e32 v142, v137
	v_cvt_pk_bf16_f32 v138, v128, v129
	v_add_f32_e32 v128, 1.0, v139
	v_rcp_f32_e32 v128, v128
; #define LAS __attribute__((address_space(3)))
; __device__ __forceinline__ float sigmoidf_(float x) { return __builtin_amdgcn_rcpf(1.0f + __expf(-x)); }
;     __device__ __forceinline__ void operator()(AccRef acc, const Unit& u, int wr, int wc, int fr, int fq) const {
;     ...
;                 f32x4 h2v = (f32x4){0.f, 0.f, 0.f, 0.f}, h3v = h2v, h2g = h2v, h3g = h2v;
;                 const int pb = ai * 2 + wr - 1;
;                 if (pb >= 0 && fr == 0) { const LAS float* xp = xch + (pb * 2) * 256 + clb + 4 * n;
;                     h2v = *(const LAS f32x4*)(xp); h3v = *(const LAS f32x4*)(xp + 256); h2g = *(const LAS f32x4*)(xp + 128); h3g = *(const LAS f32x4*)(xp + 256 + 128); }
;                 float o[4][4];
; #pragma unroll
;                 for (int j = 0; j < 4; ++j) {
;                     const float v0 = acc[ai][0][0][n][j], v1 = acc[ai][0][1][n][j], v2 = acc[ai][0][2][n][j], v3 = acc[ai][0][3][n][j];
;                     const float g0 = acc[ai][1][0][n][j], g1 = acc[ai][1][1][n][j], g2 = acc[ai][1][2][n][j], g3 = acc[ai][1][3][n][j];
;                     const float pv3 = dpp_upd<0x111>(h3v[j], v3), pv2 = dpp_upd<0x111>(h2v[j], v2), pg3 = dpp_upd<0x111>(h3g[j], g3), pg2 = dpp_upd<0x111>(h2g[j], g2);
;                     const float hv0 = bvv[j] + w2v[j] * v0 + w1v[j] * pv3 + w0v[j] * pv2, hv1 = bvv[j] + w2v[j] * v1 + w1v[j] * v0 + w0v[j] * pv3;
;                     const float hv2 = bvv[j] + w2v[j] * v2 + w1v[j] * v1 + w0v[j] * v0, hv3 = bvv[j] + w2v[j] * v3 + w1v[j] * v2 + w0v[j] * v1;
;                     const float hg0 = bvg[j] + w2g[j] * g0 + w1g[j] * pg3 + w0g[j] * pg2, hg1 = bvg[j] + w2g[j] * g1 + w1g[j] * g0 + w0g[j] * pg3;
;                     const float hg2 = bvg[j] + w2g[j] * g2 + w1g[j] * g1 + w0g[j] * g0, hg3 = bvg[j] + w2g[j] * g3 + w1g[j] * g2 + w0g[j] * g1;
;                     o[0][j] = hg0 * sigmoidf_(hg0) * hv0; o[1][j] = hg1 * sigmoidf_(hg1) * hv1; o[2][j] = hg2 * sigmoidf_(hg2) * hv2; o[3][j] = hg3 * sigmoidf_(hg3) * hv3; }
; #pragma unroll
;                 for (int m = 0; m < 4; ++m) { u32x2 w; w.x = cvt_pk_bf16(o[m][0], o[m][1]); w.y = cvt_pk_bf16(o[m][2], o[m][3]);
;                     *(u32x2*)(Aout + (size_t)(row0 + ai * 128 + m) * FH + hc0 + 4 * n) = w; } } }
	v_add_f32_e32 v129, 1.0, v142
	v_rcp_f32_e32 v129, v129
	v_pk_fma_f32 v[142:143], v[82:83], v[170:171], v[174:175]
	v_pk_mul_f32 v[128:129], v[136:137], v[128:129]
	v_pk_fma_f32 v[142:143], v[94:95], v[166:167], v[142:143]
	v_pk_fma_f32 v[136:137], v[76:77], v[168:169], v[172:173]
	v_pk_fma_f32 v[130:131], v[162:163], v[130:131], v[142:143]
	v_pk_fma_f32 v[136:137], v[80:81], v[164:165], v[136:137]
	v_pk_mul_f32 v[128:129], v[130:131], v[128:129]
	v_pk_fma_f32 v[130:131], v[64:65], v[184:185], v[188:189]
	v_pk_fma_f32 v[64:65], v[64:65], v[180:181], v[72:73]
	v_pk_fma_f32 v[130:131], v[68:69], v[180:181], v[130:131]
	v_pk_fma_f32 v[64:65], v[68:69], v[176:177], v[64:65]
	v_pk_fma_f32 v[88:89], v[88:89], v[176:177], v[130:131]
	v_pk_fma_f32 v[92:93], v[92:93], v[160:161], v[136:137]
	v_exp_f32_e32 v130, v88
	v_exp_f32_e32 v131, v89
	v_exp_f32_e32 v72, v64
	v_pk_add_f32 v[130:131], v[130:131], 1.0 op_sel_hi:[1,0]
	v_rcp_f32_e32 v130, v130
	v_rcp_f32_e32 v131, v131
	v_pk_fma_f32 v[68:69], v[74:75], v[186:187], v[190:191]
	v_exp_f32_e32 v73, v65
	v_pk_mul_f32 v[88:89], v[88:89], v[130:131]
	v_pk_mul_f32 v[88:89], v[92:93], v[88:89]
	v_pk_fma_f32 v[92:93], v[66:67], v[186:187], v[190:191]
	v_pk_fma_f32 v[66:67], v[66:67], v[182:183], v[68:69]
	v_pk_fma_f32 v[92:93], v[70:71], v[182:183], v[92:93]
	v_pk_fma_f32 v[66:67], v[70:71], v[178:179], v[66:67]
	v_pk_fma_f32 v[90:91], v[90:91], v[178:179], v[92:93]
	v_exp_f32_e32 v93, v90
	v_exp_f32_e32 v68, v66
	v_exp_f32_e32 v69, v67
	v_exp_f32_e32 v130, v91
	v_pk_add_f32 v[72:73], v[72:73], 1.0 op_sel_hi:[1,0]
	v_pk_add_f32 v[68:69], v[68:69], 1.0 op_sel_hi:[1,0]
	v_cvt_pk_bf16_f32 v92, v88, v89
	v_add_f32_e32 v88, 1.0, v93
	v_add_f32_e32 v89, 1.0, v130
	v_rcp_f32_e32 v72, v72
	v_rcp_f32_e32 v73, v73
	v_rcp_f32_e32 v68, v68
	v_rcp_f32_e32 v69, v69
	v_rcp_f32_e32 v88, v88
	v_rcp_f32_e32 v89, v89
	v_pk_fma_f32 v[74:75], v[86:87], v[170:171], v[174:175]
	v_pk_fma_f32 v[130:131], v[78:79], v[170:171], v[174:175]
	v_pk_fma_f32 v[76:77], v[76:77], v[164:165], v[84:85]
	v_pk_fma_f32 v[70:71], v[78:79], v[166:167], v[74:75]
	v_pk_fma_f32 v[130:131], v[82:83], v[166:167], v[130:131]
	v_pk_fma_f32 v[76:77], v[80:81], v[160:161], v[76:77]
	v_pk_mul_f32 v[64:65], v[64:65], v[72:73]
	v_pk_fma_f32 v[70:71], v[82:83], v[162:163], v[70:71]
	v_pk_mul_f32 v[66:67], v[66:67], v[68:69]
	v_pk_fma_f32 v[94:95], v[94:95], v[162:163], v[130:131]
	v_pk_mul_f32 v[88:89], v[90:91], v[88:89]
	v_pk_mul_f32 v[64:65], v[76:77], v[64:65]
	v_pk_mul_f32 v[66:67], v[70:71], v[66:67]
	v_pk_mul_f32 v[88:89], v[94:95], v[88:89]
	v_cvt_pk_bf16_f32 v64, v64, v65
	v_cvt_pk_bf16_f32 v65, v66, v67
	v_add_u32_e32 v66, 0x83, v245
	v_cvt_pk_bf16_f32 v139, v128, v129
	v_add_u32_e32 v128, 0x81, v245
	v_cvt_pk_bf16_f32 v93, v88, v89
	v_add_u32_e32 v88, 0x82, v245
	v_mad_i64_i32 v[66:67], s[34:35], v66, s63, v[134:135]
	v_mad_i64_i32 v[128:129], s[34:35], v128, s63, v[134:135]
	v_mad_i64_i32 v[88:89], s[34:35], v88, s63, v[134:135]
	v_lshl_add_u64 v[82:83], v[66:67], 0, v[204:205]
	v_lshl_add_u64 v[128:129], v[128:129], 0, v[204:205]
	v_lshl_add_u64 v[88:89], v[88:89], 0, v[204:205]
	v_mov_b32_e32 v148, v64
	v_mov_b32_e32 v149, v65
	v_mov_b32_e32 v64, 0
	v_mov_b64_e32 v[70:71], 0
	v_mov_b64_e32 v[72:73], 0
	v_mov_b64_e32 v[78:79], 0
	v_mov_b64_e32 v[80:81], 0
	v_mov_b64_e32 v[66:67], 0
	v_mov_b64_e32 v[68:69], 0
	v_mov_b64_e32 v[74:75], 0
	v_mov_b64_e32 v[76:77], 0
	v_mov_b32_e32 v154, v138
	v_mov_b32_e32 v155, v139
	v_mov_b32_e32 v198, v92
	v_mov_b32_e32 v199, v93
	s_and_saveexec_b64 s[34:35], s[20:21]
	s_cbranch_execz .LBB0_1953
	ds_read_b128 v[74:77], v241
	ds_read_b128 v[66:69], v240
	ds_read_b128 v[78:81], v239
	ds_read_b128 v[70:73], v238
; #define LAS __attribute__((address_space(3)))
;     __device__ __forceinline__ void operator()(AccRef acc, const Unit& u, int wr, int wc, int fr, int fq) const {
;     ...
;         const int hc0 = 128 * u.pn + clb, row0 = u.pm * 256 + wr * 64 + 4 * fr;
; #pragma unroll
;         for (int n = 0; n < 2; ++n) {
;             const f32x4 w0v = cwv[n][0], w1v = cwv[n][1], w2v = cwv[n][2], bvv = cwv[n][3], w0g = cwv[n][4], w1g = cwv[n][5], w2g = cwv[n][6], bvg = cwv[n][7];
; #pragma unroll
;             for (int ai = 0; ai < 2; ++ai) {
;                 if (n == 0 && ai == 0) {
;                     asm volatile("" ::: "memory");
;                     const float* cv = cw + hc0 + 4; const float* cg = cv + FH; const float* bp = cb + hc0 + 4;
;                     cwv[1][0] = *(const f32x4*)(cv); cwv[1][1] = *(const f32x4*)(cv + F2); cwv[1][2] = *(const f32x4*)(cv + 2 * F2); cwv[1][3] = *(const f32x4*)(bp);
;                     cwv[1][4] = *(const f32x4*)(cg); cwv[1][5] = *(const f32x4*)(cg + F2); cwv[1][6] = *(const f32x4*)(cg + 2 * F2); cwv[1][7] = *(const f32x4*)(bp + FH);
;                     asm volatile("" ::: "memory"); }
;                 f32x4 h2v = (f32x4){0.f, 0.f, 0.f, 0.f}, h3v = h2v, h2g = h2v, h3g = h2v;
;                 const int pb = ai * 2 + wr - 1;
;                 if (pb >= 0 && fr == 0) { const LAS float* xp = xch + (pb * 2) * 256 + clb + 4 * n;
;                     h2v = *(const LAS f32x4*)(xp); h3v = *(const LAS f32x4*)(xp + 256); h2g = *(const LAS f32x4*)(xp + 128); h3g = *(const LAS f32x4*)(xp + 256 + 128); }
;                 float o[4][4];
; #pragma unroll
;                 for (int j = 0; j < 4; ++j) {
;                     const float v0 = acc[ai][0][0][n][j], v1 = acc[ai][0][1][n][j], v2 = acc[ai][0][2][n][j], v3 = acc[ai][0][3][n][j];
;                     const float g0 = acc[ai][1][0][n][j], g1 = acc[ai][1][1][n][j], g2 = acc[ai][1][2][n][j], g3 = acc[ai][1][3][n][j];
;                     const float pv3 = dpp_upd<0x111>(h3v[j], v3), pv2 = dpp_upd<0x111>(h2v[j], v2), pg3 = dpp_upd<0x111>(h3g[j], g3), pg2 = dpp_upd<0x111>(h2g[j], g2);
;                     const float hv0 = bvv[j] + w2v[j] * v0 + w1v[j] * pv3 + w0v[j] * pv2, hv1 = bvv[j] + w2v[j] * v1 + w1v[j] * v0 + w0v[j] * pv3;
;                     const float hv2 = bvv[j] + w2v[j] * v2 + w1v[j] * v1 + w0v[j] * v0, hv3 = bvv[j] + w2v[j] * v3 + w1v[j] * v2 + w0v[j] * v1;
.LBB0_1953:
	s_or_b64 exec, exec, s[34:35]
	s_waitcnt lgkmcnt(0)
	v_mov_b32_dpp v70, v44 row_shr:1 row_mask:0xf bank_mask:0xf
	v_mov_b32_dpp v71, v45 row_shr:1 row_mask:0xf bank_mask:0xf
	s_waitcnt vmcnt(0)
	v_pk_fma_f32 v[84:85], v[56:57], v[120:121], v[124:125]
	v_mov_b32_dpp v78, v32 row_shr:1 row_mask:0xf bank_mask:0xf
	v_mov_b32_dpp v79, v33 row_shr:1 row_mask:0xf bank_mask:0xf
	v_pk_fma_f32 v[84:85], v[116:117], v[70:71], v[84:85]
	v_mov_b32_dpp v66, v52 row_shr:1 row_mask:0xf bank_mask:0xf
	v_pk_fma_f32 v[78:79], v[112:113], v[78:79], v[84:85]
	v_mov_b32_dpp v67, v53 row_shr:1 row_mask:0xf bank_mask:0xf
	v_exp_f32_e32 v84, v78
	v_exp_f32_e32 v85, v79
	v_pk_fma_f32 v[86:87], v[60:61], v[104:105], v[108:109]
	v_pk_add_f32 v[84:85], v[84:85], 1.0 op_sel_hi:[1,0]
	v_rcp_f32_e32 v84, v84
	v_rcp_f32_e32 v85, v85
	v_mov_b32_dpp v74, v40 row_shr:1 row_mask:0xf bank_mask:0xf
	v_mov_b32_dpp v75, v41 row_shr:1 row_mask:0xf bank_mask:0xf
	v_pk_fma_f32 v[86:87], v[100:101], v[66:67], v[86:87]
	v_pk_mul_f32 v[78:79], v[78:79], v[84:85]
	v_pk_fma_f32 v[74:75], v[96:97], v[74:75], v[86:87]
	v_mov_b32_dpp v72, v46 row_shr:1 row_mask:0xf bank_mask:0xf
	v_mov_b32_dpp v73, v47 row_shr:1 row_mask:0xf bank_mask:0xf
	v_pk_mul_f32 v[74:75], v[74:75], v[78:79]
	v_pk_fma_f32 v[78:79], v[58:59], v[122:123], v[126:127]
	v_mov_b32_dpp v80, v34 row_shr:1 row_mask:0xf bank_mask:0xf
	v_mov_b32_dpp v81, v35 row_shr:1 row_mask:0xf bank_mask:0xf
	v_pk_fma_f32 v[78:79], v[118:119], v[72:73], v[78:79]
	v_mov_b32_dpp v68, v54 row_shr:1 row_mask:0xf bank_mask:0xf
	v_pk_fma_f32 v[78:79], v[114:115], v[80:81], v[78:79]
	v_mov_b32_dpp v69, v55 row_shr:1 row_mask:0xf bank_mask:0xf
	v_exp_f32_e32 v80, v78
	v_exp_f32_e32 v81, v79
	v_pk_fma_f32 v[84:85], v[62:63], v[106:107], v[110:111]
	v_pk_add_f32 v[80:81], v[80:81], 1.0 op_sel_hi:[1,0]
	v_rcp_f32_e32 v80, v80
	v_rcp_f32_e32 v81, v81
	v_mov_b32_dpp v76, v42 row_shr:1 row_mask:0xf bank_mask:0xf
	v_mov_b32_dpp v77, v43 row_shr:1 row_mask:0xf bank_mask:0xf
	v_pk_fma_f32 v[84:85], v[102:103], v[68:69], v[84:85]
	v_pk_mul_f32 v[78:79], v[78:79], v[80:81]
	v_pk_fma_f32 v[76:77], v[98:99], v[76:77], v[84:85]
	v_cvt_pk_bf16_f32 v74, v74, v75
	v_pk_mul_f32 v[76:77], v[76:77], v[78:79]
	v_pk_fma_f32 v[44:45], v[44:45], v[120:121], v[124:125]
	v_cvt_pk_bf16_f32 v75, v76, v77
	v_pk_fma_f32 v[76:77], v[36:37], v[120:121], v[124:125]
	v_mov_b32_e32 v90, v246
	v_mov_b32_e32 v91, v247
	v_mov_b32_e32 v92, v74
	v_mov_b32_e32 v93, v75
	global_store_dwordx4 v[202:203], v[90:93], off
	v_pk_fma_f32 v[76:77], v[56:57], v[116:117], v[76:77]
	v_pk_fma_f32 v[52:53], v[52:53], v[104:105], v[108:109]
	v_pk_fma_f32 v[70:71], v[112:113], v[70:71], v[76:77]
	s_nop 0
	v_exp_f32_e32 v74, v70
	v_exp_f32_e32 v75, v71
	s_nop 0
	v_pk_add_f32 v[74:75], v[74:75], 1.0 op_sel_hi:[1,0]
	v_rcp_f32_e32 v74, v74
	v_rcp_f32_e32 v75, v75
	v_pk_fma_f32 v[76:77], v[48:49], v[104:105], v[108:109]
	v_pk_mul_f32 v[70:71], v[70:71], v[74:75]
	v_pk_fma_f32 v[76:77], v[60:61], v[100:101], v[76:77]
	v_pk_fma_f32 v[74:75], v[50:51], v[106:107], v[110:111]
	v_pk_fma_f32 v[66:67], v[96:97], v[66:67], v[76:77]
	v_pk_fma_f32 v[74:75], v[62:63], v[102:103], v[74:75]
	v_pk_mul_f32 v[66:67], v[66:67], v[70:71]
	v_pk_fma_f32 v[70:71], v[38:39], v[122:123], v[126:127]
	v_pk_fma_f32 v[68:69], v[98:99], v[68:69], v[74:75]
	v_pk_fma_f32 v[70:71], v[58:59], v[118:119], v[70:71]
	v_cvt_pk_bf16_f32 v66, v66, v67
	v_pk_fma_f32 v[70:71], v[114:115], v[72:73], v[70:71]
	s_nop 0
	v_exp_f32_e32 v72, v70
	v_exp_f32_e32 v73, v71
	s_nop 0
	v_pk_add_f32 v[72:73], v[72:73], 1.0 op_sel_hi:[1,0]
	v_rcp_f32_e32 v72, v72
	v_rcp_f32_e32 v73, v73
	s_nop 0
	v_pk_mul_f32 v[70:71], v[70:71], v[72:73]
	s_nop 0
	v_pk_mul_f32 v[68:69], v[68:69], v[70:71]
	s_nop 0
	v_cvt_pk_bf16_f32 v67, v68, v69
	v_pk_fma_f32 v[68:69], v[32:33], v[120:121], v[124:125]
	v_mov_b32_e32 v134, v248
	v_mov_b32_e32 v135, v249
	v_mov_b32_e32 v136, v66
	v_mov_b32_e32 v137, v67
	global_store_dwordx4 v[196:197], v[134:137], off
	v_pk_fma_f32 v[68:69], v[36:37], v[116:117], v[68:69]
	v_pk_fma_f32 v[32:33], v[32:33], v[116:117], v[44:45]
	v_pk_fma_f32 v[56:57], v[56:57], v[112:113], v[68:69]
	v_pk_fma_f32 v[32:33], v[36:37], v[112:113], v[32:33]
	v_exp_f32_e32 v66, v56
	v_exp_f32_e32 v67, v57
	s_nop 0
	v_pk_add_f32 v[66:67], v[66:67], 1.0 op_sel_hi:[1,0]
	v_rcp_f32_e32 v66, v66
	v_rcp_f32_e32 v67, v67
	v_pk_fma_f32 v[68:69], v[40:41], v[104:105], v[108:109]
	v_exp_f32_e32 v44, v32
	v_pk_fma_f32 v[68:69], v[48:49], v[100:101], v[68:69]
	v_pk_mul_f32 v[56:57], v[56:57], v[66:67]
	v_pk_fma_f32 v[60:61], v[60:61], v[96:97], v[68:69]
	v_pk_fma_f32 v[36:37], v[46:47], v[122:123], v[126:127]
	v_pk_mul_f32 v[56:57], v[60:61], v[56:57]
	v_pk_fma_f32 v[60:61], v[34:35], v[122:123], v[126:127]
	v_pk_fma_f32 v[34:35], v[34:35], v[118:119], v[36:37]
	v_pk_fma_f32 v[60:61], v[38:39], v[118:119], v[60:61]
	v_pk_fma_f32 v[34:35], v[38:39], v[114:115], v[34:35]
	v_pk_fma_f32 v[58:59], v[58:59], v[114:115], v[60:61]
	v_exp_f32_e32 v60, v58
	v_exp_f32_e32 v45, v33
	v_exp_f32_e32 v36, v34
	v_exp_f32_e32 v37, v35
	v_exp_f32_e32 v61, v59
	v_cvt_pk_bf16_f32 v56, v56, v57
	v_pk_add_f32 v[44:45], v[44:45], 1.0 op_sel_hi:[1,0]
	v_pk_add_f32 v[36:37], v[36:37], 1.0 op_sel_hi:[1,0]
	v_pk_add_f32 v[60:61], v[60:61], 1.0 op_sel_hi:[1,0]
	v_rcp_f32_e32 v44, v44
	v_rcp_f32_e32 v45, v45
	v_rcp_f32_e32 v36, v36
	v_rcp_f32_e32 v37, v37
	v_rcp_f32_e32 v60, v60
	v_rcp_f32_e32 v61, v61
	v_pk_fma_f32 v[46:47], v[54:55], v[106:107], v[110:111]
	v_pk_fma_f32 v[66:67], v[42:43], v[106:107], v[110:111]
	v_pk_fma_f32 v[40:41], v[40:41], v[100:101], v[52:53]
	v_pk_fma_f32 v[38:39], v[42:43], v[102:103], v[46:47]
	v_pk_fma_f32 v[66:67], v[50:51], v[102:103], v[66:67]
	v_pk_fma_f32 v[40:41], v[48:49], v[96:97], v[40:41]
	v_pk_mul_f32 v[32:33], v[32:33], v[44:45]
	v_pk_fma_f32 v[38:39], v[50:51], v[98:99], v[38:39]
	v_pk_mul_f32 v[34:35], v[34:35], v[36:37]
	v_pk_fma_f32 v[62:63], v[62:63], v[98:99], v[66:67]
	v_pk_mul_f32 v[58:59], v[58:59], v[60:61]
	v_pk_mul_f32 v[32:33], v[40:41], v[32:33]
	v_pk_mul_f32 v[34:35], v[38:39], v[34:35]
	v_pk_mul_f32 v[58:59], v[62:63], v[58:59]
	v_cvt_pk_bf16_f32 v32, v32, v33
	v_cvt_pk_bf16_f32 v33, v34, v35
	v_cvt_pk_bf16_f32 v57, v58, v59
	v_mov_b32_e32 v158, v250
	v_mov_b32_e32 v159, v251
	v_mov_b32_e32 v160, v32
	v_mov_b32_e32 v161, v33
	global_store_dwordx4 v[140:141], v[158:161], off
	v_mov_b32_e32 v65, 0
	v_mov_b64_e32 v[66:67], 0
	v_mov_b64_e32 v[40:41], 0
	v_mov_b64_e32 v[42:43], 0
	v_mov_b64_e32 v[32:33], 0
	v_mov_b64_e32 v[34:35], 0
	v_mov_b64_e32 v[36:37], 0
	v_mov_b64_e32 v[38:39], 0
	v_mov_b32_e32 v162, v253
	v_mov_b32_e32 v163, v254
	v_mov_b32_e32 v164, v56
	v_mov_b32_e32 v165, v57
	global_store_dwordx4 v[152:153], v[162:165], off
	s_and_saveexec_b64 s[34:35], s[22:23]
	s_cbranch_execz .LBB0_1936
	ds_read_b128 v[36:39], v236 offset:2064
	ds_read_b128 v[40:43], v236 offset:2576
	ds_read_b128 v[32:35], v236 offset:3088
	ds_read_b128 v[64:67], v236 offset:3600
	s_branch .LBB0_1936
